# gemm_stream K loops: 2 super-phases of 32 MFMAs per K tile (4 barriers instead of 8); prologue waits for the first three stages before the first barrier since the first load interval now also reads th
# speedup vs baseline: 1.0328x; 1.0328x over previous
; #define WAIT_V(n) asm volatile("s_waitcnt vmcnt(" #n ")" ::: "memory")
; #define BAR __builtin_amdgcn_s_barrier()
; template <class EPI>
; DI void gemm_stream(const u16* __restrict__ A, const u16* __restrict__ Bt, const int K, const int nM, const int nN,
;                     const int bid, const int nb, const int tid, EPI epi) {
;     ...
;   unsigned so0, so1;
;   { int r0, c0; stage_rc(tid * 16, r0, c0); so0 = (unsigned)((r0 * K + c0) * 2); so1 = so0 + (unsigned)(64 * K * 2); }
;   const int lanepart = lds_byte(fr, fq * 8);
;   const int aoff = wr * 8192 + lanepart, boff = wc * 4096 + lanepart;
;   const int nt = K / BK;
;   int pm, pn; gemm_tile_coords(bid, nM, nN, pm, pn);
;   int brow = pm * BM, bcol = pn * BM;
;   GemmAcc acc = {};
;   STAGE(SB(0, 0), Bt, bcol, 0); STAGE(SA(0, 0), A, brow, 0);
;   STAGE(SB(0, 1), Bt, bcol + HALF, 0); STAGE(SA(0, 1), A, brow + HALF, 0);
;   if (wr == 1) BAR;
;   WAIT_V(4); BAR;
;   STAGE(SB(1, 0), Bt, bcol, 1); STAGE(SA(1, 0), A, brow, 1); STAGE(SB(1, 1), Bt, bcol + HALF, 1);
;   WAIT_V(6); BAR;
.LBB0_28:
	s_or_b64 exec, exec, s[0:1]
	v_add_u32_e32 v151, 0x18000, v0
	s_bitset1_b32 s5, 7
	v_readfirstlane_b32 s0, v151
	v_add_u32_e32 v152, 0x1a000, v0
	v_add_u32_e32 v7, s5, v142
	s_mov_b32 m0, s0
	v_readfirstlane_b32 s0, v152
	v_add_u32_e32 v153, 0x8000, v0
	s_waitcnt vmcnt(2)
	s_barrier
	global_load_lds_dwordx4 v7, s[78:79]
	v_add_u32_e32 v7, s5, v143
	s_mov_b32 m0, s0
	s_bitset1_b32 s6, 7
	v_readfirstlane_b32 s0, v153
	v_add_u32_e32 v154, 0xa000, v0
	global_load_lds_dwordx4 v7, s[78:79]
	v_add_u32_e32 v7, s6, v142
	s_mov_b32 m0, s0
	v_readfirstlane_b32 s0, v154
	v_add_u32_e32 v155, 0x1c000, v0
	global_load_lds_dwordx4 v7, s[76:77]
	v_add_u32_e32 v7, s6, v143
	s_mov_b32 m0, s0
	s_bitset1_b32 s4, 7
	v_readfirstlane_b32 s0, v155
	v_add_u32_e32 v156, 0x1e000, v0
	global_load_lds_dwordx4 v7, s[76:77]
	v_add_u32_e32 v7, s4, v142
	s_mov_b32 m0, s0
	v_readfirstlane_b32 s0, v156
	global_load_lds_dwordx4 v7, s[78:79]
	v_add_u32_e32 v7, s4, v143
	s_mov_b32 m0, s0
	v_and_b32_e32 v8, 48, v239
	global_load_lds_dwordx4 v7, s[78:79]
	v_and_b32_e32 v7, 15, v239
	v_lshlrev_b32_e32 v7, 6, v7
	v_lshlrev_b32_e32 v10, 2, v239
	v_or_b32_e32 v9, v7, v8
	v_and_b32_e32 v10, 32, v10
	v_lshlrev_b32_e32 v2, 13, v2
	v_bitop3_b32 v7, v7, v10, v8 bitop3:0x36
	v_bitop3_b32 v157, v9, v2, v10 bitop3:0xde
	v_lshlrev_b32_e32 v2, 6, v239
	s_movk_i32 s0, 0x3000
	v_and_or_b32 v7, v2, s0, v7
	s_movk_i32 s0, 0x1600
	v_lshrrev_b32_e32 v3, 1, v3
	v_mul_lo_u32 v2, v5, s0
	s_mov_b32 s0, 0x16000
	v_mad_u64_u32 v[2:3], s[0:1], v3, s0, v[2:3]
	s_waitcnt vmcnt(6)
	v_or_b32_e32 v2, v2, v4
	v_add_u32_e32 v2, v2, v6
	v_mov_b32_e32 v3, 0x210080
	s_lshl_b32 s8, s3, 8
	s_lshl_b32 s7, s2, 8
	v_lshl_add_u32 v158, v2, 1, v3
	v_or_b32_e32 v159, 0x10000, v7
	v_add_u32_e32 v160, 0x10400, v7
	v_add_u32_e32 v161, 0x10800, v7
	v_add_u32_e32 v162, 0x10c00, v7
	v_add_u32_e32 v163, 0xc000, v0
	v_add_u32_e32 v165, 0xe000, v0
	v_or_b32_e32 v166, 0x14000, v7
	v_add_u32_e32 v167, 0x14400, v7
	v_add_u32_e32 v168, 0x14800, v7
	v_add_u32_e32 v169, 0x14c00, v7
	v_or_b32_e32 v170, 0x18000, v7
	v_add_u32_e32 v171, 0x18400, v7
	v_add_u32_e32 v172, 0x18800, v7
	v_add_u32_e32 v173, 0x18c00, v7
	v_or_b32_e32 v174, 0x1c000, v7
	v_add_u32_e32 v175, 0x1c400, v7
	v_add_u32_e32 v176, 0x1c800, v7
	v_add_u32_e32 v177, 0x1cc00, v7
	s_mov_b32 s4, s45
	s_barrier

.LBB0_32:
	s_add_i32 s11, s10, 2
	ds_read_b128 v[132:135], v159
	ds_read_b128 v[136:139], v160
	ds_read_b128 v[180:183], v161
	ds_read_b128 v[184:187], v162
	s_cmpk_lt_u32 s10, 0x56
	s_cselect_b32 s12, s8, s5
	s_cselect_b32 s13, s7, s6
	s_cselect_b32 s14, s9, 0
	s_mulk_i32 s13, 0x1600
	s_mulk_i32 s12, 0x1600
	s_or_b32 s15, s14, 64
	s_add_i32 s17, s12, s14
	s_add_i32 s18, s13, 0xb0000
	s_add_i32 s16, s13, s14
	s_add_i32 s13, s15, s13
	s_add_i32 s12, s15, s12
	s_lshl_b32 s17, s17, 1
	s_add_i32 s14, s18, s14
	s_add_i32 s18, s18, s15
	s_addk_i32 s9, 0x80
	s_lshl_b32 s16, s16, 1
	s_lshl_b32 s19, s13, 1
	s_lshl_b32 s13, s12, 1
	s_lshl_b32 s14, s14, 1
	s_add_i32 s15, s17, 0x160000
	s_lshl_b32 s12, s18, 1
	s_cmpk_gt_u32 s10, 0x55
	v_readfirstlane_b32 s10, v163
	v_add_u32_e32 v131, 0xfff50000, v130
	s_mov_b32 m0, s10
	v_readfirstlane_b32 s10, v165
	ds_read_b128 v[188:191], v157
	ds_read_b128 v[192:195], v157 offset:1024
	ds_read_b128 v[196:199], v157 offset:2048
	ds_read_b128 v[200:203], v157 offset:3072
	ds_read_b128 v[204:207], v157 offset:4096
	ds_read_b128 v[208:211], v157 offset:5120
	ds_read_b128 v[212:215], v157 offset:6144
	ds_read_b128 v[216:219], v157 offset:7168
	global_load_lds_dwordx4 v131, s[76:77]
	s_mov_b32 m0, s10
	s_nop 0
	global_load_lds_dwordx4 v130, s[76:77]
	s_waitcnt lgkmcnt(8)
	ds_read_b128 v[220:223], v166
	ds_read_b128 v[242:245], v167
	ds_read_b128 v[246:249], v168
	ds_read_b128 v[250:253], v169
	s_waitcnt vmcnt(8)
	s_waitcnt lgkmcnt(0)
	s_barrier
	s_setprio 1
	v_mfma_f32_16x16x32_bf16 v[126:129], v[132:135], v[188:191], v[126:129]
	v_mfma_f32_16x16x32_bf16 v[122:125], v[180:183], v[188:191], v[122:125]
	v_mfma_f32_16x16x32_bf16 v[118:121], v[132:135], v[196:199], v[118:121]
	v_mfma_f32_16x16x32_bf16 v[114:117], v[180:183], v[196:199], v[114:117]
	v_mfma_f32_16x16x32_bf16 v[110:113], v[132:135], v[204:207], v[110:113]
	v_mfma_f32_16x16x32_bf16 v[106:109], v[180:183], v[204:207], v[106:109]
	v_mfma_f32_16x16x32_bf16 v[102:105], v[132:135], v[212:215], v[102:105]
	v_mfma_f32_16x16x32_bf16 v[98:101], v[180:183], v[212:215], v[98:101]
	v_mfma_f32_16x16x32_bf16 v[126:129], v[136:139], v[192:195], v[126:129]
	v_mfma_f32_16x16x32_bf16 v[122:125], v[184:187], v[192:195], v[122:125]
	v_mfma_f32_16x16x32_bf16 v[118:121], v[136:139], v[200:203], v[118:121]
	v_mfma_f32_16x16x32_bf16 v[114:117], v[184:187], v[200:203], v[114:117]
	v_mfma_f32_16x16x32_bf16 v[110:113], v[136:139], v[208:211], v[110:113]
	v_mfma_f32_16x16x32_bf16 v[106:109], v[184:187], v[208:211], v[106:109]
	v_mfma_f32_16x16x32_bf16 v[102:105], v[136:139], v[216:219], v[102:105]
	v_mfma_f32_16x16x32_bf16 v[98:101], v[184:187], v[216:219], v[98:101]
	v_mfma_f32_16x16x32_bf16 v[94:97], v[220:223], v[188:191], v[94:97]
	v_mfma_f32_16x16x32_bf16 v[90:93], v[246:249], v[188:191], v[90:93]
	v_mfma_f32_16x16x32_bf16 v[86:89], v[220:223], v[196:199], v[86:89]
	v_mfma_f32_16x16x32_bf16 v[82:85], v[246:249], v[196:199], v[82:85]
	v_mfma_f32_16x16x32_bf16 v[78:81], v[220:223], v[204:207], v[78:81]
	v_mfma_f32_16x16x32_bf16 v[74:77], v[246:249], v[204:207], v[74:77]
	v_mfma_f32_16x16x32_bf16 v[70:73], v[220:223], v[212:215], v[70:73]
	v_mfma_f32_16x16x32_bf16 v[66:69], v[246:249], v[212:215], v[66:69]
	v_mfma_f32_16x16x32_bf16 v[94:97], v[242:245], v[192:195], v[94:97]
	v_mfma_f32_16x16x32_bf16 v[90:93], v[250:253], v[192:195], v[90:93]
	v_mfma_f32_16x16x32_bf16 v[86:89], v[242:245], v[200:203], v[86:89]
	v_mfma_f32_16x16x32_bf16 v[82:85], v[250:253], v[200:203], v[82:85]
	v_mfma_f32_16x16x32_bf16 v[78:81], v[242:245], v[208:211], v[78:81]
	v_mfma_f32_16x16x32_bf16 v[74:77], v[250:253], v[208:211], v[74:77]
	v_mfma_f32_16x16x32_bf16 v[70:73], v[242:245], v[216:219], v[70:73]
	v_mfma_f32_16x16x32_bf16 v[66:69], v[250:253], v[216:219], v[66:69]
	s_setprio 0
	s_barrier
	v_readfirstlane_b32 s10, v144
	v_add_u32_e32 v131, s16, v142
	s_mov_b32 m0, s10
	v_readfirstlane_b32 s10, v145
	global_load_lds_dwordx4 v131, s[78:79]
	v_add_u32_e32 v131, s16, v143
	s_mov_b32 m0, s10
	s_nop 0
	global_load_lds_dwordx4 v131, s[78:79]
	v_readfirstlane_b32 s10, v0
	v_add_u32_e32 v131, s17, v142
	s_mov_b32 m0, s10
	v_readfirstlane_b32 s10, v146
	ds_read_b128 v[188:191], v157 offset:16384
	ds_read_b128 v[192:195], v157 offset:17408
	ds_read_b128 v[196:199], v157 offset:18432
	ds_read_b128 v[200:203], v157 offset:19456
	ds_read_b128 v[204:207], v157 offset:20480
	ds_read_b128 v[208:211], v157 offset:21504
	ds_read_b128 v[212:215], v157 offset:22528
	ds_read_b128 v[216:219], v157 offset:23552
	global_load_lds_dwordx4 v131, s[76:77]
	v_add_u32_e32 v131, s17, v143
	s_mov_b32 m0, s10
	s_nop 0
	global_load_lds_dwordx4 v131, s[76:77]
	v_readfirstlane_b32 s10, v147
	v_add_u32_e32 v131, s14, v142
	s_mov_b32 m0, s10
	v_readfirstlane_b32 s10, v148
	global_load_lds_dwordx4 v131, s[78:79]
	v_add_u32_e32 v131, s14, v143
	s_mov_b32 m0, s10
	s_nop 0
	global_load_lds_dwordx4 v131, s[78:79]
	s_waitcnt vmcnt(8)
	s_waitcnt lgkmcnt(0)
	s_barrier
	s_setprio 1
	v_mfma_f32_16x16x32_bf16 v[62:65], v[132:135], v[188:191], v[62:65]
	v_mfma_f32_16x16x32_bf16 v[58:61], v[180:183], v[188:191], v[58:61]
	v_mfma_f32_16x16x32_bf16 v[54:57], v[132:135], v[196:199], v[54:57]
	v_mfma_f32_16x16x32_bf16 v[50:53], v[180:183], v[196:199], v[50:53]
	v_mfma_f32_16x16x32_bf16 v[46:49], v[132:135], v[204:207], v[46:49]
	v_mfma_f32_16x16x32_bf16 v[42:45], v[180:183], v[204:207], v[42:45]
	v_mfma_f32_16x16x32_bf16 v[38:41], v[132:135], v[212:215], v[38:41]
	v_mfma_f32_16x16x32_bf16 v[34:37], v[180:183], v[212:215], v[34:37]
	v_mfma_f32_16x16x32_bf16 v[62:65], v[136:139], v[192:195], v[62:65]
	v_mfma_f32_16x16x32_bf16 v[58:61], v[184:187], v[192:195], v[58:61]
	v_mfma_f32_16x16x32_bf16 v[54:57], v[136:139], v[200:203], v[54:57]
	v_mfma_f32_16x16x32_bf16 v[50:53], v[184:187], v[200:203], v[50:53]
	v_mfma_f32_16x16x32_bf16 v[46:49], v[136:139], v[208:211], v[46:49]
	v_mfma_f32_16x16x32_bf16 v[42:45], v[184:187], v[208:211], v[42:45]
	v_mfma_f32_16x16x32_bf16 v[38:41], v[136:139], v[216:219], v[38:41]
	v_mfma_f32_16x16x32_bf16 v[34:37], v[184:187], v[216:219], v[34:37]
	v_mfma_f32_16x16x32_bf16 v[30:33], v[220:223], v[188:191], v[30:33]
	v_mfma_f32_16x16x32_bf16 v[26:29], v[246:249], v[188:191], v[26:29]
	v_mfma_f32_16x16x32_bf16 v[22:25], v[220:223], v[196:199], v[22:25]
	v_mfma_f32_16x16x32_bf16 v[18:21], v[246:249], v[196:199], v[18:21]
	v_mfma_f32_16x16x32_bf16 v[14:17], v[220:223], v[204:207], v[14:17]
	v_mfma_f32_16x16x32_bf16 v[10:13], v[246:249], v[204:207], v[10:13]
	v_mfma_f32_16x16x32_bf16 v[6:9], v[220:223], v[212:215], v[6:9]
	v_mfma_f32_16x16x32_bf16 v[2:5], v[246:249], v[212:215], v[2:5]
	v_mfma_f32_16x16x32_bf16 v[30:33], v[242:245], v[192:195], v[30:33]
	v_mfma_f32_16x16x32_bf16 v[26:29], v[250:253], v[192:195], v[26:29]
	v_mfma_f32_16x16x32_bf16 v[22:25], v[242:245], v[200:203], v[22:25]
	v_mfma_f32_16x16x32_bf16 v[18:21], v[250:253], v[200:203], v[18:21]
	v_mfma_f32_16x16x32_bf16 v[14:17], v[242:245], v[208:211], v[14:17]
	v_mfma_f32_16x16x32_bf16 v[10:13], v[250:253], v[208:211], v[10:13]
	v_mfma_f32_16x16x32_bf16 v[6:9], v[242:245], v[216:219], v[6:9]
	v_mfma_f32_16x16x32_bf16 v[2:5], v[250:253], v[216:219], v[2:5]
	s_setprio 0
	s_barrier
	ds_read_b128 v[132:135], v170
	ds_read_b128 v[136:139], v171
	ds_read_b128 v[180:183], v172
	ds_read_b128 v[184:187], v173
	v_readfirstlane_b32 s10, v149
	v_add_u32_e32 v131, s15, v142
	s_mov_b32 m0, s10
	v_readfirstlane_b32 s10, v150
	ds_read_b128 v[188:191], v157 offset:32768
	ds_read_b128 v[192:195], v157 offset:33792
	ds_read_b128 v[196:199], v157 offset:34816
	ds_read_b128 v[200:203], v157 offset:35840
	ds_read_b128 v[204:207], v157 offset:36864
	ds_read_b128 v[208:211], v157 offset:37888
	ds_read_b128 v[212:215], v157 offset:38912
	ds_read_b128 v[216:219], v157 offset:39936
	global_load_lds_dwordx4 v131, s[76:77]
	v_add_u32_e32 v131, s15, v143
	s_mov_b32 m0, s10
	s_nop 0
	global_load_lds_dwordx4 v131, s[76:77]
	s_waitcnt lgkmcnt(8)
	ds_read_b128 v[220:223], v174
	ds_read_b128 v[242:245], v175
	ds_read_b128 v[246:249], v176
	ds_read_b128 v[250:253], v177
	s_waitcnt vmcnt(8)
	s_waitcnt lgkmcnt(0)
	s_barrier
	s_setprio 1
	v_mfma_f32_16x16x32_bf16 v[126:129], v[132:135], v[188:191], v[126:129]
	v_mfma_f32_16x16x32_bf16 v[122:125], v[180:183], v[188:191], v[122:125]
	v_mfma_f32_16x16x32_bf16 v[118:121], v[132:135], v[196:199], v[118:121]
	v_mfma_f32_16x16x32_bf16 v[114:117], v[180:183], v[196:199], v[114:117]
	v_mfma_f32_16x16x32_bf16 v[110:113], v[132:135], v[204:207], v[110:113]
	v_mfma_f32_16x16x32_bf16 v[106:109], v[180:183], v[204:207], v[106:109]
	v_mfma_f32_16x16x32_bf16 v[102:105], v[132:135], v[212:215], v[102:105]
	v_mfma_f32_16x16x32_bf16 v[98:101], v[180:183], v[212:215], v[98:101]
	v_mfma_f32_16x16x32_bf16 v[126:129], v[136:139], v[192:195], v[126:129]
	v_mfma_f32_16x16x32_bf16 v[122:125], v[184:187], v[192:195], v[122:125]
	v_mfma_f32_16x16x32_bf16 v[118:121], v[136:139], v[200:203], v[118:121]
	v_mfma_f32_16x16x32_bf16 v[114:117], v[184:187], v[200:203], v[114:117]
	v_mfma_f32_16x16x32_bf16 v[110:113], v[136:139], v[208:211], v[110:113]
	v_mfma_f32_16x16x32_bf16 v[106:109], v[184:187], v[208:211], v[106:109]
	v_mfma_f32_16x16x32_bf16 v[102:105], v[136:139], v[216:219], v[102:105]
	v_mfma_f32_16x16x32_bf16 v[98:101], v[184:187], v[216:219], v[98:101]
	v_mfma_f32_16x16x32_bf16 v[94:97], v[220:223], v[188:191], v[94:97]
	v_mfma_f32_16x16x32_bf16 v[90:93], v[246:249], v[188:191], v[90:93]
	v_mfma_f32_16x16x32_bf16 v[86:89], v[220:223], v[196:199], v[86:89]
	v_mfma_f32_16x16x32_bf16 v[82:85], v[246:249], v[196:199], v[82:85]
	v_mfma_f32_16x16x32_bf16 v[78:81], v[220:223], v[204:207], v[78:81]
	v_mfma_f32_16x16x32_bf16 v[74:77], v[246:249], v[204:207], v[74:77]
	v_mfma_f32_16x16x32_bf16 v[70:73], v[220:223], v[212:215], v[70:73]
	v_mfma_f32_16x16x32_bf16 v[66:69], v[246:249], v[212:215], v[66:69]
	v_mfma_f32_16x16x32_bf16 v[94:97], v[242:245], v[192:195], v[94:97]
	v_mfma_f32_16x16x32_bf16 v[90:93], v[250:253], v[192:195], v[90:93]
	v_mfma_f32_16x16x32_bf16 v[86:89], v[242:245], v[200:203], v[86:89]
	v_mfma_f32_16x16x32_bf16 v[82:85], v[250:253], v[200:203], v[82:85]
	v_mfma_f32_16x16x32_bf16 v[78:81], v[242:245], v[208:211], v[78:81]
	v_mfma_f32_16x16x32_bf16 v[74:77], v[250:253], v[208:211], v[74:77]
	v_mfma_f32_16x16x32_bf16 v[70:73], v[242:245], v[216:219], v[70:73]
	v_mfma_f32_16x16x32_bf16 v[66:69], v[250:253], v[216:219], v[66:69]
	s_setprio 0
	s_barrier
; DI void gemm_resid(const u16* A, const u16* Bt, int K, const float* xin, float* xout, int bid, int nb, int tid) {
;     ...
;     for (int ai = 0; ai < 2; ++ai)
; #pragma unroll
;       for (int bj = 0; bj < 2; ++bj) {
;         float4 xi[4][2];
; #pragma unroll
;         for (int m = 0; m < 4; ++m)
; #pragma unroll
;           for (int n = 0; n < 2; ++n) xi[m][n] = *reinterpret_cast<const float4*>(xin + (size_t)ACC_ROW * 2048 + ACC_COL);
	v_readfirstlane_b32 s10, v151
	v_add_u32_e32 v131, s19, v142
	s_mov_b32 m0, s10
	v_readfirstlane_b32 s10, v152
	global_load_lds_dwordx4 v131, s[78:79]
	v_add_u32_e32 v131, s19, v143
	s_mov_b32 m0, s10
	s_nop 0
	global_load_lds_dwordx4 v131, s[78:79]
	v_readfirstlane_b32 s10, v153
	v_add_u32_e32 v131, s13, v142
	s_mov_b32 m0, s10
	v_readfirstlane_b32 s10, v154
	ds_read_b128 v[188:191], v157 offset:49152
	ds_read_b128 v[192:195], v157 offset:50176
	ds_read_b128 v[196:199], v157 offset:51200
	ds_read_b128 v[200:203], v157 offset:52224
	ds_read_b128 v[204:207], v157 offset:53248
	ds_read_b128 v[208:211], v157 offset:54272
	ds_read_b128 v[212:215], v157 offset:55296
	ds_read_b128 v[216:219], v157 offset:56320
	global_load_lds_dwordx4 v131, s[76:77]
	v_add_u32_e32 v131, s13, v143
	s_mov_b32 m0, s10
	s_nop 0
	global_load_lds_dwordx4 v131, s[76:77]
	v_readfirstlane_b32 s10, v155
	v_add_u32_e32 v131, s12, v142
	s_mov_b32 m0, s10
	v_readfirstlane_b32 s10, v156
	global_load_lds_dwordx4 v131, s[78:79]
	v_add_u32_e32 v131, s12, v143
	s_mov_b32 m0, s10
	s_nop 0
	global_load_lds_dwordx4 v131, s[78:79]
	s_waitcnt vmcnt(8)
	s_waitcnt lgkmcnt(0)
	s_barrier
	s_setprio 1
	v_mfma_f32_16x16x32_bf16 v[62:65], v[132:135], v[188:191], v[62:65]
	v_mfma_f32_16x16x32_bf16 v[58:61], v[180:183], v[188:191], v[58:61]
	v_mfma_f32_16x16x32_bf16 v[54:57], v[132:135], v[196:199], v[54:57]
	v_mfma_f32_16x16x32_bf16 v[50:53], v[180:183], v[196:199], v[50:53]
	v_mfma_f32_16x16x32_bf16 v[46:49], v[132:135], v[204:207], v[46:49]
	v_mfma_f32_16x16x32_bf16 v[42:45], v[180:183], v[204:207], v[42:45]
	v_mfma_f32_16x16x32_bf16 v[38:41], v[132:135], v[212:215], v[38:41]
	v_mfma_f32_16x16x32_bf16 v[34:37], v[180:183], v[212:215], v[34:37]
	v_mfma_f32_16x16x32_bf16 v[62:65], v[136:139], v[192:195], v[62:65]
	v_mfma_f32_16x16x32_bf16 v[58:61], v[184:187], v[192:195], v[58:61]
	v_mfma_f32_16x16x32_bf16 v[54:57], v[136:139], v[200:203], v[54:57]
	v_mfma_f32_16x16x32_bf16 v[50:53], v[184:187], v[200:203], v[50:53]
	v_mfma_f32_16x16x32_bf16 v[46:49], v[136:139], v[208:211], v[46:49]
	v_mfma_f32_16x16x32_bf16 v[42:45], v[184:187], v[208:211], v[42:45]
	v_mfma_f32_16x16x32_bf16 v[38:41], v[136:139], v[216:219], v[38:41]
	v_mfma_f32_16x16x32_bf16 v[34:37], v[184:187], v[216:219], v[34:37]
	v_mfma_f32_16x16x32_bf16 v[30:33], v[220:223], v[188:191], v[30:33]
	v_mfma_f32_16x16x32_bf16 v[26:29], v[246:249], v[188:191], v[26:29]
	v_mfma_f32_16x16x32_bf16 v[22:25], v[220:223], v[196:199], v[22:25]
	v_mfma_f32_16x16x32_bf16 v[18:21], v[246:249], v[196:199], v[18:21]
	v_mfma_f32_16x16x32_bf16 v[14:17], v[220:223], v[204:207], v[14:17]
	v_mfma_f32_16x16x32_bf16 v[10:13], v[246:249], v[204:207], v[10:13]
	v_mfma_f32_16x16x32_bf16 v[6:9], v[220:223], v[212:215], v[6:9]
	v_mfma_f32_16x16x32_bf16 v[2:5], v[246:249], v[212:215], v[2:5]
	v_mfma_f32_16x16x32_bf16 v[30:33], v[242:245], v[192:195], v[30:33]
	v_mfma_f32_16x16x32_bf16 v[26:29], v[250:253], v[192:195], v[26:29]
	v_mfma_f32_16x16x32_bf16 v[22:25], v[242:245], v[200:203], v[22:25]
	v_mfma_f32_16x16x32_bf16 v[18:21], v[250:253], v[200:203], v[18:21]
	v_mfma_f32_16x16x32_bf16 v[14:17], v[242:245], v[208:211], v[14:17]
	v_mfma_f32_16x16x32_bf16 v[10:13], v[250:253], v[208:211], v[10:13]
	v_mfma_f32_16x16x32_bf16 v[6:9], v[242:245], v[216:219], v[6:9]
	v_mfma_f32_16x16x32_bf16 v[2:5], v[250:253], v[216:219], v[2:5]
	s_setprio 0
	v_add_u32_e32 v130, 0x100, v130
	s_mov_b32 s10, s11
	s_barrier
	s_cbranch_scc0 .LBB0_32
	v_mov_b32_e32 v131, v239
	s_nop 0
	v_ashrrev_i32_e32 v130, 2, v131
	v_and_b32_e32 v130, 0xffffffc0, v130
	v_and_or_b32 v132, v131, 15, s8
	v_add_u32_e32 v130, v132, v130
	v_lshrrev_b32_e32 v132, 1, v131
	v_lshrrev_b32_e32 v131, 2, v131
	v_and_b32_e32 v132, 0x60, v132
	v_and_b32_e32 v131, 12, v131
	v_or3_b32 v132, v132, v131, s7
	v_ashrrev_i32_e32 v131, 31, v130
	v_ashrrev_i32_e32 v133, 31, v132
	v_lshlrev_b64 v[134:135], 13, v[130:131]
	v_lshl_add_u64 v[134:135], s[72:73], 0, v[134:135]
	v_lshlrev_b64 v[132:133], 2, v[132:133]
	v_lshl_add_u64 v[140:141], v[134:135], 0, v[132:133]
	v_or_b32_e32 v134, 16, v130
	v_ashrrev_i32_e32 v135, 31, v134
	v_lshlrev_b64 v[134:135], 13, v[134:135]
	v_lshl_add_u64 v[134:135], s[72:73], 0, v[134:135]
	v_lshl_add_u64 v[138:139], v[134:135], 0, v[132:133]
	v_or_b32_e32 v134, 32, v130
	v_ashrrev_i32_e32 v135, 31, v134
	v_lshlrev_b64 v[134:135], 13, v[134:135]
	v_lshl_add_u64 v[134:135], s[72:73], 0, v[134:135]
	v_lshl_add_u64 v[136:137], v[134:135], 0, v[132:133]
	v_or_b32_e32 v134, 48, v130
	v_ashrrev_i32_e32 v135, 31, v134
	v_lshlrev_b64 v[134:135], 13, v[134:135]
	v_lshl_add_u64 v[134:135], s[72:73], 0, v[134:135]
	v_lshl_add_u64 v[134:135], v[134:135], 0, v[132:133]
	global_load_dwordx4 v[180:183], v[140:141], off
	global_load_dwordx4 v[184:187], v[140:141], off offset:64
	global_load_dwordx4 v[188:191], v[138:139], off
	global_load_dwordx4 v[192:195], v[138:139], off offset:64
	global_load_dwordx4 v[196:199], v[136:137], off
	global_load_dwordx4 v[200:203], v[136:137], off offset:64
	global_load_dwordx4 v[204:207], v[134:135], off
	global_load_dwordx4 v[208:211], v[134:135], off offset:64
	s_waitcnt vmcnt(0)
; #define EPI_SCHED __builtin_amdgcn_sched_barrier(0)
; DI void gemm_resid(const u16* A, const u16* Bt, int K, const float* xin, float* xout, int bid, int nb, int tid) {
;     ...
;     for (int ai = 0; ai < 2; ++ai)
; #pragma unroll
;       for (int bj = 0; bj < 2; ++bj) {
;         float4 xi[4][2];
; #pragma unroll
;         for (int m = 0; m < 4; ++m)
; #pragma unroll
;           for (int n = 0; n < 2; ++n) xi[m][n] = *reinterpret_cast<const float4*>(xin + (size_t)ACC_ROW * 2048 + ACC_COL);
; #pragma unroll
;         for (int m = 0; m < 4; ++m)
; #pragma unroll
;           for (int n = 0; n < 2; ++n) {
;             const f32x4 v = acc[ai][bj][m][n];
;             float4 r; r.x = xi[m][n].x + v[0]; r.y = xi[m][n].y + v[1]; r.z = xi[m][n].z + v[2]; r.w = xi[m][n].w + v[3];
;             *reinterpret_cast<float4*>(xout + (size_t)ACC_ROW * 2048 + ACC_COL) = r;
;           }
;         EPI_SCHED;
;       }
	v_pk_add_f32 v[126:127], v[126:127], v[180:181]
	v_pk_add_f32 v[128:129], v[128:129], v[182:183]
	global_store_dwordx4 v[140:141], v[126:129], off
	v_pk_add_f32 v[122:123], v[122:123], v[184:185]
	v_pk_add_f32 v[124:125], v[124:125], v[186:187]
	global_store_dwordx4 v[140:141], v[122:125], off offset:64
	v_pk_add_f32 v[118:119], v[118:119], v[188:189]
	v_pk_add_f32 v[120:121], v[120:121], v[190:191]
	global_store_dwordx4 v[138:139], v[118:121], off
	v_pk_add_f32 v[114:115], v[114:115], v[192:193]
	v_pk_add_f32 v[116:117], v[116:117], v[194:195]
	global_store_dwordx4 v[138:139], v[114:117], off offset:64
	v_pk_add_f32 v[110:111], v[110:111], v[196:197]
	v_pk_add_f32 v[112:113], v[112:113], v[198:199]
	global_store_dwordx4 v[136:137], v[110:113], off
	v_pk_add_f32 v[106:107], v[106:107], v[200:201]
	v_pk_add_f32 v[108:109], v[108:109], v[202:203]
	global_store_dwordx4 v[136:137], v[106:109], off offset:64
	v_pk_add_f32 v[102:103], v[102:103], v[204:205]
	v_pk_add_f32 v[104:105], v[104:105], v[206:207]
	global_store_dwordx4 v[134:135], v[102:105], off
	v_pk_add_f32 v[98:99], v[98:99], v[208:209]
	v_pk_add_f32 v[100:101], v[100:101], v[210:211]
	global_store_dwordx4 v[134:135], v[98:101], off offset:64
	global_load_dwordx4 v[180:183], v[140:141], off offset:512
	global_load_dwordx4 v[184:187], v[140:141], off offset:576
	global_load_dwordx4 v[188:191], v[138:139], off offset:512
	global_load_dwordx4 v[192:195], v[138:139], off offset:576
	global_load_dwordx4 v[196:199], v[136:137], off offset:512
	global_load_dwordx4 v[200:203], v[136:137], off offset:576
	global_load_dwordx4 v[204:207], v[134:135], off offset:512
	global_load_dwordx4 v[208:211], v[134:135], off offset:576
	s_waitcnt vmcnt(0)
	v_pk_add_f32 v[94:95], v[94:95], v[180:181]
	v_pk_add_f32 v[96:97], v[96:97], v[182:183]
	global_store_dwordx4 v[140:141], v[94:97], off offset:512
	v_pk_add_f32 v[90:91], v[90:91], v[184:185]
	v_pk_add_f32 v[92:93], v[92:93], v[186:187]
	global_store_dwordx4 v[140:141], v[90:93], off offset:576
	v_pk_add_f32 v[86:87], v[86:87], v[188:189]
	v_pk_add_f32 v[88:89], v[88:89], v[190:191]
	global_store_dwordx4 v[138:139], v[86:89], off offset:512
	v_pk_add_f32 v[82:83], v[82:83], v[192:193]
	v_pk_add_f32 v[84:85], v[84:85], v[194:195]
	global_store_dwordx4 v[138:139], v[82:85], off offset:576
	v_pk_add_f32 v[78:79], v[78:79], v[196:197]
	v_pk_add_f32 v[80:81], v[80:81], v[198:199]
	global_store_dwordx4 v[136:137], v[78:81], off offset:512
	v_pk_add_f32 v[74:75], v[74:75], v[200:201]
	v_pk_add_f32 v[76:77], v[76:77], v[202:203]
	global_store_dwordx4 v[136:137], v[74:77], off offset:576
	v_pk_add_f32 v[70:71], v[70:71], v[204:205]
	v_pk_add_f32 v[72:73], v[72:73], v[206:207]
	global_store_dwordx4 v[134:135], v[70:73], off offset:512
	v_pk_add_f32 v[66:67], v[66:67], v[208:209]
	v_pk_add_f32 v[68:69], v[68:69], v[210:211]
	global_store_dwordx4 v[134:135], v[66:69], off offset:576
	s_nop 1
	v_add_u32_e32 v66, 0x80, v130
	v_ashrrev_i32_e32 v67, 31, v66
	v_lshlrev_b64 v[66:67], 13, v[66:67]
	v_lshl_add_u64 v[66:67], s[72:73], 0, v[66:67]
	v_lshl_add_u64 v[72:73], v[66:67], 0, v[132:133]
	v_add_u32_e32 v66, 0x90, v130
	v_ashrrev_i32_e32 v67, 31, v66
	v_lshlrev_b64 v[66:67], 13, v[66:67]
	v_lshl_add_u64 v[66:67], s[72:73], 0, v[66:67]
	v_lshl_add_u64 v[70:71], v[66:67], 0, v[132:133]
	v_add_u32_e32 v66, 0xa0, v130
	v_ashrrev_i32_e32 v67, 31, v66
	v_lshlrev_b64 v[66:67], 13, v[66:67]
	v_lshl_add_u64 v[66:67], s[72:73], 0, v[66:67]
	v_lshl_add_u64 v[68:69], v[66:67], 0, v[132:133]
	v_add_u32_e32 v66, 0xb0, v130
	v_ashrrev_i32_e32 v67, 31, v66
	v_lshlrev_b64 v[66:67], 13, v[66:67]
	v_lshl_add_u64 v[66:67], s[72:73], 0, v[66:67]
	v_lshl_add_u64 v[66:67], v[66:67], 0, v[132:133]
	global_load_dwordx4 v[180:183], v[72:73], off
	global_load_dwordx4 v[184:187], v[72:73], off offset:64
	global_load_dwordx4 v[188:191], v[70:71], off
	global_load_dwordx4 v[192:195], v[70:71], off offset:64
	global_load_dwordx4 v[196:199], v[68:69], off
	global_load_dwordx4 v[200:203], v[68:69], off offset:64
	global_load_dwordx4 v[204:207], v[66:67], off
	global_load_dwordx4 v[208:211], v[66:67], off offset:64
	s_waitcnt vmcnt(0)
	v_pk_add_f32 v[62:63], v[62:63], v[180:181]
	v_pk_add_f32 v[64:65], v[64:65], v[182:183]
	global_store_dwordx4 v[72:73], v[62:65], off
	v_pk_add_f32 v[58:59], v[58:59], v[184:185]
	v_pk_add_f32 v[60:61], v[60:61], v[186:187]
	global_store_dwordx4 v[72:73], v[58:61], off offset:64
	v_pk_add_f32 v[54:55], v[54:55], v[188:189]
	v_pk_add_f32 v[56:57], v[56:57], v[190:191]
	global_store_dwordx4 v[70:71], v[54:57], off
	v_pk_add_f32 v[50:51], v[50:51], v[192:193]
	v_pk_add_f32 v[52:53], v[52:53], v[194:195]
	global_store_dwordx4 v[70:71], v[50:53], off offset:64
	v_pk_add_f32 v[46:47], v[46:47], v[196:197]
	v_pk_add_f32 v[48:49], v[48:49], v[198:199]
	global_store_dwordx4 v[68:69], v[46:49], off
	v_pk_add_f32 v[42:43], v[42:43], v[200:201]
	v_pk_add_f32 v[44:45], v[44:45], v[202:203]
	global_store_dwordx4 v[68:69], v[42:45], off offset:64
	v_pk_add_f32 v[38:39], v[38:39], v[204:205]
	v_pk_add_f32 v[40:41], v[40:41], v[206:207]
	global_store_dwordx4 v[66:67], v[38:41], off
	v_pk_add_f32 v[34:35], v[34:35], v[208:209]
	v_pk_add_f32 v[36:37], v[36:37], v[210:211]
	global_store_dwordx4 v[66:67], v[34:37], off offset:64
	global_load_dwordx4 v[180:183], v[72:73], off offset:512
	global_load_dwordx4 v[184:187], v[72:73], off offset:576
	global_load_dwordx4 v[188:191], v[70:71], off offset:512
	global_load_dwordx4 v[192:195], v[70:71], off offset:576
	global_load_dwordx4 v[196:199], v[68:69], off offset:512
	global_load_dwordx4 v[200:203], v[68:69], off offset:576
	global_load_dwordx4 v[204:207], v[66:67], off offset:512
	global_load_dwordx4 v[208:211], v[66:67], off offset:576
	s_waitcnt vmcnt(0)
	v_pk_add_f32 v[30:31], v[30:31], v[180:181]
	v_pk_add_f32 v[32:33], v[32:33], v[182:183]
	global_store_dwordx4 v[72:73], v[30:33], off offset:512
	v_pk_add_f32 v[26:27], v[26:27], v[184:185]
	v_pk_add_f32 v[28:29], v[28:29], v[186:187]
	global_store_dwordx4 v[72:73], v[26:29], off offset:576
	v_pk_add_f32 v[22:23], v[22:23], v[188:189]
	v_pk_add_f32 v[24:25], v[24:25], v[190:191]
	global_store_dwordx4 v[70:71], v[22:25], off offset:512
	v_pk_add_f32 v[18:19], v[18:19], v[192:193]
	v_pk_add_f32 v[20:21], v[20:21], v[194:195]
	global_store_dwordx4 v[70:71], v[18:21], off offset:576
	v_pk_add_f32 v[14:15], v[14:15], v[196:197]
	v_pk_add_f32 v[16:17], v[16:17], v[198:199]
	global_store_dwordx4 v[68:69], v[14:17], off offset:512
	v_pk_add_f32 v[10:11], v[10:11], v[200:201]
	v_pk_add_f32 v[12:13], v[12:13], v[202:203]
	global_store_dwordx4 v[68:69], v[10:13], off offset:576
	v_pk_add_f32 v[6:7], v[6:7], v[204:205]
	v_pk_add_f32 v[8:9], v[8:9], v[206:207]
	global_store_dwordx4 v[66:67], v[6:9], off offset:512
	v_pk_add_f32 v[2:3], v[2:3], v[208:209]
	v_pk_add_f32 v[4:5], v[4:5], v[210:211]
	global_store_dwordx4 v[66:67], v[2:5], off offset:576
	s_and_b64 vcc, exec, s[0:1]
	s_mov_b32 s8, s5
	s_mov_b32 s7, s6
	s_cbranch_vccz .LBB0_29
; #define WAIT_V(n) asm volatile("s_waitcnt vmcnt(" #n ")" ::: "memory")
; #define BAR __builtin_amdgcn_s_barrier()
; template <class EPI>
; DI void gemm_stream(const u16* __restrict__ A, const u16* __restrict__ Bt, const int K, const int nM, const int nN,
;                     const int bid, const int nb, const int tid, EPI epi) {
;     ...
;   WAIT_V(0);
;   if (wr == 0) BAR;
;   BAR;
	s_waitcnt vmcnt(0)
	s_movk_i32 s0, 0x100
	v_cmp_gt_u32_e32 vcc, s0, v239
	s_and_saveexec_b64 s[0:1], vcc
	s_cbranch_execz .LBB0_36
	s_barrier

; #define WAIT_V(n) asm volatile("s_waitcnt vmcnt(" #n ")" ::: "memory")
; #define BAR __builtin_amdgcn_s_barrier()
; template <class EPI>
; DI void gemm_stream(const u16* __restrict__ A, const u16* __restrict__ Bt, const int K, const int nM, const int nN,
;                     const int bid, const int nb, const int tid, EPI epi) {
;     ...
;   unsigned so0, so1;
;   { int r0, c0; stage_rc(tid * 16, r0, c0); so0 = (unsigned)((r0 * K + c0) * 2); so1 = so0 + (unsigned)(64 * K * 2); }
;   const int lanepart = lds_byte(fr, fq * 8);
;   const int aoff = wr * 8192 + lanepart, boff = wc * 4096 + lanepart;
;   const int nt = K / BK;
;   int pm, pn; gemm_tile_coords(bid, nM, nN, pm, pn);
;   int brow = pm * BM, bcol = pn * BM;
;   GemmAcc acc = {};
;   STAGE(SB(0, 0), Bt, bcol, 0); STAGE(SA(0, 0), A, brow, 0);
;   STAGE(SB(0, 1), Bt, bcol + HALF, 0); STAGE(SA(0, 1), A, brow + HALF, 0);
;   if (wr == 1) BAR;
;   WAIT_V(4); BAR;
;   STAGE(SB(1, 0), Bt, bcol, 1); STAGE(SA(1, 0), A, brow, 1); STAGE(SB(1, 1), Bt, bcol + HALF, 1);
;   WAIT_V(6); BAR;
.LBB0_42:
	s_or_b64 exec, exec, s[0:1]
	v_add_u32_e32 v139, 0x18000, v0
	s_or_b32 s0, s4, 0x80
	v_readfirstlane_b32 s1, v139
	v_add_u32_e32 v6, s0, v130
	s_mov_b32 m0, s1
	v_add_u32_e32 v140, 0x1a000, v0
	s_waitcnt vmcnt(2)
	s_barrier
	global_load_lds_dwordx4 v6, s[82:83]
	v_add_u32_e32 v6, s0, v131
	v_readfirstlane_b32 s0, v140
	v_add_u32_e32 v141, 0x8000, v0
	s_mov_b32 m0, s0
	s_bitset1_b32 s5, 7
	v_readfirstlane_b32 s0, v141
	v_add_u32_e32 v142, 0xa000, v0
	global_load_lds_dwordx4 v6, s[82:83]
	v_add_u32_e32 v6, s5, v130
	s_mov_b32 m0, s0
	v_readfirstlane_b32 s0, v142
	v_add_u32_e32 v143, 0x1c000, v0
	global_load_lds_dwordx4 v6, s[80:81]
	v_add_u32_e32 v6, s5, v131
	s_mov_b32 m0, s0
	s_or_b32 s0, s4, 0x80080
	v_readfirstlane_b32 s1, v143
	global_load_lds_dwordx4 v6, s[80:81]
	v_add_u32_e32 v6, s0, v130
	s_mov_b32 m0, s1
	v_add_u32_e32 v144, 0x1e000, v0
	global_load_lds_dwordx4 v6, s[82:83]
	v_add_u32_e32 v6, s0, v131
	v_readfirstlane_b32 s0, v144
	s_mov_b32 m0, s0
	v_and_b32_e32 v7, 48, v239
	global_load_lds_dwordx4 v6, s[82:83]
	v_and_b32_e32 v6, 15, v239
	v_lshlrev_b32_e32 v6, 6, v6
	v_lshlrev_b32_e32 v9, 2, v239
	v_or_b32_e32 v8, v6, v7
	v_and_b32_e32 v9, 32, v9
	v_lshlrev_b32_e32 v3, 13, v3
	v_bitop3_b32 v6, v6, v9, v7 bitop3:0x36
	v_bitop3_b32 v145, v8, v3, v9 bitop3:0xde
	v_lshlrev_b32_e32 v3, 6, v239
	s_movk_i32 s0, 0x3000
	v_and_or_b32 v146, v3, s0, v6
	v_lshlrev_b32_e32 v3, 15, v2
	v_and_b32_e32 v3, 0xffff0000, v3
	v_lshl_add_u32 v3, v4, 12, v3
	v_and_b32_e32 v2, 1, v2
	s_waitcnt vmcnt(6)
	v_lshl_or_b32 v2, v2, 6, v3
	v_mov_b32_e32 v3, 1
	s_sext_i32_i16 s7, s3
	v_lshlrev_b32_sdwa v3, v3, sext(v5) dst_sel:DWORD dst_unused:UNUSED_PAD src0_sel:DWORD src1_sel:WORD_0
	s_mov_b32 s0, 0xc0080
	s_lshl_b32 s8, s2, 8
	s_lshl_b32 s9, s7, 8
	v_add3_u32 v147, v2, v3, s0
	s_mov_b32 s3, s45
	s_mov_b32 s4, s7
	s_barrier

.LBB0_46:
	v_or_b32_e32 v149, 0x10000, v146
	v_add_u32_e32 v154, 0x10400, v146
	ds_read_b128 v[150:153], v149
	ds_read_b128 v[154:157], v154
	v_add_u32_e32 v149, 0x10800, v146
	v_add_u32_e32 v162, 0x10c00, v146
	ds_read_b128 v[158:161], v149
	ds_read_b128 v[166:169], v162
	s_add_i32 s11, s10, -2
	s_cmp_lt_u32 s11, 30
	s_cselect_b32 s12, s9, s6
	s_cselect_b32 s13, s8, s5
	v_add_u32_e32 v162, 0xc000, v0
	v_add_u32_e32 v149, 0xfffc0000, v148
	v_readfirstlane_b32 s14, v162
	s_mov_b32 m0, s14
	ds_read_b128 v[170:173], v145
	ds_read_b128 v[174:177], v145 offset:1024
	ds_read_b128 v[180:183], v145 offset:2048
	ds_read_b128 v[184:187], v145 offset:3072
	ds_read_b128 v[188:191], v145 offset:4096
	ds_read_b128 v[192:195], v145 offset:5120
	ds_read_b128 v[196:199], v145 offset:6144
	ds_read_b128 v[200:203], v145 offset:7168
	global_load_lds_dwordx4 v149, s[80:81]
	v_add_u32_e32 v149, 0xe000, v0
	s_nop 0
	v_readfirstlane_b32 s14, v149
	s_mov_b32 m0, s14
	s_nop 0
	global_load_lds_dwordx4 v148, s[80:81]
	s_waitcnt lgkmcnt(8)
	v_or_b32_e32 v149, 0x14000, v146
	v_add_u32_e32 v162, 0x14400, v146
	ds_read_b128 v[204:207], v149
	ds_read_b128 v[208:211], v162
	v_add_u32_e32 v149, 0x14800, v146
	v_add_u32_e32 v162, 0x14c00, v146
	ds_read_b128 v[212:215], v149
	ds_read_b128 v[216:219], v162
	s_waitcnt vmcnt(8)
	s_waitcnt lgkmcnt(0)
	s_barrier
	s_setprio 1
	v_mfma_f32_16x16x32_bf16 v[126:129], v[150:153], v[170:173], v[126:129]
	v_mfma_f32_16x16x32_bf16 v[118:121], v[158:161], v[170:173], v[118:121]
	v_mfma_f32_16x16x32_bf16 v[110:113], v[150:153], v[180:183], v[110:113]
	v_mfma_f32_16x16x32_bf16 v[102:105], v[158:161], v[180:183], v[102:105]
	v_mfma_f32_16x16x32_bf16 v[94:97], v[150:153], v[188:191], v[94:97]
	v_mfma_f32_16x16x32_bf16 v[86:89], v[158:161], v[188:191], v[86:89]
	v_mfma_f32_16x16x32_bf16 v[78:81], v[150:153], v[196:199], v[78:81]
	v_mfma_f32_16x16x32_bf16 v[70:73], v[158:161], v[196:199], v[70:73]
	v_mfma_f32_16x16x32_bf16 v[126:129], v[154:157], v[174:177], v[126:129]
	v_mfma_f32_16x16x32_bf16 v[118:121], v[166:169], v[174:177], v[118:121]
	v_mfma_f32_16x16x32_bf16 v[110:113], v[154:157], v[184:187], v[110:113]
	v_mfma_f32_16x16x32_bf16 v[102:105], v[166:169], v[184:187], v[102:105]
	v_mfma_f32_16x16x32_bf16 v[94:97], v[154:157], v[192:195], v[94:97]
	v_mfma_f32_16x16x32_bf16 v[86:89], v[166:169], v[192:195], v[86:89]
	v_mfma_f32_16x16x32_bf16 v[78:81], v[154:157], v[200:203], v[78:81]
	v_mfma_f32_16x16x32_bf16 v[70:73], v[166:169], v[200:203], v[70:73]
	v_mfma_f32_16x16x32_bf16 v[122:125], v[204:207], v[170:173], v[122:125]
	v_mfma_f32_16x16x32_bf16 v[114:117], v[212:215], v[170:173], v[114:117]
	v_mfma_f32_16x16x32_bf16 v[106:109], v[204:207], v[180:183], v[106:109]
	v_mfma_f32_16x16x32_bf16 v[98:101], v[212:215], v[180:183], v[98:101]
	v_mfma_f32_16x16x32_bf16 v[90:93], v[204:207], v[188:191], v[90:93]
	v_mfma_f32_16x16x32_bf16 v[82:85], v[212:215], v[188:191], v[82:85]
	v_mfma_f32_16x16x32_bf16 v[74:77], v[204:207], v[196:199], v[74:77]
	v_mfma_f32_16x16x32_bf16 v[66:69], v[212:215], v[196:199], v[66:69]
	v_mfma_f32_16x16x32_bf16 v[122:125], v[208:211], v[174:177], v[122:125]
	v_mfma_f32_16x16x32_bf16 v[114:117], v[216:219], v[174:177], v[114:117]
	v_mfma_f32_16x16x32_bf16 v[106:109], v[208:211], v[184:187], v[106:109]
	v_mfma_f32_16x16x32_bf16 v[98:101], v[216:219], v[184:187], v[98:101]
	v_mfma_f32_16x16x32_bf16 v[90:93], v[208:211], v[192:195], v[90:93]
	v_mfma_f32_16x16x32_bf16 v[82:85], v[216:219], v[192:195], v[82:85]
	v_mfma_f32_16x16x32_bf16 v[74:77], v[208:211], v[200:203], v[74:77]
	v_mfma_f32_16x16x32_bf16 v[66:69], v[216:219], v[200:203], v[66:69]
	s_setprio 0
	s_barrier
	s_cselect_b32 s14, s10, 0
	s_lshl_b32 s12, s12, 11
	s_lshl_b32 s15, s14, 6
	s_or_b32 s16, s12, s15
	s_lshl_b32 s16, s16, 1
	v_readfirstlane_b32 s17, v132
	v_add_u32_e32 v149, s16, v130
	s_mov_b32 m0, s17
	s_nop 0
	global_load_lds_dwordx4 v149, s[82:83]
	v_add_u32_e32 v149, s16, v131
	v_readfirstlane_b32 s16, v133
	s_mov_b32 m0, s16
	s_nop 0
	global_load_lds_dwordx4 v149, s[82:83]
	s_lshl_b32 s16, s13, 11
	s_or_b32 s17, s16, s15
	s_lshl_b32 s17, s17, 1
	v_readfirstlane_b32 s18, v0
	v_add_u32_e32 v149, s17, v130
	s_mov_b32 m0, s18
	ds_read_b128 v[170:173], v145 offset:16384
	ds_read_b128 v[174:177], v145 offset:17408
	ds_read_b128 v[180:183], v145 offset:18432
	ds_read_b128 v[184:187], v145 offset:19456
	ds_read_b128 v[188:191], v145 offset:20480
	ds_read_b128 v[192:195], v145 offset:21504
	ds_read_b128 v[196:199], v145 offset:22528
	ds_read_b128 v[200:203], v145 offset:23552
	global_load_lds_dwordx4 v149, s[80:81]
	v_add_u32_e32 v149, s17, v131
	v_readfirstlane_b32 s17, v134
	s_mov_b32 m0, s17
	s_nop 0
	global_load_lds_dwordx4 v149, s[80:81]
	s_or_b32 s17, s12, 0x40000
	s_or_b32 s18, s17, s15
	s_lshl_b32 s18, s18, 1
	v_readfirstlane_b32 s19, v135
	v_add_u32_e32 v149, s18, v130
	s_mov_b32 m0, s19
	s_nop 0
	global_load_lds_dwordx4 v149, s[82:83]
	v_add_u32_e32 v149, s18, v131
	v_readfirstlane_b32 s18, v136
	s_mov_b32 m0, s18
	s_nop 0
	global_load_lds_dwordx4 v149, s[82:83]
	s_waitcnt vmcnt(8)
	s_waitcnt lgkmcnt(0)
	s_barrier
	s_setprio 1
	v_mfma_f32_16x16x32_bf16 v[62:65], v[150:153], v[170:173], v[62:65]
	v_mfma_f32_16x16x32_bf16 v[54:57], v[158:161], v[170:173], v[54:57]
	v_mfma_f32_16x16x32_bf16 v[46:49], v[150:153], v[180:183], v[46:49]
	v_mfma_f32_16x16x32_bf16 v[38:41], v[158:161], v[180:183], v[38:41]
	v_mfma_f32_16x16x32_bf16 v[30:33], v[150:153], v[188:191], v[30:33]
	v_mfma_f32_16x16x32_bf16 v[22:25], v[158:161], v[188:191], v[22:25]
	v_mfma_f32_16x16x32_bf16 v[14:17], v[150:153], v[196:199], v[14:17]
	v_mfma_f32_16x16x32_bf16 v[6:9], v[158:161], v[196:199], v[6:9]
	v_mfma_f32_16x16x32_bf16 v[62:65], v[154:157], v[174:177], v[62:65]
	v_mfma_f32_16x16x32_bf16 v[54:57], v[166:169], v[174:177], v[54:57]
	v_mfma_f32_16x16x32_bf16 v[46:49], v[154:157], v[184:187], v[46:49]
	v_mfma_f32_16x16x32_bf16 v[38:41], v[166:169], v[184:187], v[38:41]
	v_mfma_f32_16x16x32_bf16 v[30:33], v[154:157], v[192:195], v[30:33]
	v_mfma_f32_16x16x32_bf16 v[22:25], v[166:169], v[192:195], v[22:25]
	v_mfma_f32_16x16x32_bf16 v[14:17], v[154:157], v[200:203], v[14:17]
	v_mfma_f32_16x16x32_bf16 v[6:9], v[166:169], v[200:203], v[6:9]
	v_mfma_f32_16x16x32_bf16 v[58:61], v[204:207], v[170:173], v[58:61]
	v_mfma_f32_16x16x32_bf16 v[50:53], v[212:215], v[170:173], v[50:53]
	v_mfma_f32_16x16x32_bf16 v[42:45], v[204:207], v[180:183], v[42:45]
	v_mfma_f32_16x16x32_bf16 v[34:37], v[212:215], v[180:183], v[34:37]
	v_mfma_f32_16x16x32_bf16 v[26:29], v[204:207], v[188:191], v[26:29]
	v_mfma_f32_16x16x32_bf16 v[18:21], v[212:215], v[188:191], v[18:21]
	v_mfma_f32_16x16x32_bf16 v[10:13], v[204:207], v[196:199], v[10:13]
	v_mfma_f32_16x16x32_bf16 v[2:5], v[212:215], v[196:199], v[2:5]
	v_mfma_f32_16x16x32_bf16 v[58:61], v[208:211], v[174:177], v[58:61]
	v_mfma_f32_16x16x32_bf16 v[50:53], v[216:219], v[174:177], v[50:53]
	v_mfma_f32_16x16x32_bf16 v[42:45], v[208:211], v[184:187], v[42:45]
	v_mfma_f32_16x16x32_bf16 v[34:37], v[216:219], v[184:187], v[34:37]
	v_mfma_f32_16x16x32_bf16 v[26:29], v[208:211], v[192:195], v[26:29]
	v_mfma_f32_16x16x32_bf16 v[18:21], v[216:219], v[192:195], v[18:21]
	v_mfma_f32_16x16x32_bf16 v[10:13], v[208:211], v[200:203], v[10:13]
	v_mfma_f32_16x16x32_bf16 v[2:5], v[216:219], v[200:203], v[2:5]
	s_setprio 0
	s_barrier
	v_or_b32_e32 v149, 0x18000, v146
	v_add_u32_e32 v154, 0x18400, v146
	ds_read_b128 v[150:153], v149
	ds_read_b128 v[154:157], v154
	v_add_u32_e32 v149, 0x18800, v146
	v_add_u32_e32 v162, 0x18c00, v146
	ds_read_b128 v[158:161], v149
	ds_read_b128 v[166:169], v162
	s_lshl_b32 s13, s13, 12
	s_lshl_b32 s14, s14, 7
	s_add_i32 s13, s14, s13
	s_add_i32 s13, s13, 0x80000
	v_readfirstlane_b32 s14, v137
	v_add_u32_e32 v149, s13, v130
	s_mov_b32 m0, s14
	ds_read_b128 v[170:173], v145 offset:32768
	ds_read_b128 v[174:177], v145 offset:33792
	ds_read_b128 v[180:183], v145 offset:34816
	ds_read_b128 v[184:187], v145 offset:35840
	ds_read_b128 v[188:191], v145 offset:36864
	ds_read_b128 v[192:195], v145 offset:37888
	ds_read_b128 v[196:199], v145 offset:38912
	ds_read_b128 v[200:203], v145 offset:39936
	global_load_lds_dwordx4 v149, s[80:81]
	v_add_u32_e32 v149, s13, v131
	v_readfirstlane_b32 s13, v138
	s_mov_b32 m0, s13
	s_nop 0
	global_load_lds_dwordx4 v149, s[80:81]
	s_waitcnt lgkmcnt(8)
	v_or_b32_e32 v149, 0x1c000, v146
	v_add_u32_e32 v162, 0x1c400, v146
	ds_read_b128 v[204:207], v149
	ds_read_b128 v[208:211], v162
	v_add_u32_e32 v149, 0x1c800, v146
	v_add_u32_e32 v162, 0x1cc00, v146
	ds_read_b128 v[212:215], v149
	ds_read_b128 v[216:219], v162
	s_waitcnt vmcnt(8)
	s_waitcnt lgkmcnt(0)
	s_barrier
	s_setprio 1
	v_mfma_f32_16x16x32_bf16 v[126:129], v[150:153], v[170:173], v[126:129]
	v_mfma_f32_16x16x32_bf16 v[118:121], v[158:161], v[170:173], v[118:121]
	v_mfma_f32_16x16x32_bf16 v[110:113], v[150:153], v[180:183], v[110:113]
	v_mfma_f32_16x16x32_bf16 v[102:105], v[158:161], v[180:183], v[102:105]
	v_mfma_f32_16x16x32_bf16 v[94:97], v[150:153], v[188:191], v[94:97]
	v_mfma_f32_16x16x32_bf16 v[86:89], v[158:161], v[188:191], v[86:89]
	v_mfma_f32_16x16x32_bf16 v[78:81], v[150:153], v[196:199], v[78:81]
	v_mfma_f32_16x16x32_bf16 v[70:73], v[158:161], v[196:199], v[70:73]
	v_mfma_f32_16x16x32_bf16 v[126:129], v[154:157], v[174:177], v[126:129]
	v_mfma_f32_16x16x32_bf16 v[118:121], v[166:169], v[174:177], v[118:121]
	v_mfma_f32_16x16x32_bf16 v[110:113], v[154:157], v[184:187], v[110:113]
	v_mfma_f32_16x16x32_bf16 v[102:105], v[166:169], v[184:187], v[102:105]
	v_mfma_f32_16x16x32_bf16 v[94:97], v[154:157], v[192:195], v[94:97]
	v_mfma_f32_16x16x32_bf16 v[86:89], v[166:169], v[192:195], v[86:89]
	v_mfma_f32_16x16x32_bf16 v[78:81], v[154:157], v[200:203], v[78:81]
	v_mfma_f32_16x16x32_bf16 v[70:73], v[166:169], v[200:203], v[70:73]
	v_mfma_f32_16x16x32_bf16 v[122:125], v[204:207], v[170:173], v[122:125]
	v_mfma_f32_16x16x32_bf16 v[114:117], v[212:215], v[170:173], v[114:117]
	v_mfma_f32_16x16x32_bf16 v[106:109], v[204:207], v[180:183], v[106:109]
	v_mfma_f32_16x16x32_bf16 v[98:101], v[212:215], v[180:183], v[98:101]
	v_mfma_f32_16x16x32_bf16 v[90:93], v[204:207], v[188:191], v[90:93]
	v_mfma_f32_16x16x32_bf16 v[82:85], v[212:215], v[188:191], v[82:85]
	v_mfma_f32_16x16x32_bf16 v[74:77], v[204:207], v[196:199], v[74:77]
	v_mfma_f32_16x16x32_bf16 v[66:69], v[212:215], v[196:199], v[66:69]
	v_mfma_f32_16x16x32_bf16 v[122:125], v[208:211], v[174:177], v[122:125]
	v_mfma_f32_16x16x32_bf16 v[114:117], v[216:219], v[174:177], v[114:117]
	v_mfma_f32_16x16x32_bf16 v[106:109], v[208:211], v[184:187], v[106:109]
	v_mfma_f32_16x16x32_bf16 v[98:101], v[216:219], v[184:187], v[98:101]
	v_mfma_f32_16x16x32_bf16 v[90:93], v[208:211], v[192:195], v[90:93]
	v_mfma_f32_16x16x32_bf16 v[82:85], v[216:219], v[192:195], v[82:85]
	v_mfma_f32_16x16x32_bf16 v[74:77], v[208:211], v[200:203], v[74:77]
	v_mfma_f32_16x16x32_bf16 v[66:69], v[216:219], v[200:203], v[66:69]
	s_setprio 0
	s_barrier
; DI float sigmoidf_(float v) { return __builtin_amdgcn_rcpf(1.f + __expf(-v)); }
; DI void gemm_gateup(const Params& p, int bid, int nb, int tid) {
;     ...
;     _Pragma("unroll") for (int ai = 0; ai < 2; ++ai) _Pragma("unroll") for (int m = 0; m < 4; ++m) _Pragma("unroll") for (int n = 0; n < 2; ++n) {
;       const int col = pn * 128 + wc * 32 + n * 16 + fq * 4;
;       const int row = brow + ai * HALF + wr * 64 + m * 16 + fr;
;       const f32x4 g = acc[ai][0][m][n], uu = acc[ai][1][m][n];
;       uint2 w;
;       w.x = pk2(g[0] * sigmoidf_(g[0]) * uu[0], g[1] * sigmoidf_(g[1]) * uu[1]);
;       w.y = pk2(g[2] * sigmoidf_(g[2]) * uu[2], g[3] * sigmoidf_(g[3]) * uu[3]);
;       *reinterpret_cast<uint2*>(C + (size_t)row * DFF + col) = w;
	s_or_b32 s13, s15, 64
	s_or_b32 s12, s13, s12
	s_lshl_b32 s12, s12, 1
	v_readfirstlane_b32 s14, v139
	v_add_u32_e32 v149, s12, v130
	s_mov_b32 m0, s14
	s_nop 0
	global_load_lds_dwordx4 v149, s[82:83]
	v_add_u32_e32 v149, s12, v131
	v_readfirstlane_b32 s12, v140
	s_mov_b32 m0, s12
	s_nop 0
	global_load_lds_dwordx4 v149, s[82:83]
	s_or_b32 s12, s13, s16
	s_lshl_b32 s12, s12, 1
	v_readfirstlane_b32 s14, v141
	v_add_u32_e32 v149, s12, v130
	s_mov_b32 m0, s14
	ds_read_b128 v[170:173], v145 offset:49152
	ds_read_b128 v[174:177], v145 offset:50176
	ds_read_b128 v[180:183], v145 offset:51200
	ds_read_b128 v[184:187], v145 offset:52224
	ds_read_b128 v[188:191], v145 offset:53248
	ds_read_b128 v[192:195], v145 offset:54272
	ds_read_b128 v[196:199], v145 offset:55296
	ds_read_b128 v[200:203], v145 offset:56320
	global_load_lds_dwordx4 v149, s[80:81]
	v_add_u32_e32 v149, s12, v131
	v_readfirstlane_b32 s12, v142
	s_mov_b32 m0, s12
	s_nop 0
	global_load_lds_dwordx4 v149, s[80:81]
	s_or_b32 s12, s17, s13
	s_lshl_b32 s12, s12, 1
	v_readfirstlane_b32 s13, v143
	v_add_u32_e32 v149, s12, v130
	s_mov_b32 m0, s13
	s_nop 0
	global_load_lds_dwordx4 v149, s[82:83]
	v_add_u32_e32 v149, s12, v131
	v_readfirstlane_b32 s12, v144
	s_mov_b32 m0, s12
	s_nop 0
	global_load_lds_dwordx4 v149, s[82:83]
	s_waitcnt vmcnt(8)
	s_waitcnt lgkmcnt(0)
	s_barrier
	s_setprio 1
	v_mfma_f32_16x16x32_bf16 v[62:65], v[150:153], v[170:173], v[62:65]
	v_mfma_f32_16x16x32_bf16 v[54:57], v[158:161], v[170:173], v[54:57]
	v_mfma_f32_16x16x32_bf16 v[46:49], v[150:153], v[180:183], v[46:49]
	v_mfma_f32_16x16x32_bf16 v[38:41], v[158:161], v[180:183], v[38:41]
	v_mfma_f32_16x16x32_bf16 v[30:33], v[150:153], v[188:191], v[30:33]
	v_mfma_f32_16x16x32_bf16 v[22:25], v[158:161], v[188:191], v[22:25]
	v_mfma_f32_16x16x32_bf16 v[14:17], v[150:153], v[196:199], v[14:17]
	v_mfma_f32_16x16x32_bf16 v[6:9], v[158:161], v[196:199], v[6:9]
	v_mfma_f32_16x16x32_bf16 v[62:65], v[154:157], v[174:177], v[62:65]
	v_mfma_f32_16x16x32_bf16 v[54:57], v[166:169], v[174:177], v[54:57]
	v_mfma_f32_16x16x32_bf16 v[46:49], v[154:157], v[184:187], v[46:49]
	v_mfma_f32_16x16x32_bf16 v[38:41], v[166:169], v[184:187], v[38:41]
	v_mfma_f32_16x16x32_bf16 v[30:33], v[154:157], v[192:195], v[30:33]
	v_mfma_f32_16x16x32_bf16 v[22:25], v[166:169], v[192:195], v[22:25]
	v_mfma_f32_16x16x32_bf16 v[14:17], v[154:157], v[200:203], v[14:17]
	v_mfma_f32_16x16x32_bf16 v[6:9], v[166:169], v[200:203], v[6:9]
	v_mfma_f32_16x16x32_bf16 v[58:61], v[204:207], v[170:173], v[58:61]
	v_mfma_f32_16x16x32_bf16 v[50:53], v[212:215], v[170:173], v[50:53]
	v_mfma_f32_16x16x32_bf16 v[42:45], v[204:207], v[180:183], v[42:45]
	v_mfma_f32_16x16x32_bf16 v[34:37], v[212:215], v[180:183], v[34:37]
	v_mfma_f32_16x16x32_bf16 v[26:29], v[204:207], v[188:191], v[26:29]
	v_mfma_f32_16x16x32_bf16 v[18:21], v[212:215], v[188:191], v[18:21]
	v_mfma_f32_16x16x32_bf16 v[10:13], v[204:207], v[196:199], v[10:13]
	v_mfma_f32_16x16x32_bf16 v[2:5], v[212:215], v[196:199], v[2:5]
	v_mfma_f32_16x16x32_bf16 v[58:61], v[208:211], v[174:177], v[58:61]
	v_mfma_f32_16x16x32_bf16 v[50:53], v[216:219], v[174:177], v[50:53]
	v_mfma_f32_16x16x32_bf16 v[42:45], v[208:211], v[184:187], v[42:45]
	v_mfma_f32_16x16x32_bf16 v[34:37], v[216:219], v[184:187], v[34:37]
	v_mfma_f32_16x16x32_bf16 v[26:29], v[208:211], v[192:195], v[26:29]
	v_mfma_f32_16x16x32_bf16 v[18:21], v[216:219], v[192:195], v[18:21]
	v_mfma_f32_16x16x32_bf16 v[10:13], v[208:211], v[200:203], v[10:13]
	v_mfma_f32_16x16x32_bf16 v[2:5], v[216:219], v[200:203], v[2:5]
	s_setprio 0
	s_add_i32 s10, s10, 2
	s_cmp_gt_u32 s11, 29
	v_add_u32_e32 v148, 0x100, v148
	s_barrier
	s_cbranch_scc0 .LBB0_46
	v_mov_b32_e32 v148, v239
	s_lshl_b32 s7, s7, 7
	v_lshrrev_b32_e32 v149, 1, v148
	v_lshrrev_b32_e32 v150, 2, v148
	v_and_b32_e32 v149, 0x60, v149
	v_and_b32_e32 v150, 12, v150
	v_or3_b32 v150, v149, s7, v150
	v_ashrrev_i32_e32 v149, 2, v148
	v_and_b32_e32 v149, 0xffffffc0, v149
	v_and_or_b32 v148, v148, 15, s8
	v_add_u32_e32 v148, v148, v149
	v_mul_f32_e32 v149, 0xbfb8aa3b, v126
	v_exp_f32_e32 v149, v149
	s_movk_i32 s7, 0x2c00
	v_ashrrev_i32_e32 v151, 31, v150
	v_add_f32_e32 v149, 1.0, v149
	v_rcp_f32_e32 v152, v149
	v_mul_f32_e32 v149, 0xbfb8aa3b, v127
	v_exp_f32_e32 v149, v149
	s_nop 0
	v_add_f32_e32 v149, 1.0, v149
	v_rcp_f32_e32 v153, v149
	s_nop 0
	v_pk_mul_f32 v[126:127], v[126:127], v[152:153]
	s_nop 0
	v_pk_mul_f32 v[122:123], v[126:127], v[122:123]
	s_nop 0
	v_cvt_pk_bf16_f32 v126, v122, v123
	v_mul_f32_e32 v122, 0xbfb8aa3b, v128
	v_mul_f32_e32 v123, 0xbfb8aa3b, v129
	v_exp_f32_e32 v122, v122
	v_exp_f32_e32 v123, v123
	v_add_f32_e32 v122, 1.0, v122
	v_add_f32_e32 v123, 1.0, v123
	v_rcp_f32_e32 v122, v122
	v_rcp_f32_e32 v123, v123
	s_nop 0
	v_pk_mul_f32 v[122:123], v[128:129], v[122:123]
	s_nop 0
	v_pk_mul_f32 v[122:123], v[122:123], v[124:125]
	v_lshlrev_b64 v[124:125], 1, v[150:151]
	v_cvt_pk_bf16_f32 v127, v122, v123
	v_mov_b64_e32 v[122:123], s[76:77]
	v_mad_i64_i32 v[128:129], s[8:9], v148, s7, v[122:123]
	v_lshl_add_u64 v[128:129], v[128:129], 0, v[124:125]
	global_store_dwordx2 v[128:129], v[126:127], off
	v_mul_f32_e32 v126, 0xbfb8aa3b, v118
	v_mul_f32_e32 v127, 0xbfb8aa3b, v119
	v_exp_f32_e32 v126, v126
	v_exp_f32_e32 v127, v127
	v_add_f32_e32 v126, 1.0, v126
	v_add_f32_e32 v127, 1.0, v127
	v_rcp_f32_e32 v126, v126
	v_rcp_f32_e32 v127, v127
	s_nop 0
	v_pk_mul_f32 v[118:119], v[118:119], v[126:127]
	s_nop 0
	v_pk_mul_f32 v[114:115], v[118:119], v[114:115]
	s_nop 0
	v_cvt_pk_bf16_f32 v114, v114, v115
	v_mul_f32_e32 v115, 0xbfb8aa3b, v120
	v_exp_f32_e32 v115, v115
	s_nop 0
	v_add_f32_e32 v115, 1.0, v115
	v_rcp_f32_e32 v118, v115
; DI float sigmoidf_(float v) { return __builtin_amdgcn_rcpf(1.f + __expf(-v)); }
; #define EPI_SCHED __builtin_amdgcn_sched_barrier(0)
; DI void gemm_gateup(const Params& p, int bid, int nb, int tid) {
;     ...
;     _Pragma("unroll") for (int ai = 0; ai < 2; ++ai) _Pragma("unroll") for (int m = 0; m < 4; ++m) _Pragma("unroll") for (int n = 0; n < 2; ++n) {
;       const int col = pn * 128 + wc * 32 + n * 16 + fq * 4;
;       const int row = brow + ai * HALF + wr * 64 + m * 16 + fr;
;       const f32x4 g = acc[ai][0][m][n], uu = acc[ai][1][m][n];
;       uint2 w;
;       w.x = pk2(g[0] * sigmoidf_(g[0]) * uu[0], g[1] * sigmoidf_(g[1]) * uu[1]);
;       w.y = pk2(g[2] * sigmoidf_(g[2]) * uu[2], g[3] * sigmoidf_(g[3]) * uu[3]);
;       *reinterpret_cast<uint2*>(C + (size_t)row * DFF + col) = w;
;       EPI_SCHED;
;     }
	v_mul_f32_e32 v115, 0xbfb8aa3b, v121
	v_exp_f32_e32 v115, v115
	s_nop 0
	v_add_f32_e32 v115, 1.0, v115
	v_rcp_f32_e32 v119, v115
	s_nop 0
	v_pk_mul_f32 v[118:119], v[120:121], v[118:119]
	s_nop 0
	v_pk_mul_f32 v[116:117], v[118:119], v[116:117]
	s_nop 0
	v_cvt_pk_bf16_f32 v115, v116, v117
	global_store_dwordx2 v[128:129], v[114:115], off offset:32
	v_mul_f32_e32 v114, 0xbfb8aa3b, v110
	v_mul_f32_e32 v115, 0xbfb8aa3b, v111
	v_exp_f32_e32 v114, v114
	v_exp_f32_e32 v115, v115
	v_or_b32_e32 v116, 16, v148
	v_add_f32_e32 v114, 1.0, v114
	v_add_f32_e32 v115, 1.0, v115
	v_rcp_f32_e32 v114, v114
	v_rcp_f32_e32 v115, v115
	s_nop 0
	v_pk_mul_f32 v[110:111], v[110:111], v[114:115]
	s_nop 0
	v_pk_mul_f32 v[106:107], v[110:111], v[106:107]
	s_nop 0
	v_cvt_pk_bf16_f32 v106, v106, v107
	v_mul_f32_e32 v107, 0xbfb8aa3b, v112
	v_exp_f32_e32 v107, v107
	s_nop 0
	v_add_f32_e32 v107, 1.0, v107
	v_rcp_f32_e32 v110, v107
	v_mul_f32_e32 v107, 0xbfb8aa3b, v113
	v_exp_f32_e32 v107, v107
	s_nop 0
	v_add_f32_e32 v107, 1.0, v107
	v_rcp_f32_e32 v111, v107
	s_nop 0
	v_pk_mul_f32 v[110:111], v[112:113], v[110:111]
	s_nop 0
	v_pk_mul_f32 v[108:109], v[110:111], v[108:109]
	s_nop 0
	v_cvt_pk_bf16_f32 v107, v108, v109
	v_mad_i64_i32 v[108:109], s[8:9], v116, s7, v[122:123]
	v_lshl_add_u64 v[108:109], v[108:109], 0, v[124:125]
	global_store_dwordx2 v[108:109], v[106:107], off
	v_mul_f32_e32 v106, 0xbfb8aa3b, v102
	v_mul_f32_e32 v107, 0xbfb8aa3b, v103
	v_exp_f32_e32 v106, v106
	v_exp_f32_e32 v107, v107
	v_add_f32_e32 v106, 1.0, v106
	v_add_f32_e32 v107, 1.0, v107
	v_rcp_f32_e32 v106, v106
	v_rcp_f32_e32 v107, v107
	s_nop 0
	v_pk_mul_f32 v[102:103], v[102:103], v[106:107]
	s_nop 0
	v_pk_mul_f32 v[98:99], v[102:103], v[98:99]
	s_nop 0
	v_cvt_pk_bf16_f32 v98, v98, v99
	v_mul_f32_e32 v99, 0xbfb8aa3b, v104
	v_exp_f32_e32 v99, v99
	s_nop 0
	v_add_f32_e32 v99, 1.0, v99
	v_rcp_f32_e32 v102, v99
	v_mul_f32_e32 v99, 0xbfb8aa3b, v105
	v_exp_f32_e32 v99, v99
	s_nop 0
	v_add_f32_e32 v99, 1.0, v99
	v_rcp_f32_e32 v103, v99
	s_nop 0
	v_pk_mul_f32 v[102:103], v[104:105], v[102:103]
	s_nop 0
	v_pk_mul_f32 v[100:101], v[102:103], v[100:101]
	s_nop 0
	v_cvt_pk_bf16_f32 v99, v100, v101
	global_store_dwordx2 v[108:109], v[98:99], off offset:32
	v_mul_f32_e32 v98, 0xbfb8aa3b, v94
	v_mul_f32_e32 v99, 0xbfb8aa3b, v95
	v_exp_f32_e32 v98, v98
	v_exp_f32_e32 v99, v99
	v_or_b32_e32 v100, 32, v148
	v_add_f32_e32 v98, 1.0, v98
	v_add_f32_e32 v99, 1.0, v99
	v_rcp_f32_e32 v98, v98
	v_rcp_f32_e32 v99, v99
	s_nop 0
	v_pk_mul_f32 v[94:95], v[94:95], v[98:99]
	s_nop 0
	v_pk_mul_f32 v[90:91], v[94:95], v[90:91]
	s_nop 0
	v_cvt_pk_bf16_f32 v90, v90, v91
	v_mul_f32_e32 v91, 0xbfb8aa3b, v96
	v_exp_f32_e32 v91, v91
	s_nop 0
	v_add_f32_e32 v91, 1.0, v91
	v_rcp_f32_e32 v94, v91
	v_mul_f32_e32 v91, 0xbfb8aa3b, v97
	v_exp_f32_e32 v91, v91
	s_nop 0
	v_add_f32_e32 v91, 1.0, v91
	v_rcp_f32_e32 v95, v91
	s_nop 0
	v_pk_mul_f32 v[94:95], v[96:97], v[94:95]
	s_nop 0
	v_pk_mul_f32 v[92:93], v[94:95], v[92:93]
	s_nop 0
	v_cvt_pk_bf16_f32 v91, v92, v93
	v_mad_i64_i32 v[92:93], s[8:9], v100, s7, v[122:123]
	v_lshl_add_u64 v[92:93], v[92:93], 0, v[124:125]
	global_store_dwordx2 v[92:93], v[90:91], off
	v_mul_f32_e32 v90, 0xbfb8aa3b, v86
	v_mul_f32_e32 v91, 0xbfb8aa3b, v87
	v_exp_f32_e32 v90, v90
	v_exp_f32_e32 v91, v91
	v_add_f32_e32 v90, 1.0, v90
	v_add_f32_e32 v91, 1.0, v91
	v_rcp_f32_e32 v90, v90
	v_rcp_f32_e32 v91, v91
	s_nop 0
	v_pk_mul_f32 v[86:87], v[86:87], v[90:91]
	s_nop 0
	v_pk_mul_f32 v[82:83], v[86:87], v[82:83]
	s_nop 0
	v_cvt_pk_bf16_f32 v82, v82, v83
	v_mul_f32_e32 v83, 0xbfb8aa3b, v88
	v_exp_f32_e32 v83, v83
	s_nop 0
	v_add_f32_e32 v83, 1.0, v83
	v_rcp_f32_e32 v86, v83
	v_mul_f32_e32 v83, 0xbfb8aa3b, v89
	v_exp_f32_e32 v83, v83
	s_nop 0
	v_add_f32_e32 v83, 1.0, v83
	v_rcp_f32_e32 v87, v83
	s_nop 0
	v_pk_mul_f32 v[86:87], v[88:89], v[86:87]
	s_nop 0
	v_pk_mul_f32 v[84:85], v[86:87], v[84:85]
	s_nop 0
	v_cvt_pk_bf16_f32 v83, v84, v85
	global_store_dwordx2 v[92:93], v[82:83], off offset:32
	v_mul_f32_e32 v82, 0xbfb8aa3b, v78
	v_mul_f32_e32 v83, 0xbfb8aa3b, v79
	v_exp_f32_e32 v82, v82
	v_exp_f32_e32 v83, v83
	v_or_b32_e32 v84, 48, v148
	v_add_f32_e32 v82, 1.0, v82
	v_add_f32_e32 v83, 1.0, v83
	v_rcp_f32_e32 v82, v82
	v_rcp_f32_e32 v83, v83
	s_nop 0
	v_pk_mul_f32 v[78:79], v[78:79], v[82:83]
	s_nop 0
	v_pk_mul_f32 v[74:75], v[78:79], v[74:75]
	s_nop 0
	v_cvt_pk_bf16_f32 v74, v74, v75
	v_mul_f32_e32 v75, 0xbfb8aa3b, v80
	v_exp_f32_e32 v75, v75
	s_nop 0
	v_add_f32_e32 v75, 1.0, v75
	v_rcp_f32_e32 v78, v75
	v_mul_f32_e32 v75, 0xbfb8aa3b, v81
	v_exp_f32_e32 v75, v75
	s_nop 0
	v_add_f32_e32 v75, 1.0, v75
	v_rcp_f32_e32 v79, v75
	s_nop 0
	v_pk_mul_f32 v[78:79], v[80:81], v[78:79]
	s_nop 0
	v_pk_mul_f32 v[76:77], v[78:79], v[76:77]
	s_nop 0
	v_cvt_pk_bf16_f32 v75, v76, v77
	v_mad_i64_i32 v[76:77], s[8:9], v84, s7, v[122:123]
	v_lshl_add_u64 v[76:77], v[76:77], 0, v[124:125]
	global_store_dwordx2 v[76:77], v[74:75], off
	v_mul_f32_e32 v74, 0xbfb8aa3b, v70
	v_mul_f32_e32 v75, 0xbfb8aa3b, v71
	v_exp_f32_e32 v74, v74
	v_exp_f32_e32 v75, v75
	v_add_f32_e32 v74, 1.0, v74
	v_add_f32_e32 v75, 1.0, v75
	v_rcp_f32_e32 v74, v74
	v_rcp_f32_e32 v75, v75
	s_nop 0
	v_pk_mul_f32 v[70:71], v[70:71], v[74:75]
	s_nop 0
	v_pk_mul_f32 v[66:67], v[70:71], v[66:67]
	s_nop 0
	v_cvt_pk_bf16_f32 v66, v66, v67
	v_mul_f32_e32 v67, 0xbfb8aa3b, v72
	v_exp_f32_e32 v67, v67
	s_nop 0
	v_add_f32_e32 v67, 1.0, v67
	v_rcp_f32_e32 v70, v67
	v_mul_f32_e32 v67, 0xbfb8aa3b, v73
	v_exp_f32_e32 v67, v67
	s_nop 0
	v_add_f32_e32 v67, 1.0, v67
	v_rcp_f32_e32 v71, v67
	s_nop 0
	v_pk_mul_f32 v[70:71], v[72:73], v[70:71]
	s_nop 0
	v_pk_mul_f32 v[68:69], v[70:71], v[68:69]
; DI float sigmoidf_(float v) { return __builtin_amdgcn_rcpf(1.f + __expf(-v)); }
; #define EPI_SCHED __builtin_amdgcn_sched_barrier(0)
; DI void gemm_gateup(const Params& p, int bid, int nb, int tid) {
;     ...
;     _Pragma("unroll") for (int ai = 0; ai < 2; ++ai) _Pragma("unroll") for (int m = 0; m < 4; ++m) _Pragma("unroll") for (int n = 0; n < 2; ++n) {
;       const int col = pn * 128 + wc * 32 + n * 16 + fq * 4;
;       const int row = brow + ai * HALF + wr * 64 + m * 16 + fr;
;       const f32x4 g = acc[ai][0][m][n], uu = acc[ai][1][m][n];
;       uint2 w;
;       w.x = pk2(g[0] * sigmoidf_(g[0]) * uu[0], g[1] * sigmoidf_(g[1]) * uu[1]);
;       w.y = pk2(g[2] * sigmoidf_(g[2]) * uu[2], g[3] * sigmoidf_(g[3]) * uu[3]);
;       *reinterpret_cast<uint2*>(C + (size_t)row * DFF + col) = w;
;       EPI_SCHED;
;     }
	s_nop 0
	v_cvt_pk_bf16_f32 v67, v68, v69
	global_store_dwordx2 v[76:77], v[66:67], off offset:32
	v_mul_f32_e32 v66, 0xbfb8aa3b, v62
	v_mul_f32_e32 v67, 0xbfb8aa3b, v63
	v_exp_f32_e32 v66, v66
	v_exp_f32_e32 v67, v67
	v_add_u32_e32 v68, 0x80, v148
	v_add_f32_e32 v66, 1.0, v66
	v_add_f32_e32 v67, 1.0, v67
	v_rcp_f32_e32 v66, v66
	v_rcp_f32_e32 v67, v67
	s_nop 0
	v_pk_mul_f32 v[62:63], v[62:63], v[66:67]
	s_nop 0
	v_pk_mul_f32 v[58:59], v[62:63], v[58:59]
	s_nop 0
	v_cvt_pk_bf16_f32 v58, v58, v59
	v_mul_f32_e32 v59, 0xbfb8aa3b, v64
	v_exp_f32_e32 v59, v59
	s_nop 0
	v_add_f32_e32 v59, 1.0, v59
	v_rcp_f32_e32 v62, v59
	v_mul_f32_e32 v59, 0xbfb8aa3b, v65
	v_exp_f32_e32 v59, v59
	s_nop 0
	v_add_f32_e32 v59, 1.0, v59
	v_rcp_f32_e32 v63, v59
	s_nop 0
	v_pk_mul_f32 v[62:63], v[64:65], v[62:63]
	s_nop 0
	v_pk_mul_f32 v[60:61], v[62:63], v[60:61]
	s_nop 0
	v_cvt_pk_bf16_f32 v59, v60, v61
	v_mad_i64_i32 v[60:61], s[8:9], v68, s7, v[122:123]
	v_lshl_add_u64 v[60:61], v[60:61], 0, v[124:125]
	global_store_dwordx2 v[60:61], v[58:59], off
	v_mul_f32_e32 v58, 0xbfb8aa3b, v54
	v_mul_f32_e32 v59, 0xbfb8aa3b, v55
	v_exp_f32_e32 v58, v58
	v_exp_f32_e32 v59, v59
	v_add_f32_e32 v58, 1.0, v58
	v_add_f32_e32 v59, 1.0, v59
	v_rcp_f32_e32 v58, v58
	v_rcp_f32_e32 v59, v59
	s_nop 0
	v_pk_mul_f32 v[54:55], v[54:55], v[58:59]
	s_nop 0
	v_pk_mul_f32 v[50:51], v[54:55], v[50:51]
	s_nop 0
	v_cvt_pk_bf16_f32 v50, v50, v51
	v_mul_f32_e32 v51, 0xbfb8aa3b, v56
	v_exp_f32_e32 v51, v51
	s_nop 0
	v_add_f32_e32 v51, 1.0, v51
	v_rcp_f32_e32 v54, v51
	v_mul_f32_e32 v51, 0xbfb8aa3b, v57
	v_exp_f32_e32 v51, v51
	s_nop 0
	v_add_f32_e32 v51, 1.0, v51
	v_rcp_f32_e32 v55, v51
	s_nop 0
	v_pk_mul_f32 v[54:55], v[56:57], v[54:55]
	s_nop 0
	v_pk_mul_f32 v[52:53], v[54:55], v[52:53]
	s_nop 0
	v_cvt_pk_bf16_f32 v51, v52, v53
	global_store_dwordx2 v[60:61], v[50:51], off offset:32
	v_mul_f32_e32 v50, 0xbfb8aa3b, v46
	v_mul_f32_e32 v51, 0xbfb8aa3b, v47
	v_exp_f32_e32 v50, v50
	v_exp_f32_e32 v51, v51
	v_add_u32_e32 v52, 0x90, v148
	v_add_f32_e32 v50, 1.0, v50
	v_add_f32_e32 v51, 1.0, v51
	v_rcp_f32_e32 v50, v50
	v_rcp_f32_e32 v51, v51
	s_nop 0
	v_pk_mul_f32 v[46:47], v[46:47], v[50:51]
	s_nop 0
	v_pk_mul_f32 v[42:43], v[46:47], v[42:43]
	s_nop 0
	v_cvt_pk_bf16_f32 v42, v42, v43
	v_mul_f32_e32 v43, 0xbfb8aa3b, v48
	v_exp_f32_e32 v43, v43
	s_nop 0
	v_add_f32_e32 v43, 1.0, v43
	v_rcp_f32_e32 v46, v43
	v_mul_f32_e32 v43, 0xbfb8aa3b, v49
	v_exp_f32_e32 v43, v43
	s_nop 0
	v_add_f32_e32 v43, 1.0, v43
	v_rcp_f32_e32 v47, v43
	s_nop 0
	v_pk_mul_f32 v[46:47], v[48:49], v[46:47]
	s_nop 0
	v_pk_mul_f32 v[44:45], v[46:47], v[44:45]
	s_nop 0
	v_cvt_pk_bf16_f32 v43, v44, v45
	v_mad_i64_i32 v[44:45], s[8:9], v52, s7, v[122:123]
	v_lshl_add_u64 v[44:45], v[44:45], 0, v[124:125]
	global_store_dwordx2 v[44:45], v[42:43], off
	v_mul_f32_e32 v42, 0xbfb8aa3b, v38
	v_mul_f32_e32 v43, 0xbfb8aa3b, v39
	v_exp_f32_e32 v42, v42
	v_exp_f32_e32 v43, v43
	v_add_f32_e32 v42, 1.0, v42
	v_add_f32_e32 v43, 1.0, v43
	v_rcp_f32_e32 v42, v42
	v_rcp_f32_e32 v43, v43
	s_nop 0
	v_pk_mul_f32 v[38:39], v[38:39], v[42:43]
	s_nop 0
	v_pk_mul_f32 v[34:35], v[38:39], v[34:35]
	s_nop 0
	v_cvt_pk_bf16_f32 v34, v34, v35
	v_mul_f32_e32 v35, 0xbfb8aa3b, v40
	v_exp_f32_e32 v35, v35
	s_nop 0
	v_add_f32_e32 v35, 1.0, v35
	v_rcp_f32_e32 v38, v35
	v_mul_f32_e32 v35, 0xbfb8aa3b, v41
	v_exp_f32_e32 v35, v35
	s_nop 0
	v_add_f32_e32 v35, 1.0, v35
	v_rcp_f32_e32 v39, v35
	s_nop 0
	v_pk_mul_f32 v[38:39], v[40:41], v[38:39]
	s_nop 0
	v_pk_mul_f32 v[36:37], v[38:39], v[36:37]
	s_nop 0
	v_cvt_pk_bf16_f32 v35, v36, v37
	global_store_dwordx2 v[44:45], v[34:35], off offset:32
	v_mul_f32_e32 v34, 0xbfb8aa3b, v30
; DI float sigmoidf_(float v) { return __builtin_amdgcn_rcpf(1.f + __expf(-v)); }
; #define EPI_SCHED __builtin_amdgcn_sched_barrier(0)
; DI void gemm_gateup(const Params& p, int bid, int nb, int tid) {
;     ...
;     _Pragma("unroll") for (int ai = 0; ai < 2; ++ai) _Pragma("unroll") for (int m = 0; m < 4; ++m) _Pragma("unroll") for (int n = 0; n < 2; ++n) {
;       const int col = pn * 128 + wc * 32 + n * 16 + fq * 4;
;       const int row = brow + ai * HALF + wr * 64 + m * 16 + fr;
;       const f32x4 g = acc[ai][0][m][n], uu = acc[ai][1][m][n];
;       uint2 w;
;       w.x = pk2(g[0] * sigmoidf_(g[0]) * uu[0], g[1] * sigmoidf_(g[1]) * uu[1]);
;       w.y = pk2(g[2] * sigmoidf_(g[2]) * uu[2], g[3] * sigmoidf_(g[3]) * uu[3]);
;       *reinterpret_cast<uint2*>(C + (size_t)row * DFF + col) = w;
;       EPI_SCHED;
;     }
	v_mul_f32_e32 v35, 0xbfb8aa3b, v31
	v_exp_f32_e32 v34, v34
	v_exp_f32_e32 v35, v35
	v_add_u32_e32 v36, 0xa0, v148
	v_add_f32_e32 v34, 1.0, v34
	v_add_f32_e32 v35, 1.0, v35
	v_rcp_f32_e32 v34, v34
	v_rcp_f32_e32 v35, v35
	s_nop 0
	v_pk_mul_f32 v[30:31], v[30:31], v[34:35]
	s_nop 0
	v_pk_mul_f32 v[26:27], v[30:31], v[26:27]
	s_nop 0
	v_cvt_pk_bf16_f32 v26, v26, v27
	v_mul_f32_e32 v27, 0xbfb8aa3b, v32
	v_exp_f32_e32 v27, v27
	s_nop 0
	v_add_f32_e32 v27, 1.0, v27
	v_rcp_f32_e32 v30, v27
	v_mul_f32_e32 v27, 0xbfb8aa3b, v33
	v_exp_f32_e32 v27, v27
	s_nop 0
	v_add_f32_e32 v27, 1.0, v27
	v_rcp_f32_e32 v31, v27
	s_nop 0
	v_pk_mul_f32 v[30:31], v[32:33], v[30:31]
	s_nop 0
	v_pk_mul_f32 v[28:29], v[30:31], v[28:29]
	s_nop 0
	v_cvt_pk_bf16_f32 v27, v28, v29
	v_mad_i64_i32 v[28:29], s[8:9], v36, s7, v[122:123]
	v_lshl_add_u64 v[28:29], v[28:29], 0, v[124:125]
	global_store_dwordx2 v[28:29], v[26:27], off
	v_mul_f32_e32 v26, 0xbfb8aa3b, v22
	v_mul_f32_e32 v27, 0xbfb8aa3b, v23
	v_exp_f32_e32 v26, v26
	v_exp_f32_e32 v27, v27
	v_add_f32_e32 v26, 1.0, v26
	v_add_f32_e32 v27, 1.0, v27
	v_rcp_f32_e32 v26, v26
	v_rcp_f32_e32 v27, v27
	s_nop 0
	v_pk_mul_f32 v[22:23], v[22:23], v[26:27]
	s_nop 0
	v_pk_mul_f32 v[18:19], v[22:23], v[18:19]
	s_nop 0
	v_cvt_pk_bf16_f32 v18, v18, v19
	v_mul_f32_e32 v19, 0xbfb8aa3b, v24
	v_exp_f32_e32 v19, v19
	s_nop 0
	v_add_f32_e32 v19, 1.0, v19
	v_rcp_f32_e32 v22, v19
	v_mul_f32_e32 v19, 0xbfb8aa3b, v25
	v_exp_f32_e32 v19, v19
	s_nop 0
	v_add_f32_e32 v19, 1.0, v19
	v_rcp_f32_e32 v23, v19
	s_nop 0
	v_pk_mul_f32 v[22:23], v[24:25], v[22:23]
	s_nop 0
	v_pk_mul_f32 v[20:21], v[22:23], v[20:21]
	s_nop 0
	v_cvt_pk_bf16_f32 v19, v20, v21
	global_store_dwordx2 v[28:29], v[18:19], off offset:32
	v_mul_f32_e32 v18, 0xbfb8aa3b, v14
	v_mul_f32_e32 v19, 0xbfb8aa3b, v15
	v_exp_f32_e32 v18, v18
	v_exp_f32_e32 v19, v19
	v_add_u32_e32 v20, 0xb0, v148
	v_add_f32_e32 v18, 1.0, v18
	v_add_f32_e32 v19, 1.0, v19
	v_rcp_f32_e32 v18, v18
	v_rcp_f32_e32 v19, v19
	s_nop 0
	v_pk_mul_f32 v[14:15], v[14:15], v[18:19]
	s_nop 0
	v_pk_mul_f32 v[10:11], v[14:15], v[10:11]
	s_nop 0
	v_cvt_pk_bf16_f32 v10, v10, v11
	v_mul_f32_e32 v11, 0xbfb8aa3b, v16
	v_exp_f32_e32 v11, v11
	s_nop 0
	v_add_f32_e32 v11, 1.0, v11
	v_rcp_f32_e32 v14, v11
	v_mul_f32_e32 v11, 0xbfb8aa3b, v17
	v_exp_f32_e32 v11, v11
	s_nop 0
	v_add_f32_e32 v11, 1.0, v11
	v_rcp_f32_e32 v15, v11
	s_nop 0
	v_pk_mul_f32 v[14:15], v[16:17], v[14:15]
	s_nop 0
	v_pk_mul_f32 v[12:13], v[14:15], v[12:13]
	s_nop 0
	v_cvt_pk_bf16_f32 v11, v12, v13
	v_mad_i64_i32 v[12:13], s[8:9], v20, s7, v[122:123]
	v_lshl_add_u64 v[12:13], v[12:13], 0, v[124:125]
	global_store_dwordx2 v[12:13], v[10:11], off
	v_mul_f32_e32 v10, 0xbfb8aa3b, v6
	v_mul_f32_e32 v11, 0xbfb8aa3b, v7
	v_exp_f32_e32 v10, v10
	v_exp_f32_e32 v11, v11
	v_add_f32_e32 v10, 1.0, v10
	v_add_f32_e32 v11, 1.0, v11
	v_rcp_f32_e32 v10, v10
	v_rcp_f32_e32 v11, v11
	s_nop 0
	v_pk_mul_f32 v[6:7], v[6:7], v[10:11]
	s_nop 0
	v_pk_mul_f32 v[2:3], v[6:7], v[2:3]
	s_nop 0
	v_cvt_pk_bf16_f32 v2, v2, v3
	v_mul_f32_e32 v3, 0xbfb8aa3b, v8
	v_exp_f32_e32 v3, v3
	s_nop 0
	v_add_f32_e32 v3, 1.0, v3
	v_rcp_f32_e32 v6, v3
	v_mul_f32_e32 v3, 0xbfb8aa3b, v9
	v_exp_f32_e32 v3, v3
	s_nop 0
	v_add_f32_e32 v3, 1.0, v3
	v_rcp_f32_e32 v7, v3
	s_nop 0
	v_pk_mul_f32 v[6:7], v[8:9], v[6:7]
	s_nop 0
	v_pk_mul_f32 v[4:5], v[6:7], v[4:5]
	s_nop 0
	v_cvt_pk_bf16_f32 v3, v4, v5
	global_store_dwordx2 v[12:13], v[2:3], off offset:32
	s_and_b64 vcc, exec, s[0:1]
	s_mov_b32 s8, s5
	s_mov_b32 s9, s6
	s_mov_b32 s7, s4
	s_cbranch_vccz .LBB0_43
	s_waitcnt vmcnt(0)
	s_movk_i32 s0, 0x100
	v_cmp_gt_u32_e32 vcc, s0, v239
	s_and_saveexec_b64 s[0:1], vcc
	s_cbranch_execz .LBB0_50
	s_barrier

; #define WAIT_V(n) asm volatile("s_waitcnt vmcnt(" #n ")" ::: "memory")
; #define BAR __builtin_amdgcn_s_barrier()
; template <class EPI>
; DI void gemm_stream(const u16* __restrict__ A, const u16* __restrict__ Bt, const int K, const int nM, const int nN,
;                     const int bid, const int nb, const int tid, EPI epi) {
;     ...
;   unsigned so0, so1;
;   { int r0, c0; stage_rc(tid * 16, r0, c0); so0 = (unsigned)((r0 * K + c0) * 2); so1 = so0 + (unsigned)(64 * K * 2); }
;   const int lanepart = lds_byte(fr, fq * 8);
;   const int aoff = wr * 8192 + lanepart, boff = wc * 4096 + lanepart;
;   const int nt = K / BK;
;   int pm, pn; gemm_tile_coords(bid, nM, nN, pm, pn);
;   int brow = pm * BM, bcol = pn * BM;
;   GemmAcc acc = {};
;   STAGE(SB(0, 0), Bt, bcol, 0); STAGE(SA(0, 0), A, brow, 0);
;   STAGE(SB(0, 1), Bt, bcol + HALF, 0); STAGE(SA(0, 1), A, brow + HALF, 0);
;   if (wr == 1) BAR;
;   WAIT_V(4); BAR;
;   STAGE(SB(1, 0), Bt, bcol, 1); STAGE(SA(1, 0), A, brow, 1); STAGE(SB(1, 1), Bt, bcol + HALF, 1);
;   WAIT_V(6); BAR;
.LBB0_128:
	s_or_b64 exec, exec, s[0:1]
	v_add_u32_e32 v159, 0x18000, v0
	s_or_b32 s0, s4, 0x80
	v_readfirstlane_b32 s1, v159
	v_add_u32_e32 v7, s0, v150
	s_mov_b32 m0, s1
	v_add_u32_e32 v160, 0x1a000, v0
	s_waitcnt vmcnt(2)
	s_barrier
	global_load_lds_dwordx4 v7, s[88:89]
	v_add_u32_e32 v7, s0, v151
	v_readfirstlane_b32 s0, v160
	v_add_u32_e32 v161, 0x8000, v0
	s_mov_b32 m0, s0
	s_bitset1_b32 s5, 7
	v_readfirstlane_b32 s0, v161
	v_add_u32_e32 v162, 0xa000, v0
	global_load_lds_dwordx4 v7, s[88:89]
	v_add_u32_e32 v7, s5, v150
	s_mov_b32 m0, s0
	v_readfirstlane_b32 s0, v162
	v_add_u32_e32 v163, 0x1c000, v0
	global_load_lds_dwordx4 v7, s[86:87]
	v_add_u32_e32 v7, s5, v151
	s_mov_b32 m0, s0
	s_or_b32 s0, s4, 0x80080
	v_readfirstlane_b32 s1, v163
	global_load_lds_dwordx4 v7, s[86:87]
	v_add_u32_e32 v7, s0, v150
	s_mov_b32 m0, s1
	v_add_u32_e32 v165, 0x1e000, v0
	global_load_lds_dwordx4 v7, s[88:89]
	v_add_u32_e32 v7, s0, v151
	v_readfirstlane_b32 s0, v165
	s_mov_b32 m0, s0
	v_and_b32_e32 v8, 48, v239
	global_load_lds_dwordx4 v7, s[88:89]
	v_and_b32_e32 v7, 15, v239
	v_lshlrev_b32_e32 v7, 6, v7
	v_lshlrev_b32_e32 v10, 2, v239
	v_or_b32_e32 v9, v7, v8
	v_and_b32_e32 v10, 32, v10
	v_lshlrev_b32_e32 v2, 13, v2
	v_bitop3_b32 v7, v7, v10, v8 bitop3:0x36
	v_bitop3_b32 v166, v9, v2, v10 bitop3:0xde
	v_lshlrev_b32_e32 v2, 6, v239
	s_movk_i32 s0, 0x3000
	v_and_or_b32 v167, v2, s0, v7
	v_lshlrev_b32_e32 v2, 14, v3
	v_and_b32_e32 v2, 0x7fff8000, v2
	v_lshl_add_u32 v2, v4, 11, v2
	s_waitcnt vmcnt(6)
	v_or_b32_e32 v2, v2, v5
	v_add_u32_e32 v2, v2, v6
	v_mov_b32_e32 v3, 0xc0080
	s_lshl_b32 s8, s3, 8
	s_lshl_b32 s7, s2, 8
	v_lshl_add_u32 v168, v2, 1, v3
	s_mov_b32 s4, s45
	s_barrier

.LBB0_132:
	v_or_b32_e32 v131, 0x10000, v167
	v_add_u32_e32 v136, 0x10400, v167
	v_add_u32_e32 v140, 0x10800, v167
	v_add_u32_e32 v144, 0x10c00, v167
	s_add_i32 s11, s10, 2
	ds_read_b128 v[132:135], v131
	ds_read_b128 v[136:139], v136
	ds_read_b128 v[140:143], v140
	ds_read_b128 v[144:147], v144
	s_cmp_lt_u32 s10, 30
	s_cselect_b32 s12, s8, s5
	s_cselect_b32 s13, s7, s6
	s_cselect_b32 s14, s9, 0
	s_lshl_b32 s13, s13, 11
	s_lshl_b32 s12, s12, 11
	s_or_b32 s15, s14, 64
	s_add_i32 s17, s12, s14
	s_or_b32 s18, s13, 0x40000
	s_add_i32 s16, s13, s14
	s_add_i32 s13, s15, s13
	s_add_i32 s12, s15, s12
	s_lshl_b32 s17, s17, 1
	s_add_i32 s19, s18, s14
	s_add_i32 s18, s18, s15
	s_addk_i32 s9, 0x80
	s_lshl_b32 s16, s16, 1
	s_lshl_b32 s14, s13, 1
	s_lshl_b32 s13, s12, 1
	s_lshl_b32 s15, s19, 1
	s_add_i32 s19, s17, 0x80000
	s_lshl_b32 s12, s18, 1
	s_cmp_gt_u32 s10, 29
	v_add_u32_e32 v148, 0xc000, v0
	v_add_u32_e32 v131, 0xfffc0000, v130
	v_readfirstlane_b32 s10, v148
	s_mov_b32 m0, s10
	ds_read_b128 v[170:173], v166
	ds_read_b128 v[174:177], v166 offset:1024
	ds_read_b128 v[180:183], v166 offset:2048
	ds_read_b128 v[184:187], v166 offset:3072
	ds_read_b128 v[188:191], v166 offset:4096
	ds_read_b128 v[192:195], v166 offset:5120
	ds_read_b128 v[196:199], v166 offset:6144
	ds_read_b128 v[200:203], v166 offset:7168
	global_load_lds_dwordx4 v131, s[86:87]
	v_add_u32_e32 v131, 0xe000, v0
	s_nop 0
	v_readfirstlane_b32 s10, v131
	s_mov_b32 m0, s10
	s_nop 0
	global_load_lds_dwordx4 v130, s[86:87]
	s_waitcnt lgkmcnt(8)
	v_or_b32_e32 v131, 0x14000, v167
	v_add_u32_e32 v148, 0x14400, v167
	ds_read_b128 v[204:207], v131
	ds_read_b128 v[208:211], v148
	v_add_u32_e32 v131, 0x14800, v167
	v_add_u32_e32 v148, 0x14c00, v167
	ds_read_b128 v[212:215], v131
	ds_read_b128 v[216:219], v148
	s_waitcnt vmcnt(8)
	s_waitcnt lgkmcnt(0)
	s_barrier
	s_setprio 1
	v_mfma_f32_16x16x32_bf16 v[98:101], v[132:135], v[170:173], v[98:101]
	v_mfma_f32_16x16x32_bf16 v[102:105], v[140:143], v[170:173], v[102:105]
	v_mfma_f32_16x16x32_bf16 v[126:129], v[132:135], v[180:183], v[126:129]
	v_mfma_f32_16x16x32_bf16 v[122:125], v[140:143], v[180:183], v[122:125]
	v_mfma_f32_16x16x32_bf16 v[118:121], v[132:135], v[188:191], v[118:121]
	v_mfma_f32_16x16x32_bf16 v[114:117], v[140:143], v[188:191], v[114:117]
	v_mfma_f32_16x16x32_bf16 v[110:113], v[132:135], v[196:199], v[110:113]
	v_mfma_f32_16x16x32_bf16 v[106:109], v[140:143], v[196:199], v[106:109]
	v_mfma_f32_16x16x32_bf16 v[98:101], v[136:139], v[174:177], v[98:101]
	v_mfma_f32_16x16x32_bf16 v[102:105], v[144:147], v[174:177], v[102:105]
	v_mfma_f32_16x16x32_bf16 v[126:129], v[136:139], v[184:187], v[126:129]
	v_mfma_f32_16x16x32_bf16 v[122:125], v[144:147], v[184:187], v[122:125]
	v_mfma_f32_16x16x32_bf16 v[118:121], v[136:139], v[192:195], v[118:121]
	v_mfma_f32_16x16x32_bf16 v[114:117], v[144:147], v[192:195], v[114:117]
	v_mfma_f32_16x16x32_bf16 v[110:113], v[136:139], v[200:203], v[110:113]
	v_mfma_f32_16x16x32_bf16 v[106:109], v[144:147], v[200:203], v[106:109]
	v_mfma_f32_16x16x32_bf16 v[66:69], v[204:207], v[170:173], v[66:69]
	v_mfma_f32_16x16x32_bf16 v[70:73], v[212:215], v[170:173], v[70:73]
	v_mfma_f32_16x16x32_bf16 v[74:77], v[204:207], v[180:183], v[74:77]
	v_mfma_f32_16x16x32_bf16 v[78:81], v[212:215], v[180:183], v[78:81]
	v_mfma_f32_16x16x32_bf16 v[82:85], v[204:207], v[188:191], v[82:85]
	v_mfma_f32_16x16x32_bf16 v[86:89], v[212:215], v[188:191], v[86:89]
	v_mfma_f32_16x16x32_bf16 v[90:93], v[204:207], v[196:199], v[90:93]
	v_mfma_f32_16x16x32_bf16 v[94:97], v[212:215], v[196:199], v[94:97]
	v_mfma_f32_16x16x32_bf16 v[66:69], v[208:211], v[174:177], v[66:69]
	v_mfma_f32_16x16x32_bf16 v[70:73], v[216:219], v[174:177], v[70:73]
	v_mfma_f32_16x16x32_bf16 v[74:77], v[208:211], v[184:187], v[74:77]
	v_mfma_f32_16x16x32_bf16 v[78:81], v[216:219], v[184:187], v[78:81]
	v_mfma_f32_16x16x32_bf16 v[82:85], v[208:211], v[192:195], v[82:85]
	v_mfma_f32_16x16x32_bf16 v[86:89], v[216:219], v[192:195], v[86:89]
	v_mfma_f32_16x16x32_bf16 v[90:93], v[208:211], v[200:203], v[90:93]
	v_mfma_f32_16x16x32_bf16 v[94:97], v[216:219], v[200:203], v[94:97]
	s_setprio 0
	s_barrier
	v_readfirstlane_b32 s10, v152
	v_add_u32_e32 v131, s16, v150
	s_mov_b32 m0, s10
	v_readfirstlane_b32 s10, v153
	global_load_lds_dwordx4 v131, s[88:89]
	v_add_u32_e32 v131, s16, v151
	s_mov_b32 m0, s10
	s_nop 0
	global_load_lds_dwordx4 v131, s[88:89]
	v_readfirstlane_b32 s10, v0
	v_add_u32_e32 v131, s17, v150
	s_mov_b32 m0, s10
	v_readfirstlane_b32 s10, v154
	ds_read_b128 v[170:173], v166 offset:16384
	ds_read_b128 v[174:177], v166 offset:17408
	ds_read_b128 v[180:183], v166 offset:18432
	ds_read_b128 v[184:187], v166 offset:19456
	ds_read_b128 v[188:191], v166 offset:20480
	ds_read_b128 v[192:195], v166 offset:21504
	ds_read_b128 v[196:199], v166 offset:22528
	ds_read_b128 v[200:203], v166 offset:23552
	global_load_lds_dwordx4 v131, s[86:87]
	v_add_u32_e32 v131, s17, v151
	s_mov_b32 m0, s10
	s_nop 0
	global_load_lds_dwordx4 v131, s[86:87]
	v_readfirstlane_b32 s10, v155
	v_add_u32_e32 v131, s15, v150
	s_mov_b32 m0, s10
	v_readfirstlane_b32 s10, v156
	global_load_lds_dwordx4 v131, s[88:89]
	v_add_u32_e32 v131, s15, v151
	s_mov_b32 m0, s10
	s_nop 0
	global_load_lds_dwordx4 v131, s[88:89]
	s_waitcnt vmcnt(8)
	s_waitcnt lgkmcnt(0)
	s_barrier
	s_setprio 1
	v_mfma_f32_16x16x32_bf16 v[34:37], v[132:135], v[170:173], v[34:37]
	v_mfma_f32_16x16x32_bf16 v[38:41], v[140:143], v[170:173], v[38:41]
	v_mfma_f32_16x16x32_bf16 v[42:45], v[132:135], v[180:183], v[42:45]
	v_mfma_f32_16x16x32_bf16 v[46:49], v[140:143], v[180:183], v[46:49]
	v_mfma_f32_16x16x32_bf16 v[50:53], v[132:135], v[188:191], v[50:53]
	v_mfma_f32_16x16x32_bf16 v[54:57], v[140:143], v[188:191], v[54:57]
	v_mfma_f32_16x16x32_bf16 v[58:61], v[132:135], v[196:199], v[58:61]
	v_mfma_f32_16x16x32_bf16 v[62:65], v[140:143], v[196:199], v[62:65]
	v_mfma_f32_16x16x32_bf16 v[34:37], v[136:139], v[174:177], v[34:37]
	v_mfma_f32_16x16x32_bf16 v[38:41], v[144:147], v[174:177], v[38:41]
	v_mfma_f32_16x16x32_bf16 v[42:45], v[136:139], v[184:187], v[42:45]
	v_mfma_f32_16x16x32_bf16 v[46:49], v[144:147], v[184:187], v[46:49]
	v_mfma_f32_16x16x32_bf16 v[50:53], v[136:139], v[192:195], v[50:53]
	v_mfma_f32_16x16x32_bf16 v[54:57], v[144:147], v[192:195], v[54:57]
	v_mfma_f32_16x16x32_bf16 v[58:61], v[136:139], v[200:203], v[58:61]
	v_mfma_f32_16x16x32_bf16 v[62:65], v[144:147], v[200:203], v[62:65]
	v_mfma_f32_16x16x32_bf16 v[2:5], v[204:207], v[170:173], v[2:5]
	v_mfma_f32_16x16x32_bf16 v[6:9], v[212:215], v[170:173], v[6:9]
	v_mfma_f32_16x16x32_bf16 v[10:13], v[204:207], v[180:183], v[10:13]
	v_mfma_f32_16x16x32_bf16 v[14:17], v[212:215], v[180:183], v[14:17]
	v_mfma_f32_16x16x32_bf16 v[18:21], v[204:207], v[188:191], v[18:21]
	v_mfma_f32_16x16x32_bf16 v[22:25], v[212:215], v[188:191], v[22:25]
	v_mfma_f32_16x16x32_bf16 v[26:29], v[204:207], v[196:199], v[26:29]
	v_mfma_f32_16x16x32_bf16 v[30:33], v[212:215], v[196:199], v[30:33]
	v_mfma_f32_16x16x32_bf16 v[2:5], v[208:211], v[174:177], v[2:5]
	v_mfma_f32_16x16x32_bf16 v[6:9], v[216:219], v[174:177], v[6:9]
	v_mfma_f32_16x16x32_bf16 v[10:13], v[208:211], v[184:187], v[10:13]
	v_mfma_f32_16x16x32_bf16 v[14:17], v[216:219], v[184:187], v[14:17]
	v_mfma_f32_16x16x32_bf16 v[18:21], v[208:211], v[192:195], v[18:21]
	v_mfma_f32_16x16x32_bf16 v[22:25], v[216:219], v[192:195], v[22:25]
	v_mfma_f32_16x16x32_bf16 v[26:29], v[208:211], v[200:203], v[26:29]
	v_mfma_f32_16x16x32_bf16 v[30:33], v[216:219], v[200:203], v[30:33]
	s_setprio 0
	s_barrier
	v_or_b32_e32 v131, 0x18000, v167
	v_add_u32_e32 v136, 0x18400, v167
	ds_read_b128 v[132:135], v131
	ds_read_b128 v[136:139], v136
	v_add_u32_e32 v131, 0x18800, v167
	v_add_u32_e32 v144, 0x18c00, v167
	ds_read_b128 v[140:143], v131
	ds_read_b128 v[144:147], v144
	v_readfirstlane_b32 s10, v157
	v_add_u32_e32 v131, s19, v150
	s_mov_b32 m0, s10
	v_readfirstlane_b32 s10, v158
	ds_read_b128 v[170:173], v166 offset:32768
	ds_read_b128 v[174:177], v166 offset:33792
	ds_read_b128 v[180:183], v166 offset:34816
	ds_read_b128 v[184:187], v166 offset:35840
	ds_read_b128 v[188:191], v166 offset:36864
	ds_read_b128 v[192:195], v166 offset:37888
	ds_read_b128 v[196:199], v166 offset:38912
	ds_read_b128 v[200:203], v166 offset:39936
	global_load_lds_dwordx4 v131, s[86:87]
	v_add_u32_e32 v131, s19, v151
	s_mov_b32 m0, s10
	s_nop 0
	global_load_lds_dwordx4 v131, s[86:87]
	s_waitcnt lgkmcnt(8)
	v_or_b32_e32 v131, 0x1c000, v167
	v_add_u32_e32 v148, 0x1c400, v167
	ds_read_b128 v[204:207], v131
	ds_read_b128 v[208:211], v148
	v_add_u32_e32 v131, 0x1c800, v167
	v_add_u32_e32 v148, 0x1cc00, v167
	ds_read_b128 v[212:215], v131
	ds_read_b128 v[216:219], v148
	s_waitcnt vmcnt(8)
	s_waitcnt lgkmcnt(0)
	s_barrier
	s_setprio 1
	v_mfma_f32_16x16x32_bf16 v[98:101], v[132:135], v[170:173], v[98:101]
	v_mfma_f32_16x16x32_bf16 v[102:105], v[140:143], v[170:173], v[102:105]
	v_mfma_f32_16x16x32_bf16 v[126:129], v[132:135], v[180:183], v[126:129]
	v_mfma_f32_16x16x32_bf16 v[122:125], v[140:143], v[180:183], v[122:125]
	v_mfma_f32_16x16x32_bf16 v[118:121], v[132:135], v[188:191], v[118:121]
	v_mfma_f32_16x16x32_bf16 v[114:117], v[140:143], v[188:191], v[114:117]
	v_mfma_f32_16x16x32_bf16 v[110:113], v[132:135], v[196:199], v[110:113]
	v_mfma_f32_16x16x32_bf16 v[106:109], v[140:143], v[196:199], v[106:109]
	v_mfma_f32_16x16x32_bf16 v[98:101], v[136:139], v[174:177], v[98:101]
	v_mfma_f32_16x16x32_bf16 v[102:105], v[144:147], v[174:177], v[102:105]
	v_mfma_f32_16x16x32_bf16 v[126:129], v[136:139], v[184:187], v[126:129]
	v_mfma_f32_16x16x32_bf16 v[122:125], v[144:147], v[184:187], v[122:125]
	v_mfma_f32_16x16x32_bf16 v[118:121], v[136:139], v[192:195], v[118:121]
	v_mfma_f32_16x16x32_bf16 v[114:117], v[144:147], v[192:195], v[114:117]
	v_mfma_f32_16x16x32_bf16 v[110:113], v[136:139], v[200:203], v[110:113]
	v_mfma_f32_16x16x32_bf16 v[106:109], v[144:147], v[200:203], v[106:109]
	v_mfma_f32_16x16x32_bf16 v[66:69], v[204:207], v[170:173], v[66:69]
	v_mfma_f32_16x16x32_bf16 v[70:73], v[212:215], v[170:173], v[70:73]
	v_mfma_f32_16x16x32_bf16 v[74:77], v[204:207], v[180:183], v[74:77]
	v_mfma_f32_16x16x32_bf16 v[78:81], v[212:215], v[180:183], v[78:81]
	v_mfma_f32_16x16x32_bf16 v[82:85], v[204:207], v[188:191], v[82:85]
	v_mfma_f32_16x16x32_bf16 v[86:89], v[212:215], v[188:191], v[86:89]
	v_mfma_f32_16x16x32_bf16 v[90:93], v[204:207], v[196:199], v[90:93]
	v_mfma_f32_16x16x32_bf16 v[94:97], v[212:215], v[196:199], v[94:97]
	v_mfma_f32_16x16x32_bf16 v[66:69], v[208:211], v[174:177], v[66:69]
	v_mfma_f32_16x16x32_bf16 v[70:73], v[216:219], v[174:177], v[70:73]
	v_mfma_f32_16x16x32_bf16 v[74:77], v[208:211], v[184:187], v[74:77]
	v_mfma_f32_16x16x32_bf16 v[78:81], v[216:219], v[184:187], v[78:81]
	v_mfma_f32_16x16x32_bf16 v[82:85], v[208:211], v[192:195], v[82:85]
	v_mfma_f32_16x16x32_bf16 v[86:89], v[216:219], v[192:195], v[86:89]
	v_mfma_f32_16x16x32_bf16 v[90:93], v[208:211], v[200:203], v[90:93]
	v_mfma_f32_16x16x32_bf16 v[94:97], v[216:219], v[200:203], v[94:97]
	s_setprio 0
	s_barrier
; DI void gemm_resid(const u16* A, const u16* Bt, int K, const float* xin, float* xout, int bid, int nb, int tid) {
;     ...
;     for (int ai = 0; ai < 2; ++ai)
; #pragma unroll
;       for (int bj = 0; bj < 2; ++bj) {
;         float4 xi[4][2];
; #pragma unroll
;         for (int m = 0; m < 4; ++m)
; #pragma unroll
;           for (int n = 0; n < 2; ++n) xi[m][n] = *reinterpret_cast<const float4*>(xin + (size_t)ACC_ROW * 2048 + ACC_COL);
	v_readfirstlane_b32 s10, v159
	v_add_u32_e32 v131, s14, v150
	s_mov_b32 m0, s10
	v_readfirstlane_b32 s10, v160
	global_load_lds_dwordx4 v131, s[88:89]
	v_add_u32_e32 v131, s14, v151
	s_mov_b32 m0, s10
	s_nop 0
	global_load_lds_dwordx4 v131, s[88:89]
	v_readfirstlane_b32 s10, v161
	v_add_u32_e32 v131, s13, v150
	s_mov_b32 m0, s10
	v_readfirstlane_b32 s10, v162
	ds_read_b128 v[170:173], v166 offset:49152
	ds_read_b128 v[174:177], v166 offset:50176
	ds_read_b128 v[180:183], v166 offset:51200
	ds_read_b128 v[184:187], v166 offset:52224
	ds_read_b128 v[188:191], v166 offset:53248
	ds_read_b128 v[192:195], v166 offset:54272
	ds_read_b128 v[196:199], v166 offset:55296
	ds_read_b128 v[200:203], v166 offset:56320
	global_load_lds_dwordx4 v131, s[86:87]
	v_add_u32_e32 v131, s13, v151
	s_mov_b32 m0, s10
	s_nop 0
	global_load_lds_dwordx4 v131, s[86:87]
	v_readfirstlane_b32 s10, v163
	v_add_u32_e32 v131, s12, v150
	s_mov_b32 m0, s10
	v_readfirstlane_b32 s10, v165
	global_load_lds_dwordx4 v131, s[88:89]
	v_add_u32_e32 v131, s12, v151
	s_mov_b32 m0, s10
	s_nop 0
	global_load_lds_dwordx4 v131, s[88:89]
	s_waitcnt vmcnt(8)
	s_waitcnt lgkmcnt(0)
	s_barrier
	s_setprio 1
	v_mfma_f32_16x16x32_bf16 v[34:37], v[132:135], v[170:173], v[34:37]
	v_mfma_f32_16x16x32_bf16 v[38:41], v[140:143], v[170:173], v[38:41]
	v_mfma_f32_16x16x32_bf16 v[42:45], v[132:135], v[180:183], v[42:45]
	v_mfma_f32_16x16x32_bf16 v[46:49], v[140:143], v[180:183], v[46:49]
	v_mfma_f32_16x16x32_bf16 v[50:53], v[132:135], v[188:191], v[50:53]
	v_mfma_f32_16x16x32_bf16 v[54:57], v[140:143], v[188:191], v[54:57]
	v_mfma_f32_16x16x32_bf16 v[58:61], v[132:135], v[196:199], v[58:61]
	v_mfma_f32_16x16x32_bf16 v[62:65], v[140:143], v[196:199], v[62:65]
	v_mfma_f32_16x16x32_bf16 v[34:37], v[136:139], v[174:177], v[34:37]
	v_mfma_f32_16x16x32_bf16 v[38:41], v[144:147], v[174:177], v[38:41]
	v_mfma_f32_16x16x32_bf16 v[42:45], v[136:139], v[184:187], v[42:45]
	v_mfma_f32_16x16x32_bf16 v[46:49], v[144:147], v[184:187], v[46:49]
	v_mfma_f32_16x16x32_bf16 v[50:53], v[136:139], v[192:195], v[50:53]
	v_mfma_f32_16x16x32_bf16 v[54:57], v[144:147], v[192:195], v[54:57]
	v_mfma_f32_16x16x32_bf16 v[58:61], v[136:139], v[200:203], v[58:61]
	v_mfma_f32_16x16x32_bf16 v[62:65], v[144:147], v[200:203], v[62:65]
	v_mfma_f32_16x16x32_bf16 v[2:5], v[204:207], v[170:173], v[2:5]
	v_mfma_f32_16x16x32_bf16 v[6:9], v[212:215], v[170:173], v[6:9]
	v_mfma_f32_16x16x32_bf16 v[10:13], v[204:207], v[180:183], v[10:13]
	v_mfma_f32_16x16x32_bf16 v[14:17], v[212:215], v[180:183], v[14:17]
	v_mfma_f32_16x16x32_bf16 v[18:21], v[204:207], v[188:191], v[18:21]
	v_mfma_f32_16x16x32_bf16 v[22:25], v[212:215], v[188:191], v[22:25]
	v_mfma_f32_16x16x32_bf16 v[26:29], v[204:207], v[196:199], v[26:29]
	v_mfma_f32_16x16x32_bf16 v[30:33], v[212:215], v[196:199], v[30:33]
	v_mfma_f32_16x16x32_bf16 v[2:5], v[208:211], v[174:177], v[2:5]
	v_mfma_f32_16x16x32_bf16 v[6:9], v[216:219], v[174:177], v[6:9]
	v_mfma_f32_16x16x32_bf16 v[10:13], v[208:211], v[184:187], v[10:13]
	v_mfma_f32_16x16x32_bf16 v[14:17], v[216:219], v[184:187], v[14:17]
	v_mfma_f32_16x16x32_bf16 v[18:21], v[208:211], v[192:195], v[18:21]
	v_mfma_f32_16x16x32_bf16 v[22:25], v[216:219], v[192:195], v[22:25]
	v_mfma_f32_16x16x32_bf16 v[26:29], v[208:211], v[200:203], v[26:29]
	v_mfma_f32_16x16x32_bf16 v[30:33], v[216:219], v[200:203], v[30:33]
	s_setprio 0
	v_add_u32_e32 v130, 0x100, v130
	s_mov_b32 s10, s11
	s_barrier
	s_cbranch_scc0 .LBB0_132
	v_mov_b32_e32 v131, v239
	s_nop 0
	v_ashrrev_i32_e32 v130, 2, v131
	v_and_b32_e32 v130, 0xffffffc0, v130
	v_and_or_b32 v132, v131, 15, s8
	v_add_u32_e32 v130, v132, v130
	v_lshrrev_b32_e32 v132, 1, v131
	v_lshrrev_b32_e32 v131, 2, v131
	v_and_b32_e32 v132, 0x60, v132
	v_and_b32_e32 v131, 12, v131
	v_or3_b32 v132, v132, v131, s7
	v_ashrrev_i32_e32 v131, 31, v130
	v_ashrrev_i32_e32 v133, 31, v132
	v_lshlrev_b64 v[134:135], 13, v[130:131]
	v_lshl_add_u64 v[136:137], s[48:49], 0, v[134:135]
	v_lshlrev_b64 v[132:133], 2, v[132:133]
	v_lshl_add_u64 v[142:143], v[136:137], 0, v[132:133]
	v_or_b32_e32 v136, 16, v130
	v_ashrrev_i32_e32 v137, 31, v136
	v_lshlrev_b64 v[136:137], 13, v[136:137]
	v_lshl_add_u64 v[138:139], s[48:49], 0, v[136:137]
	v_lshl_add_u64 v[144:145], v[138:139], 0, v[132:133]
	v_or_b32_e32 v138, 32, v130
	v_ashrrev_i32_e32 v139, 31, v138
	v_lshlrev_b64 v[170:171], 13, v[138:139]
	v_lshl_add_u64 v[138:139], s[48:49], 0, v[170:171]
	v_lshl_add_u64 v[146:147], v[138:139], 0, v[132:133]
	v_or_b32_e32 v138, 48, v130
	v_ashrrev_i32_e32 v139, 31, v138
	v_lshlrev_b64 v[172:173], 13, v[138:139]
	v_lshl_add_u64 v[134:135], s[72:73], 0, v[134:135]
	v_lshl_add_u64 v[138:139], s[48:49], 0, v[172:173]
	v_lshl_add_u64 v[140:141], v[134:135], 0, v[132:133]
	v_lshl_add_u64 v[134:135], s[72:73], 0, v[136:137]
	v_lshl_add_u64 v[148:149], v[138:139], 0, v[132:133]
	v_lshl_add_u64 v[138:139], v[134:135], 0, v[132:133]
	v_lshl_add_u64 v[134:135], s[72:73], 0, v[170:171]
	v_lshl_add_u64 v[136:137], v[134:135], 0, v[132:133]
	v_lshl_add_u64 v[134:135], s[72:73], 0, v[172:173]
	v_lshl_add_u64 v[134:135], v[134:135], 0, v[132:133]
	global_load_dwordx4 v[180:183], v[148:149], off offset:64
	global_load_dwordx4 v[184:187], v[148:149], off
	global_load_dwordx4 v[188:191], v[146:147], off offset:64
	global_load_dwordx4 v[192:195], v[146:147], off
	global_load_dwordx4 v[196:199], v[144:145], off offset:64
	global_load_dwordx4 v[200:203], v[144:145], off
	global_load_dwordx4 v[204:207], v[142:143], off offset:64
	global_load_dwordx4 v[208:211], v[142:143], off
	s_waitcnt vmcnt(0)
; DI void gemm_resid(const u16* A, const u16* Bt, int K, const float* xin, float* xout, int bid, int nb, int tid) {
;     ...
;     for (int ai = 0; ai < 2; ++ai)
; #pragma unroll
;       for (int bj = 0; bj < 2; ++bj) {
;         float4 xi[4][2];
; #pragma unroll
;         for (int m = 0; m < 4; ++m)
; #pragma unroll
;           for (int n = 0; n < 2; ++n) xi[m][n] = *reinterpret_cast<const float4*>(xin + (size_t)ACC_ROW * 2048 + ACC_COL);
; #pragma unroll
;         for (int m = 0; m < 4; ++m)
; #pragma unroll
;           for (int n = 0; n < 2; ++n) {
;             const f32x4 v = acc[ai][bj][m][n];
;             float4 r; r.x = xi[m][n].x + v[0]; r.y = xi[m][n].y + v[1]; r.z = xi[m][n].z + v[2]; r.w = xi[m][n].w + v[3];
;             *reinterpret_cast<float4*>(xout + (size_t)ACC_ROW * 2048 + ACC_COL) = r;
;           }
	v_pk_add_f32 v[106:107], v[106:107], v[180:181]
	v_pk_add_f32 v[108:109], v[108:109], v[182:183]
	v_pk_add_f32 v[110:111], v[110:111], v[184:185]
	v_pk_add_f32 v[112:113], v[112:113], v[186:187]
	v_pk_add_f32 v[114:115], v[114:115], v[188:189]
	v_pk_add_f32 v[116:117], v[116:117], v[190:191]
	v_pk_add_f32 v[118:119], v[118:119], v[192:193]
	v_pk_add_f32 v[120:121], v[120:121], v[194:195]
	v_pk_add_f32 v[122:123], v[122:123], v[196:197]
	v_pk_add_f32 v[124:125], v[124:125], v[198:199]
	v_pk_add_f32 v[126:127], v[126:127], v[200:201]
	v_pk_add_f32 v[128:129], v[128:129], v[202:203]
	v_pk_add_f32 v[102:103], v[102:103], v[204:205]
	v_pk_add_f32 v[104:105], v[104:105], v[206:207]
	v_pk_add_f32 v[98:99], v[98:99], v[208:209]
	v_pk_add_f32 v[100:101], v[100:101], v[210:211]
	global_store_dwordx4 v[140:141], v[98:101], off
	global_store_dwordx4 v[140:141], v[102:105], off offset:64
	global_store_dwordx4 v[138:139], v[126:129], off
	global_store_dwordx4 v[138:139], v[122:125], off offset:64
	global_store_dwordx4 v[136:137], v[118:121], off
	global_store_dwordx4 v[136:137], v[114:117], off offset:64
	global_store_dwordx4 v[134:135], v[110:113], off
	global_store_dwordx4 v[134:135], v[106:109], off offset:64
	global_load_dwordx4 v[180:183], v[148:149], off offset:576
	global_load_dwordx4 v[184:187], v[148:149], off offset:512
	global_load_dwordx4 v[188:191], v[146:147], off offset:576
	global_load_dwordx4 v[192:195], v[146:147], off offset:512
	global_load_dwordx4 v[196:199], v[144:145], off offset:576
	global_load_dwordx4 v[200:203], v[144:145], off offset:512
	global_load_dwordx4 v[204:207], v[142:143], off offset:576
	global_load_dwordx4 v[208:211], v[142:143], off offset:512
	s_waitcnt vmcnt(0)
	v_pk_add_f32 v[94:95], v[94:95], v[180:181]
	v_pk_add_f32 v[96:97], v[96:97], v[182:183]
	v_pk_add_f32 v[90:91], v[90:91], v[184:185]
	v_pk_add_f32 v[92:93], v[92:93], v[186:187]
	v_pk_add_f32 v[86:87], v[86:87], v[188:189]
	v_pk_add_f32 v[88:89], v[88:89], v[190:191]
	v_pk_add_f32 v[82:83], v[82:83], v[192:193]
	v_pk_add_f32 v[84:85], v[84:85], v[194:195]
	v_pk_add_f32 v[78:79], v[78:79], v[196:197]
	v_pk_add_f32 v[80:81], v[80:81], v[198:199]
	v_pk_add_f32 v[74:75], v[74:75], v[200:201]
	v_pk_add_f32 v[76:77], v[76:77], v[202:203]
	v_pk_add_f32 v[70:71], v[70:71], v[204:205]
	v_pk_add_f32 v[72:73], v[72:73], v[206:207]
	v_pk_add_f32 v[66:67], v[66:67], v[208:209]
	v_pk_add_f32 v[68:69], v[68:69], v[210:211]
	global_store_dwordx4 v[140:141], v[66:69], off offset:512
	global_store_dwordx4 v[140:141], v[70:73], off offset:576
	global_store_dwordx4 v[138:139], v[74:77], off offset:512
	global_store_dwordx4 v[138:139], v[78:81], off offset:576
	global_store_dwordx4 v[136:137], v[82:85], off offset:512
	global_store_dwordx4 v[136:137], v[86:89], off offset:576
	global_store_dwordx4 v[134:135], v[90:93], off offset:512
	global_store_dwordx4 v[134:135], v[94:97], off offset:576
	v_add_u32_e32 v66, 0x80, v130
	v_ashrrev_i32_e32 v67, 31, v66
	v_lshlrev_b64 v[66:67], 13, v[66:67]
	v_lshl_add_u64 v[68:69], s[48:49], 0, v[66:67]
	v_lshl_add_u64 v[74:75], v[68:69], 0, v[132:133]
	v_add_u32_e32 v68, 0x90, v130
	v_ashrrev_i32_e32 v69, 31, v68
	v_lshlrev_b64 v[68:69], 13, v[68:69]
	v_lshl_add_u64 v[70:71], s[48:49], 0, v[68:69]
	v_lshl_add_u64 v[76:77], v[70:71], 0, v[132:133]
	v_add_u32_e32 v70, 0xa0, v130
	v_ashrrev_i32_e32 v71, 31, v70
	v_lshlrev_b64 v[82:83], 13, v[70:71]
	v_lshl_add_u64 v[70:71], s[48:49], 0, v[82:83]
	v_lshl_add_u64 v[78:79], v[70:71], 0, v[132:133]
	v_add_u32_e32 v70, 0xb0, v130
	v_ashrrev_i32_e32 v71, 31, v70
	v_lshlrev_b64 v[84:85], 13, v[70:71]
	v_lshl_add_u64 v[66:67], s[72:73], 0, v[66:67]
	v_lshl_add_u64 v[70:71], s[48:49], 0, v[84:85]
	v_lshl_add_u64 v[72:73], v[66:67], 0, v[132:133]
	v_lshl_add_u64 v[66:67], s[72:73], 0, v[68:69]
	v_lshl_add_u64 v[80:81], v[70:71], 0, v[132:133]
	v_lshl_add_u64 v[70:71], v[66:67], 0, v[132:133]
	v_lshl_add_u64 v[66:67], s[72:73], 0, v[82:83]
	v_lshl_add_u64 v[68:69], v[66:67], 0, v[132:133]
	v_lshl_add_u64 v[66:67], s[72:73], 0, v[84:85]
	v_lshl_add_u64 v[66:67], v[66:67], 0, v[132:133]
	global_load_dwordx4 v[180:183], v[80:81], off offset:64
	global_load_dwordx4 v[184:187], v[80:81], off
	global_load_dwordx4 v[188:191], v[78:79], off offset:64
	global_load_dwordx4 v[192:195], v[78:79], off
	global_load_dwordx4 v[196:199], v[76:77], off offset:64
	global_load_dwordx4 v[200:203], v[76:77], off
	global_load_dwordx4 v[204:207], v[74:75], off offset:64
	global_load_dwordx4 v[208:211], v[74:75], off
	s_waitcnt vmcnt(0)
; #define WAIT_V(n) asm volatile("s_waitcnt vmcnt(" #n ")" ::: "memory")
; #define BAR __builtin_amdgcn_s_barrier()
; #define EPI_SCHED __builtin_amdgcn_sched_barrier(0)
; template <class EPI>
; DI void gemm_stream(const u16* __restrict__ A, const u16* __restrict__ Bt, const int K, const int nM, const int nN,
;                     const int bid, const int nb, const int tid, EPI epi) {
;     ...
;   WAIT_V(0);
;   if (wr == 0) BAR;
; DI void gemm_resid(const u16* A, const u16* Bt, int K, const float* xin, float* xout, int bid, int nb, int tid) {
;     ...
;     for (int ai = 0; ai < 2; ++ai)
; #pragma unroll
;       for (int bj = 0; bj < 2; ++bj) {
;         float4 xi[4][2];
; #pragma unroll
;         for (int m = 0; m < 4; ++m)
; #pragma unroll
;           for (int n = 0; n < 2; ++n) xi[m][n] = *reinterpret_cast<const float4*>(xin + (size_t)ACC_ROW * 2048 + ACC_COL);
; #pragma unroll
;         for (int m = 0; m < 4; ++m)
; #pragma unroll
;           for (int n = 0; n < 2; ++n) {
;             const f32x4 v = acc[ai][bj][m][n];
;             float4 r; r.x = xi[m][n].x + v[0]; r.y = xi[m][n].y + v[1]; r.z = xi[m][n].z + v[2]; r.w = xi[m][n].w + v[3];
;             *reinterpret_cast<float4*>(xout + (size_t)ACC_ROW * 2048 + ACC_COL) = r;
;           }
;         EPI_SCHED;
;       }
	v_pk_add_f32 v[62:63], v[62:63], v[180:181]
	v_pk_add_f32 v[64:65], v[64:65], v[182:183]
	v_pk_add_f32 v[58:59], v[58:59], v[184:185]
	v_pk_add_f32 v[60:61], v[60:61], v[186:187]
	v_pk_add_f32 v[54:55], v[54:55], v[188:189]
	v_pk_add_f32 v[56:57], v[56:57], v[190:191]
	v_pk_add_f32 v[50:51], v[50:51], v[192:193]
	v_pk_add_f32 v[52:53], v[52:53], v[194:195]
	v_pk_add_f32 v[46:47], v[46:47], v[196:197]
	v_pk_add_f32 v[48:49], v[48:49], v[198:199]
	v_pk_add_f32 v[42:43], v[42:43], v[200:201]
	v_pk_add_f32 v[44:45], v[44:45], v[202:203]
	v_pk_add_f32 v[38:39], v[38:39], v[204:205]
	v_pk_add_f32 v[40:41], v[40:41], v[206:207]
	v_pk_add_f32 v[34:35], v[34:35], v[208:209]
	v_pk_add_f32 v[36:37], v[36:37], v[210:211]
	global_store_dwordx4 v[72:73], v[34:37], off
	global_store_dwordx4 v[72:73], v[38:41], off offset:64
	global_store_dwordx4 v[70:71], v[42:45], off
	global_store_dwordx4 v[70:71], v[46:49], off offset:64
	global_store_dwordx4 v[68:69], v[50:53], off
	global_store_dwordx4 v[68:69], v[54:57], off offset:64
	global_store_dwordx4 v[66:67], v[58:61], off
	global_store_dwordx4 v[66:67], v[62:65], off offset:64
	global_load_dwordx4 v[180:183], v[80:81], off offset:576
	global_load_dwordx4 v[184:187], v[80:81], off offset:512
	global_load_dwordx4 v[188:191], v[78:79], off offset:576
	global_load_dwordx4 v[192:195], v[78:79], off offset:512
	global_load_dwordx4 v[196:199], v[76:77], off offset:576
	global_load_dwordx4 v[200:203], v[76:77], off offset:512
	global_load_dwordx4 v[204:207], v[74:75], off offset:576
	global_load_dwordx4 v[208:211], v[74:75], off offset:512
	s_waitcnt vmcnt(0)
	v_pk_add_f32 v[30:31], v[30:31], v[180:181]
	v_pk_add_f32 v[32:33], v[32:33], v[182:183]
	v_pk_add_f32 v[26:27], v[26:27], v[184:185]
	v_pk_add_f32 v[28:29], v[28:29], v[186:187]
	v_pk_add_f32 v[22:23], v[22:23], v[188:189]
	v_pk_add_f32 v[24:25], v[24:25], v[190:191]
	v_pk_add_f32 v[18:19], v[18:19], v[192:193]
	v_pk_add_f32 v[20:21], v[20:21], v[194:195]
	v_pk_add_f32 v[14:15], v[14:15], v[196:197]
	v_pk_add_f32 v[16:17], v[16:17], v[198:199]
	v_pk_add_f32 v[10:11], v[10:11], v[200:201]
	v_pk_add_f32 v[12:13], v[12:13], v[202:203]
	v_pk_add_f32 v[6:7], v[6:7], v[204:205]
	v_pk_add_f32 v[8:9], v[8:9], v[206:207]
	v_pk_add_f32 v[2:3], v[2:3], v[208:209]
	v_pk_add_f32 v[4:5], v[4:5], v[210:211]
	global_store_dwordx4 v[72:73], v[2:5], off offset:512
	global_store_dwordx4 v[72:73], v[6:9], off offset:576
	global_store_dwordx4 v[70:71], v[10:13], off offset:512
	global_store_dwordx4 v[70:71], v[14:17], off offset:576
	global_store_dwordx4 v[68:69], v[18:21], off offset:512
	global_store_dwordx4 v[68:69], v[22:25], off offset:576
	global_store_dwordx4 v[66:67], v[26:29], off offset:512
	global_store_dwordx4 v[66:67], v[30:33], off offset:576
	s_and_b64 vcc, exec, s[0:1]
	s_mov_b32 s8, s5
	s_mov_b32 s7, s6
	s_cbranch_vccz .LBB0_129
	s_waitcnt vmcnt(0)
	s_movk_i32 s0, 0x100
	v_cmp_gt_u32_e32 vcc, s0, v239
	s_and_saveexec_b64 s[0:1], vcc
	s_cbranch_execz .LBB0_136
	s_barrier

; #define MFMA32(a, b, c) __builtin_amdgcn_mfma_f32_32x32x16_bf16((a), (b), (c), 0, 0, 0)
; template <int C>
; DI void pv_block2(f32x16& oa, f32x16& ob, unsigned vbase, const bf16x8& pf0, const bf16x8& pf1) {
;   s16x4 r[8];
;   tr_read8<64 * C>(vbase, r);
;   const bf16x8 a0 = __builtin_shufflevector(r[0], r[1], 0, 1, 2, 3, 4, 5, 6, 7);
;   const bf16x8 a1 = __builtin_shufflevector(r[2], r[3], 0, 1, 2, 3, 4, 5, 6, 7);
;   const bf16x8 b0 = __builtin_shufflevector(r[4], r[5], 0, 1, 2, 3, 4, 5, 6, 7);
;   const bf16x8 b1 = __builtin_shufflevector(r[6], r[7], 0, 1, 2, 3, 4, 5, 6, 7);
;   oa = MFMA32(a0, pf0, oa);
;   ob = MFMA32(b0, pf0, ob);
;   oa = MFMA32(a1, pf1, oa);
;   ob = MFMA32(b1, pf1, ob);
; }
; DI void coop_compute(AttnAcc& a, const bf16x8 (&qf)[8], char* stg, const int lo, const int hi, int lane) {
;     ...
;   mx = fmaxf(mx, __shfl_xor(mx, 32));
;   const float msafe = (mx == NEG) ? 0.f : mx;
;   const float alpha = __builtin_amdgcn_exp2f(a.m - msafe);
;   a.m = mx;
;   float ls = 0.f;
; #pragma unroll
;   for (int hf = 0; hf < 2; ++hf)
; #pragma unroll
;     for (int i = 0; i < 16; ++i) { const float pv = __builtin_amdgcn_exp2f(st[hf][i] - msafe); st[hf][i] = pv; ls += pv; }
;   a.l = a.l * alpha + ls;
;   if (!__all(alpha == 1.f)) {
; #pragma unroll
;     for (int c = 0; c < 4; ++c) a.o[c] *= alpha;
;   }
;   pv_tile(a, st[0], stg + STG_K, lane);
;   pv_tile(a, st[1], stg + STG_K + 32 * VSTRIDE, lane);
.LBB0_210:
	v_sub_f32_e32 v14, v14, v94
	v_sub_f32_e32 v15, v15, v94
	v_exp_f32_e32 v95, v14
	v_exp_f32_e32 v96, v15
	v_sub_f32_e32 v15, v186, v94
	v_exp_f32_e32 v97, v15
	v_sub_f32_e32 v15, v187, v94
	v_exp_f32_e32 v98, v15
	v_sub_f32_e32 v15, v188, v94
	v_exp_f32_e32 v99, v15
	v_sub_f32_e32 v15, v189, v94
	v_add_f32_e32 v14, 0, v95
	v_exp_f32_e32 v100, v15
	v_sub_f32_e32 v15, v190, v94
	v_add_f32_e32 v14, v96, v14
	v_exp_f32_e32 v101, v15
	v_sub_f32_e32 v15, v191, v94
	v_add_f32_e32 v14, v97, v14
	v_exp_f32_e32 v102, v15
	v_sub_f32_e32 v15, v192, v94
	v_add_f32_e32 v14, v98, v14
	v_exp_f32_e32 v103, v15
	v_sub_f32_e32 v15, v193, v94
	v_add_f32_e32 v14, v99, v14
	v_exp_f32_e32 v104, v15
	v_sub_f32_e32 v15, v194, v94
	v_add_f32_e32 v14, v100, v14
	v_exp_f32_e32 v105, v15
	v_sub_f32_e32 v15, v195, v94
	v_add_f32_e32 v14, v101, v14
	v_exp_f32_e32 v106, v15
	v_sub_f32_e32 v15, v196, v94
	v_add_f32_e32 v14, v102, v14
	v_exp_f32_e32 v107, v15
	v_sub_f32_e32 v15, v197, v94
	v_add_f32_e32 v14, v103, v14
	v_exp_f32_e32 v108, v15
	v_sub_f32_e32 v15, v198, v94
	v_add_f32_e32 v14, v104, v14
	v_exp_f32_e32 v109, v15
	v_sub_f32_e32 v15, v199, v94
	v_add_f32_e32 v14, v105, v14
	v_exp_f32_e32 v110, v15
	v_add_f32_e32 v14, v106, v14
	v_add_f32_e32 v14, v107, v14
	v_sub_f32_e32 v15, v200, v94
	v_sub_f32_e32 v80, v201, v94
	v_sub_f32_e32 v81, v202, v94
	v_sub_f32_e32 v82, v203, v94
	v_sub_f32_e32 v83, v204, v94
	v_sub_f32_e32 v84, v205, v94
	v_sub_f32_e32 v85, v206, v94
	v_sub_f32_e32 v86, v207, v94
	v_sub_f32_e32 v87, v208, v94
	v_sub_f32_e32 v88, v209, v94
	v_sub_f32_e32 v89, v210, v94
	v_sub_f32_e32 v90, v211, v94
	v_sub_f32_e32 v91, v212, v94
	v_sub_f32_e32 v92, v213, v94
	v_sub_f32_e32 v93, v214, v94
	v_sub_f32_e32 v94, v215, v94
	v_add_f32_e32 v14, v108, v14
	v_exp_f32_e32 v111, v94
	v_cvt_pk_bf16_f32 v94, v95, v96
	v_cvt_pk_bf16_f32 v95, v97, v98
	v_cvt_pk_bf16_f32 v96, v99, v100
	v_cvt_pk_bf16_f32 v97, v101, v102
	s_waitcnt lgkmcnt(0)
	v_add_f32_e32 v14, v109, v14
	v_exp_f32_e32 v15, v15
	v_cvt_pk_bf16_f32 v98, v103, v104
	v_cvt_pk_bf16_f32 v99, v105, v106
	v_cvt_pk_bf16_f32 v100, v107, v108
	v_cvt_pk_bf16_f32 v101, v109, v110
	ds_read_b64_tr_b16 v[190:191], v221 offset:0
	ds_read_b64_tr_b16 v[192:193], v221 offset:0x900
	ds_read_b64_tr_b16 v[186:187], v221 offset:0x1200
	ds_read_b64_tr_b16 v[188:189], v221 offset:0x1b00
	ds_read_b64_tr_b16 v[106:107], v221 offset:64
	ds_read_b64_tr_b16 v[108:109], v221 offset:0x940
	ds_read_b64_tr_b16 v[102:103], v221 offset:0x1240
	ds_read_b64_tr_b16 v[104:105], v221 offset:0x1b40
	s_waitcnt lgkmcnt(7)
	ds_read_b64_tr_b16 v[194:195], v221 offset:128
	ds_read_b64_tr_b16 v[196:197], v221 offset:0x980
	ds_read_b64_tr_b16 v[198:199], v221 offset:0x1280
	ds_read_b64_tr_b16 v[200:201], v221 offset:0x1b80
	ds_read_b64_tr_b16 v[202:203], v221 offset:192
	ds_read_b64_tr_b16 v[204:205], v221 offset:0x9c0
	ds_read_b64_tr_b16 v[206:207], v221 offset:0x12c0
	ds_read_b64_tr_b16 v[208:209], v221 offset:0x1bc0
	s_waitcnt lgkmcnt(8)
	v_exp_f32_e32 v80, v80
	v_mfma_f32_32x32x16_bf16 v[64:79], v[190:193], v[94:97], v[64:79]
	v_exp_f32_e32 v81, v81
	v_add_f32_e32 v14, v110, v14
	v_exp_f32_e32 v82, v82
	v_add_f32_e32 v14, v15, v14
	v_exp_f32_e32 v83, v83
	v_add_f32_e32 v14, v80, v14
	v_exp_f32_e32 v84, v84
	v_mfma_f32_32x32x16_bf16 v[48:63], v[106:109], v[94:97], v[48:63]
	v_add_f32_e32 v14, v81, v14
	v_exp_f32_e32 v85, v85
	v_add_f32_e32 v14, v82, v14
	v_exp_f32_e32 v86, v86
	v_add_f32_e32 v14, v83, v14
	v_exp_f32_e32 v87, v87
	v_add_f32_e32 v14, v84, v14
	v_mfma_f32_32x32x16_bf16 v[64:79], v[186:189], v[98:101], v[64:79]
	v_exp_f32_e32 v88, v88
	v_add_f32_e32 v14, v85, v14
	v_exp_f32_e32 v89, v89
	v_add_f32_e32 v14, v86, v14
	v_exp_f32_e32 v90, v90
	v_add_f32_e32 v14, v87, v14
	v_exp_f32_e32 v91, v91
	v_mfma_f32_32x32x16_bf16 v[48:63], v[102:105], v[98:101], v[48:63]
	s_waitcnt lgkmcnt(7)
	ds_read_b64_tr_b16 v[190:191], v241 offset:0
	ds_read_b64_tr_b16 v[192:193], v241 offset:0x900
	ds_read_b64_tr_b16 v[186:187], v241 offset:0x1200
	ds_read_b64_tr_b16 v[188:189], v241 offset:0x1b00
	ds_read_b64_tr_b16 v[106:107], v241 offset:64
	ds_read_b64_tr_b16 v[108:109], v241 offset:0x940
	ds_read_b64_tr_b16 v[102:103], v241 offset:0x1240
	ds_read_b64_tr_b16 v[104:105], v241 offset:0x1b40
	s_waitcnt lgkmcnt(8)
	v_exp_f32_e32 v92, v92
	v_add_f32_e32 v14, v88, v14
	v_add_f32_e32 v14, v89, v14
	v_add_f32_e32 v14, v90, v14
	v_add_f32_e32 v14, v91, v14
	v_mfma_f32_32x32x16_bf16 v[32:47], v[194:197], v[94:97], v[32:47]
	v_exp_f32_e32 v93, v93
	v_add_f32_e32 v14, v92, v14
	v_add_f32_e32 v14, v93, v14
	v_add_f32_e32 v14, v111, v14
	v_fmac_f32_e32 v14, v175, v0
	v_mfma_f32_32x32x16_bf16 v[16:31], v[202:205], v[94:97], v[16:31]
	v_cvt_pk_bf16_f32 v94, v15, v80
	v_cvt_pk_bf16_f32 v95, v81, v82
	v_cvt_pk_bf16_f32 v96, v83, v84
	v_cvt_pk_bf16_f32 v97, v85, v86
	v_cvt_pk_bf16_f32 v80, v87, v88
	v_cvt_pk_bf16_f32 v81, v89, v90
	v_cvt_pk_bf16_f32 v82, v91, v92
	v_mfma_f32_32x32x16_bf16 v[32:47], v[198:201], v[98:101], v[32:47]
	v_cvt_pk_bf16_f32 v83, v93, v111
	v_mov_b32_e32 v175, v14
	v_mfma_f32_32x32x16_bf16 v[16:31], v[206:209], v[98:101], v[16:31]
	s_waitcnt lgkmcnt(7)
	ds_read_b64_tr_b16 v[194:195], v241 offset:128
	ds_read_b64_tr_b16 v[196:197], v241 offset:0x980
	ds_read_b64_tr_b16 v[198:199], v241 offset:0x1280
	ds_read_b64_tr_b16 v[200:201], v241 offset:0x1b80
	ds_read_b64_tr_b16 v[202:203], v241 offset:192
	ds_read_b64_tr_b16 v[204:205], v241 offset:0x9c0
	ds_read_b64_tr_b16 v[206:207], v241 offset:0x12c0
	ds_read_b64_tr_b16 v[208:209], v241 offset:0x1bc0
	s_waitcnt lgkmcnt(8)
	s_nop 0
	v_mfma_f32_32x32x16_bf16 v[64:79], v[190:193], v[94:97], v[64:79]
	v_mfma_f32_32x32x16_bf16 v[48:63], v[106:109], v[94:97], v[48:63]
	v_mfma_f32_32x32x16_bf16 v[64:79], v[186:189], v[80:83], v[64:79]
	v_mfma_f32_32x32x16_bf16 v[48:63], v[102:105], v[80:83], v[48:63]
	s_waitcnt lgkmcnt(0)
	v_mfma_f32_32x32x16_bf16 v[32:47], v[194:197], v[94:97], v[32:47]
	v_mfma_f32_32x32x16_bf16 v[16:31], v[202:205], v[94:97], v[16:31]
	v_mfma_f32_32x32x16_bf16 v[32:47], v[198:201], v[80:83], v[32:47]
	v_mfma_f32_32x32x16_bf16 v[16:31], v[206:209], v[80:83], v[16:31]
	s_cmp_lt_i32 s11, 0
	s_cbranch_scc1 .LBB0_212

; #define MFMA32(a, b, c) __builtin_amdgcn_mfma_f32_32x32x16_bf16((a), (b), (c), 0, 0, 0)
; template <int C>
; DI void pv_block2(f32x16& oa, f32x16& ob, unsigned vbase, const bf16x8& pf0, const bf16x8& pf1) {
;   s16x4 r[8];
;   tr_read8<64 * C>(vbase, r);
;   const bf16x8 a0 = __builtin_shufflevector(r[0], r[1], 0, 1, 2, 3, 4, 5, 6, 7);
;   const bf16x8 a1 = __builtin_shufflevector(r[2], r[3], 0, 1, 2, 3, 4, 5, 6, 7);
;   const bf16x8 b0 = __builtin_shufflevector(r[4], r[5], 0, 1, 2, 3, 4, 5, 6, 7);
;   const bf16x8 b1 = __builtin_shufflevector(r[6], r[7], 0, 1, 2, 3, 4, 5, 6, 7);
;   oa = MFMA32(a0, pf0, oa);
;   ob = MFMA32(b0, pf0, ob);
;   oa = MFMA32(a1, pf1, oa);
;   ob = MFMA32(b1, pf1, ob);
; }
; DI void coop_compute(AttnAcc& a, const bf16x8 (&qf)[8], char* stg, const int lo, const int hi, int lane) {
;     ...
;   mx = fmaxf(mx, __shfl_xor(mx, 32));
;   const float msafe = (mx == NEG) ? 0.f : mx;
;   const float alpha = __builtin_amdgcn_exp2f(a.m - msafe);
;   a.m = mx;
;   float ls = 0.f;
; #pragma unroll
;   for (int hf = 0; hf < 2; ++hf)
; #pragma unroll
;     for (int i = 0; i < 16; ++i) { const float pv = __builtin_amdgcn_exp2f(st[hf][i] - msafe); st[hf][i] = pv; ls += pv; }
;   a.l = a.l * alpha + ls;
;   if (!__all(alpha == 1.f)) {
; #pragma unroll
;     for (int c = 0; c < 4; ++c) a.o[c] *= alpha;
;   }
;   pv_tile(a, st[0], stg + STG_K, lane);
;   pv_tile(a, st[1], stg + STG_K + 32 * VSTRIDE, lane);
.LBB0_222:
	v_sub_f32_e32 v14, v14, v94
	v_sub_f32_e32 v15, v15, v94
	v_exp_f32_e32 v95, v14
	v_exp_f32_e32 v96, v15
	v_sub_f32_e32 v15, v186, v94
	v_exp_f32_e32 v97, v15
	v_sub_f32_e32 v15, v187, v94
	v_exp_f32_e32 v98, v15
	v_sub_f32_e32 v15, v188, v94
	v_exp_f32_e32 v99, v15
	v_sub_f32_e32 v15, v189, v94
	v_add_f32_e32 v14, 0, v95
	v_exp_f32_e32 v100, v15
	v_sub_f32_e32 v15, v190, v94
	v_add_f32_e32 v14, v96, v14
	v_exp_f32_e32 v101, v15
	v_sub_f32_e32 v15, v191, v94
	v_add_f32_e32 v14, v97, v14
	v_exp_f32_e32 v102, v15
	v_sub_f32_e32 v15, v192, v94
	v_add_f32_e32 v14, v98, v14
	v_exp_f32_e32 v103, v15
	v_sub_f32_e32 v15, v193, v94
	v_add_f32_e32 v14, v99, v14
	v_exp_f32_e32 v104, v15
	v_sub_f32_e32 v15, v194, v94
	v_add_f32_e32 v14, v100, v14
	v_exp_f32_e32 v105, v15
	v_sub_f32_e32 v15, v195, v94
	v_add_f32_e32 v14, v101, v14
	v_exp_f32_e32 v106, v15
	v_sub_f32_e32 v15, v196, v94
	v_add_f32_e32 v14, v102, v14
	v_exp_f32_e32 v107, v15
	v_sub_f32_e32 v15, v197, v94
	v_add_f32_e32 v14, v103, v14
	v_exp_f32_e32 v108, v15
	v_sub_f32_e32 v15, v198, v94
	v_add_f32_e32 v14, v104, v14
	v_exp_f32_e32 v109, v15
	v_sub_f32_e32 v15, v199, v94
	v_add_f32_e32 v14, v105, v14
	v_exp_f32_e32 v110, v15
	v_add_f32_e32 v14, v106, v14
	v_add_f32_e32 v14, v107, v14
	v_sub_f32_e32 v15, v200, v94
	v_sub_f32_e32 v80, v201, v94
	v_sub_f32_e32 v81, v202, v94
	v_sub_f32_e32 v82, v203, v94
	v_sub_f32_e32 v83, v204, v94
	v_sub_f32_e32 v84, v205, v94
	v_sub_f32_e32 v85, v206, v94
	v_sub_f32_e32 v86, v207, v94
	v_sub_f32_e32 v87, v208, v94
	v_sub_f32_e32 v88, v209, v94
	v_sub_f32_e32 v89, v210, v94
	v_sub_f32_e32 v90, v211, v94
	v_sub_f32_e32 v91, v212, v94
	v_sub_f32_e32 v92, v213, v94
	v_sub_f32_e32 v93, v214, v94
	v_sub_f32_e32 v94, v215, v94
	v_add_f32_e32 v14, v108, v14
	v_exp_f32_e32 v111, v94
	v_cvt_pk_bf16_f32 v94, v95, v96
	v_cvt_pk_bf16_f32 v95, v97, v98
	v_cvt_pk_bf16_f32 v96, v99, v100
	v_cvt_pk_bf16_f32 v97, v101, v102
	s_waitcnt lgkmcnt(0)
	v_add_f32_e32 v14, v109, v14
	v_exp_f32_e32 v15, v15
	v_cvt_pk_bf16_f32 v98, v103, v104
	v_cvt_pk_bf16_f32 v99, v105, v106
	v_cvt_pk_bf16_f32 v100, v107, v108
	v_cvt_pk_bf16_f32 v101, v109, v110
	ds_read_b64_tr_b16 v[190:191], v242 offset:0
	ds_read_b64_tr_b16 v[192:193], v242 offset:0x900
	ds_read_b64_tr_b16 v[186:187], v242 offset:0x1200
	ds_read_b64_tr_b16 v[188:189], v242 offset:0x1b00
	ds_read_b64_tr_b16 v[106:107], v242 offset:64
	ds_read_b64_tr_b16 v[108:109], v242 offset:0x940
	ds_read_b64_tr_b16 v[102:103], v242 offset:0x1240
	ds_read_b64_tr_b16 v[104:105], v242 offset:0x1b40
	s_waitcnt lgkmcnt(7)
	ds_read_b64_tr_b16 v[194:195], v242 offset:128
	ds_read_b64_tr_b16 v[196:197], v242 offset:0x980
	ds_read_b64_tr_b16 v[198:199], v242 offset:0x1280
	ds_read_b64_tr_b16 v[200:201], v242 offset:0x1b80
	ds_read_b64_tr_b16 v[202:203], v242 offset:192
	ds_read_b64_tr_b16 v[204:205], v242 offset:0x9c0
	ds_read_b64_tr_b16 v[206:207], v242 offset:0x12c0
	ds_read_b64_tr_b16 v[208:209], v242 offset:0x1bc0
	s_waitcnt lgkmcnt(8)
	v_exp_f32_e32 v80, v80
	v_mfma_f32_32x32x16_bf16 v[64:79], v[190:193], v[94:97], v[64:79]
	v_exp_f32_e32 v81, v81
	v_add_f32_e32 v14, v110, v14
	v_exp_f32_e32 v82, v82
	v_add_f32_e32 v14, v15, v14
	v_exp_f32_e32 v83, v83
	v_add_f32_e32 v14, v80, v14
	v_exp_f32_e32 v84, v84
	v_mfma_f32_32x32x16_bf16 v[48:63], v[106:109], v[94:97], v[48:63]
	v_add_f32_e32 v14, v81, v14
	v_exp_f32_e32 v85, v85
	v_add_f32_e32 v14, v82, v14
	v_exp_f32_e32 v86, v86
	v_add_f32_e32 v14, v83, v14
	v_exp_f32_e32 v87, v87
	v_add_f32_e32 v14, v84, v14
	v_mfma_f32_32x32x16_bf16 v[64:79], v[186:189], v[98:101], v[64:79]
	v_exp_f32_e32 v88, v88
	v_add_f32_e32 v14, v85, v14
	v_exp_f32_e32 v89, v89
	v_add_f32_e32 v14, v86, v14
	v_exp_f32_e32 v90, v90
	v_add_f32_e32 v14, v87, v14
	v_exp_f32_e32 v91, v91
	v_mfma_f32_32x32x16_bf16 v[48:63], v[102:105], v[98:101], v[48:63]
	s_waitcnt lgkmcnt(7)
	ds_read_b64_tr_b16 v[190:191], v243 offset:0
	ds_read_b64_tr_b16 v[192:193], v243 offset:0x900
	ds_read_b64_tr_b16 v[186:187], v243 offset:0x1200
	ds_read_b64_tr_b16 v[188:189], v243 offset:0x1b00
	ds_read_b64_tr_b16 v[106:107], v243 offset:64
	ds_read_b64_tr_b16 v[108:109], v243 offset:0x940
	ds_read_b64_tr_b16 v[102:103], v243 offset:0x1240
	ds_read_b64_tr_b16 v[104:105], v243 offset:0x1b40
	s_waitcnt lgkmcnt(8)
	v_exp_f32_e32 v92, v92
	v_add_f32_e32 v14, v88, v14
	v_add_f32_e32 v14, v89, v14
	v_add_f32_e32 v14, v90, v14
	v_add_f32_e32 v14, v91, v14
	v_mfma_f32_32x32x16_bf16 v[32:47], v[194:197], v[94:97], v[32:47]
	v_exp_f32_e32 v93, v93
	v_add_f32_e32 v14, v92, v14
	v_add_f32_e32 v14, v93, v14
	v_add_f32_e32 v14, v111, v14
	v_fmac_f32_e32 v14, v175, v0
	v_mfma_f32_32x32x16_bf16 v[16:31], v[202:205], v[94:97], v[16:31]
	v_cvt_pk_bf16_f32 v94, v15, v80
	v_cvt_pk_bf16_f32 v95, v81, v82
	v_cvt_pk_bf16_f32 v96, v83, v84
	v_cvt_pk_bf16_f32 v97, v85, v86
	v_cvt_pk_bf16_f32 v80, v87, v88
	v_cvt_pk_bf16_f32 v81, v89, v90
	v_cvt_pk_bf16_f32 v82, v91, v92
	v_mfma_f32_32x32x16_bf16 v[32:47], v[198:201], v[98:101], v[32:47]
	v_cvt_pk_bf16_f32 v83, v93, v111
	v_mov_b32_e32 v175, v14
	v_mfma_f32_32x32x16_bf16 v[16:31], v[206:209], v[98:101], v[16:31]
	s_waitcnt lgkmcnt(7)
	ds_read_b64_tr_b16 v[194:195], v243 offset:128
	ds_read_b64_tr_b16 v[196:197], v243 offset:0x980
	ds_read_b64_tr_b16 v[198:199], v243 offset:0x1280
	ds_read_b64_tr_b16 v[200:201], v243 offset:0x1b80
	ds_read_b64_tr_b16 v[202:203], v243 offset:192
	ds_read_b64_tr_b16 v[204:205], v243 offset:0x9c0
	ds_read_b64_tr_b16 v[206:207], v243 offset:0x12c0
	ds_read_b64_tr_b16 v[208:209], v243 offset:0x1bc0
	s_waitcnt lgkmcnt(8)
	s_nop 0
	v_mfma_f32_32x32x16_bf16 v[64:79], v[190:193], v[94:97], v[64:79]
	v_mfma_f32_32x32x16_bf16 v[48:63], v[106:109], v[94:97], v[48:63]
	v_mfma_f32_32x32x16_bf16 v[64:79], v[186:189], v[80:83], v[64:79]
	v_mfma_f32_32x32x16_bf16 v[48:63], v[102:105], v[80:83], v[48:63]
	s_waitcnt lgkmcnt(0)
	v_mfma_f32_32x32x16_bf16 v[32:47], v[194:197], v[94:97], v[32:47]
	v_mfma_f32_32x32x16_bf16 v[16:31], v[202:205], v[94:97], v[16:31]
	v_mfma_f32_32x32x16_bf16 v[32:47], v[198:201], v[80:83], v[32:47]
	v_mfma_f32_32x32x16_bf16 v[16:31], v[206:209], v[80:83], v[16:31]
	s_andn2_b64 vcc, exec, s[58:59]
	s_cbranch_vccnz .LBB0_224

; #define WAIT_V(n) asm volatile("s_waitcnt vmcnt(" #n ")" ::: "memory")
; #define BAR __builtin_amdgcn_s_barrier()
; template <class EPI>
; DI void gemm_stream(const u16* __restrict__ A, const u16* __restrict__ Bt, const int K, const int nM, const int nN,
;                     const int bid, const int nb, const int tid, EPI epi) {
;     ...
;   STAGE(SB(0, 0), Bt, bcol, 0); STAGE(SA(0, 0), A, brow, 0);
;   STAGE(SB(0, 1), Bt, bcol + HALF, 0); STAGE(SA(0, 1), A, brow + HALF, 0);
;   if (wr == 1) BAR;
;   WAIT_V(4); BAR;
;   STAGE(SB(1, 0), Bt, bcol, 1); STAGE(SA(1, 0), A, brow, 1); STAGE(SB(1, 1), Bt, bcol + HALF, 1);
;   WAIT_V(6); BAR;
.LBB0_409:
	s_or_b64 exec, exec, s[0:1]
	v_add_u32_e32 v193, 0x18000, v179
	s_or_b32 s0, s3, 0x80
	v_readfirstlane_b32 s1, v193
	v_add_u32_e32 v5, s0, v184
	s_mov_b32 m0, s1
	v_add_u32_e32 v194, 0x1a000, v179
	s_waitcnt vmcnt(2)
	s_barrier
	global_load_lds_dwordx4 v5, s[74:75]
	v_add_u32_e32 v5, s0, v185
	v_readfirstlane_b32 s0, v194
	v_add_u32_e32 v195, 0x8000, v179
	s_mov_b32 m0, s0
	s_bitset1_b32 s4, 7
	v_readfirstlane_b32 s0, v195
	v_add_u32_e32 v196, 0xa000, v179
	global_load_lds_dwordx4 v5, s[74:75]
	v_add_u32_e32 v5, s4, v184
	s_mov_b32 m0, s0
	v_readfirstlane_b32 s0, v196
	v_add_u32_e32 v197, 0x1c000, v179
	global_load_lds_dwordx4 v5, s[80:81]
	v_add_u32_e32 v5, s4, v185
	s_mov_b32 m0, s0
	s_or_b32 s0, s3, 0x80080
	v_readfirstlane_b32 s1, v197
	global_load_lds_dwordx4 v5, s[80:81]
	v_add_u32_e32 v5, s0, v184
	s_mov_b32 m0, s1
	v_add_u32_e32 v198, 0x1e000, v179
	global_load_lds_dwordx4 v5, s[74:75]
	v_add_u32_e32 v5, s0, v185
	v_readfirstlane_b32 s0, v198
	s_mov_b32 m0, s0
	v_and_b32_e32 v6, 48, v239
	global_load_lds_dwordx4 v5, s[74:75]
	v_and_b32_e32 v5, 15, v239
	v_lshlrev_b32_e32 v5, 6, v5
	v_lshlrev_b32_e32 v8, 2, v239
	v_or_b32_e32 v7, v5, v6
	v_and_b32_e32 v8, 32, v8
	v_lshlrev_b32_e32 v2, 13, v2
	v_bitop3_b32 v5, v5, v8, v6 bitop3:0x36
	v_bitop3_b32 v199, v7, v2, v8 bitop3:0xde
	v_lshlrev_b32_e32 v2, 6, v239
	s_movk_i32 s0, 0x3000
	v_and_or_b32 v200, v2, s0, v5
	v_lshlrev_b32_e32 v2, 15, v0
	v_and_b32_e32 v2, 0xffff0000, v2
	v_lshl_add_u32 v2, v3, 12, v2
	v_and_b32_e32 v0, 1, v0
	s_waitcnt vmcnt(6)
	v_lshl_or_b32 v0, v0, 6, v2
	v_mov_b32_e32 v2, 1
	s_sext_i32_i16 s17, s2
	v_lshlrev_b32_sdwa v2, v2, sext(v4) dst_sel:DWORD dst_unused:UNUSED_PAD src0_sel:DWORD src1_sel:WORD_0
	s_mov_b32 s0, 0xc0080
	s_lshl_b32 s2, s12, 8
	s_lshl_b32 s4, s17, 8
	v_add3_u32 v201, v0, v2, s0
	s_mov_b32 s13, s45
	s_mov_b32 s14, s17
	s_barrier
	s_branch .LBB0_411
.Lpj48_loop:
	v_or_b32_e32 v122, 0x10000, v200
	v_add_u32_e32 v134, 0x10400, v200
	v_add_u32_e32 v138, 0x10800, v200
	v_add_u32_e32 v142, 0x10c00, v200
	ds_read_b128 v[122:125], v122
	ds_read_b128 v[134:137], v134
	ds_read_b128 v[138:141], v138
	ds_read_b128 v[142:145], v142
	s_add_i32 s1, s0, -2
	s_cmp_lt_u32 s1, 30
	s_cselect_b32 s3, s4, s16
	s_cselect_b32 s5, s2, s15
	v_add_u32_e32 v181, 0xc000, v179
	v_add_u32_e32 v180, 0xfffc0000, v0
	v_readfirstlane_b32 s6, v181
	s_mov_b32 m0, s6
	ds_read_b128 v[146:149], v199
	ds_read_b128 v[150:153], v199 offset:1024
	ds_read_b128 v[154:157], v199 offset:2048
	ds_read_b128 v[158:161], v199 offset:3072
	ds_read_b128 v[162:165], v199 offset:4096
	ds_read_b128 v[166:169], v199 offset:5120
	ds_read_b128 v[170:173], v199 offset:6144
	ds_read_b128 v[174:177], v199 offset:7168
	global_load_lds_dwordx4 v180, s[80:81]
	v_add_u32_e32 v180, 0xe000, v179
	s_nop 0
	v_readfirstlane_b32 s6, v180
	s_mov_b32 m0, s6
	s_nop 0
	global_load_lds_dwordx4 v0, s[80:81]
	s_waitcnt lgkmcnt(8)
	v_or_b32_e32 v180, 0x14000, v200
	v_add_u32_e32 v202, 0x14400, v200
	v_add_u32_e32 v206, 0x14800, v200
	v_add_u32_e32 v210, 0x14c00, v200
	ds_read_b128 v[180:183], v180
	ds_read_b128 v[202:205], v202
	ds_read_b128 v[206:209], v206
	ds_read_b128 v[210:213], v210
	s_waitcnt vmcnt(8)
	s_waitcnt lgkmcnt(0)
	s_barrier
	s_setprio 1
	v_mfma_f32_16x16x32_bf16 v[130:133], v[122:125], v[146:149], v[130:133]
	v_mfma_f32_16x16x32_bf16 v[110:113], v[122:125], v[154:157], v[110:113]
	v_mfma_f32_16x16x32_bf16 v[94:97], v[122:125], v[162:165], v[94:97]
	v_mfma_f32_16x16x32_bf16 v[78:81], v[122:125], v[170:173], v[78:81]
	v_mfma_f32_16x16x32_bf16 v[130:133], v[134:137], v[150:153], v[130:133]
	v_mfma_f32_16x16x32_bf16 v[110:113], v[134:137], v[158:161], v[110:113]
	v_mfma_f32_16x16x32_bf16 v[94:97], v[134:137], v[166:169], v[94:97]
	v_mfma_f32_16x16x32_bf16 v[78:81], v[134:137], v[174:177], v[78:81]
	s_setprio 0
	s_barrier
	s_cselect_b32 s6, s0, 0
	s_lshl_b32 s3, s3, 11
	s_lshl_b32 s7, s6, 6
	s_or_b32 s10, s3, s7
	s_lshl_b32 s10, s10, 1
	v_readfirstlane_b32 s11, v186
	v_add_u32_e32 v214, s10, v184
	s_mov_b32 m0, s11
	global_load_lds_dwordx4 v214, s[74:75]
	v_add_u32_e32 v214, s10, v185
	v_readfirstlane_b32 s10, v187
	s_mov_b32 m0, s10
	s_nop 0
	global_load_lds_dwordx4 v214, s[74:75]
	s_lshl_b32 s10, s5, 11
	s_or_b32 s11, s10, s7
	s_lshl_b32 s11, s11, 1
	v_readfirstlane_b32 s18, v179
	v_add_u32_e32 v214, s11, v184
	s_mov_b32 m0, s18
	ds_read_b128 v[146:149], v199 offset:16384
	ds_read_b128 v[150:153], v199 offset:17408
	ds_read_b128 v[154:157], v199 offset:18432
	ds_read_b128 v[158:161], v199 offset:19456
	ds_read_b128 v[162:165], v199 offset:20480
	ds_read_b128 v[166:169], v199 offset:21504
	ds_read_b128 v[170:173], v199 offset:22528
	ds_read_b128 v[174:177], v199 offset:23552
	global_load_lds_dwordx4 v214, s[80:81]
	v_add_u32_e32 v214, s11, v185
	v_readfirstlane_b32 s11, v188
	s_mov_b32 m0, s11
	s_nop 0
	global_load_lds_dwordx4 v214, s[80:81]
	s_or_b32 s11, s3, 0x40000
	s_or_b32 s18, s11, s7
	s_lshl_b32 s18, s18, 1
	v_readfirstlane_b32 s19, v189
	v_add_u32_e32 v215, s18, v184
	s_mov_b32 m0, s19
	s_nop 0
	global_load_lds_dwordx4 v215, s[74:75]
	v_add_u32_e32 v215, s18, v185
	v_readfirstlane_b32 s18, v190
	s_mov_b32 m0, s18
	s_nop 0
	global_load_lds_dwordx4 v215, s[74:75]
	s_waitcnt vmcnt(8)
	s_waitcnt lgkmcnt(0)
	s_barrier
	s_setprio 1
	v_mfma_f32_16x16x32_bf16 v[62:65], v[122:125], v[146:149], v[62:65]
	v_mfma_f32_16x16x32_bf16 v[46:49], v[122:125], v[154:157], v[46:49]
	v_mfma_f32_16x16x32_bf16 v[30:33], v[122:125], v[162:165], v[30:33]
	v_mfma_f32_16x16x32_bf16 v[14:17], v[122:125], v[170:173], v[14:17]
	v_mfma_f32_16x16x32_bf16 v[62:65], v[134:137], v[150:153], v[62:65]
	v_mfma_f32_16x16x32_bf16 v[46:49], v[134:137], v[158:161], v[46:49]
	v_mfma_f32_16x16x32_bf16 v[30:33], v[134:137], v[166:169], v[30:33]
	v_mfma_f32_16x16x32_bf16 v[14:17], v[134:137], v[174:177], v[14:17]
	s_setprio 0
	s_barrier
	v_or_b32_e32 v122, 0x18000, v200
	v_add_u32_e32 v134, 0x18400, v200
	v_add_u32_e32 v138, 0x18800, v200
	v_add_u32_e32 v142, 0x18c00, v200
	ds_read_b128 v[122:125], v122
	ds_read_b128 v[134:137], v134
	ds_read_b128 v[138:141], v138
	ds_read_b128 v[142:145], v142
	s_lshl_b32 s5, s5, 12
	s_lshl_b32 s6, s6, 7
	s_add_i32 s5, s6, s5
	s_add_i32 s5, s5, 0x80000
	v_readfirstlane_b32 s6, v191
	v_add_u32_e32 v180, s5, v184
	s_mov_b32 m0, s6
	ds_read_b128 v[146:149], v199 offset:32768
	ds_read_b128 v[150:153], v199 offset:33792
	ds_read_b128 v[154:157], v199 offset:34816
	ds_read_b128 v[158:161], v199 offset:35840
	ds_read_b128 v[162:165], v199 offset:36864
	ds_read_b128 v[166:169], v199 offset:37888
	ds_read_b128 v[170:173], v199 offset:38912
	ds_read_b128 v[174:177], v199 offset:39936
	global_load_lds_dwordx4 v180, s[80:81]
	v_add_u32_e32 v180, s5, v185
	v_readfirstlane_b32 s5, v192
	s_mov_b32 m0, s5
	s_nop 0
	global_load_lds_dwordx4 v180, s[80:81]
	s_waitcnt lgkmcnt(8)
	v_or_b32_e32 v180, 0x1c000, v200
	v_add_u32_e32 v202, 0x1c400, v200
	v_add_u32_e32 v206, 0x1c800, v200
	v_add_u32_e32 v210, 0x1cc00, v200
	ds_read_b128 v[180:183], v180
	ds_read_b128 v[202:205], v202
	ds_read_b128 v[206:209], v206
	ds_read_b128 v[210:213], v210
	s_waitcnt vmcnt(8)
	s_waitcnt lgkmcnt(0)
	s_barrier
	s_setprio 1
	v_mfma_f32_16x16x32_bf16 v[130:133], v[122:125], v[146:149], v[130:133]
	v_mfma_f32_16x16x32_bf16 v[110:113], v[122:125], v[154:157], v[110:113]
	v_mfma_f32_16x16x32_bf16 v[94:97], v[122:125], v[162:165], v[94:97]
	v_mfma_f32_16x16x32_bf16 v[78:81], v[122:125], v[170:173], v[78:81]
	v_mfma_f32_16x16x32_bf16 v[130:133], v[134:137], v[150:153], v[130:133]
	v_mfma_f32_16x16x32_bf16 v[110:113], v[134:137], v[158:161], v[110:113]
	v_mfma_f32_16x16x32_bf16 v[94:97], v[134:137], v[166:169], v[94:97]
	v_mfma_f32_16x16x32_bf16 v[78:81], v[134:137], v[174:177], v[78:81]
	s_setprio 0
	s_barrier
	s_or_b32 s5, s7, 64
	s_or_b32 s3, s5, s3
	s_lshl_b32 s3, s3, 1
	v_readfirstlane_b32 s6, v193
	v_add_u32_e32 v214, s3, v184
	s_mov_b32 m0, s6
	global_load_lds_dwordx4 v214, s[74:75]
	v_add_u32_e32 v214, s3, v185
	v_readfirstlane_b32 s3, v194
	s_mov_b32 m0, s3
	s_nop 0
	global_load_lds_dwordx4 v214, s[74:75]
	s_or_b32 s3, s5, s10
	s_lshl_b32 s3, s3, 1
	v_readfirstlane_b32 s6, v195
	v_add_u32_e32 v214, s3, v184
	s_mov_b32 m0, s6
	ds_read_b128 v[146:149], v199 offset:49152
	ds_read_b128 v[150:153], v199 offset:50176
	ds_read_b128 v[154:157], v199 offset:51200
	ds_read_b128 v[158:161], v199 offset:52224
	ds_read_b128 v[162:165], v199 offset:53248
	ds_read_b128 v[166:169], v199 offset:54272
	ds_read_b128 v[170:173], v199 offset:55296
	ds_read_b128 v[174:177], v199 offset:56320
	global_load_lds_dwordx4 v214, s[80:81]
	v_add_u32_e32 v214, s3, v185
	v_readfirstlane_b32 s3, v196
	s_mov_b32 m0, s3
	s_nop 0
	global_load_lds_dwordx4 v214, s[80:81]
	s_or_b32 s3, s11, s5
	s_lshl_b32 s3, s3, 1
	v_readfirstlane_b32 s5, v197
	v_add_u32_e32 v215, s3, v184
	s_mov_b32 m0, s5
	s_nop 0
	global_load_lds_dwordx4 v215, s[74:75]
	v_add_u32_e32 v215, s3, v185
	v_readfirstlane_b32 s3, v198
	s_mov_b32 m0, s3
	s_nop 0
	global_load_lds_dwordx4 v215, s[74:75]
	s_waitcnt vmcnt(8)
	s_waitcnt lgkmcnt(0)
	s_barrier
	s_setprio 1
	v_mfma_f32_16x16x32_bf16 v[62:65], v[122:125], v[146:149], v[62:65]
	v_mfma_f32_16x16x32_bf16 v[46:49], v[122:125], v[154:157], v[46:49]
	v_mfma_f32_16x16x32_bf16 v[30:33], v[122:125], v[162:165], v[30:33]
	v_mfma_f32_16x16x32_bf16 v[14:17], v[122:125], v[170:173], v[14:17]
	v_mfma_f32_16x16x32_bf16 v[62:65], v[134:137], v[150:153], v[62:65]
	v_mfma_f32_16x16x32_bf16 v[46:49], v[134:137], v[158:161], v[46:49]
	v_mfma_f32_16x16x32_bf16 v[30:33], v[134:137], v[166:169], v[30:33]
	v_mfma_f32_16x16x32_bf16 v[14:17], v[134:137], v[174:177], v[14:17]
	s_setprio 0
	s_add_i32 s0, s0, 2
	s_cmp_gt_u32 s1, 29
	v_add_u32_e32 v0, 0x100, v0
	s_barrier
	s_cbranch_scc0 .Lpj48_loop
	s_branch .Lpj48_done

.LBB0_414:
	v_or_b32_e32 v122, 0x10000, v200
	v_add_u32_e32 v134, 0x10400, v200
	v_add_u32_e32 v138, 0x10800, v200
	v_add_u32_e32 v142, 0x10c00, v200
	ds_read_b128 v[122:125], v122
	ds_read_b128 v[134:137], v134
	ds_read_b128 v[138:141], v138
	ds_read_b128 v[142:145], v142
	s_add_i32 s1, s0, -2
	s_cmp_lt_u32 s1, 30
	s_cselect_b32 s3, s4, s16
	s_cselect_b32 s5, s2, s15
	v_add_u32_e32 v181, 0xc000, v179
	v_add_u32_e32 v180, 0xfffc0000, v0
	v_readfirstlane_b32 s6, v181
	s_mov_b32 m0, s6
	ds_read_b128 v[146:149], v199
	ds_read_b128 v[150:153], v199 offset:1024
	ds_read_b128 v[154:157], v199 offset:2048
	ds_read_b128 v[158:161], v199 offset:3072
	ds_read_b128 v[162:165], v199 offset:4096
	ds_read_b128 v[166:169], v199 offset:5120
	ds_read_b128 v[170:173], v199 offset:6144
	ds_read_b128 v[174:177], v199 offset:7168
	global_load_lds_dwordx4 v180, s[80:81]
	v_add_u32_e32 v180, 0xe000, v179
	s_nop 0
	v_readfirstlane_b32 s6, v180
	s_mov_b32 m0, s6
	s_nop 0
	global_load_lds_dwordx4 v0, s[80:81]
	s_waitcnt lgkmcnt(8)
	v_or_b32_e32 v180, 0x14000, v200
	v_add_u32_e32 v202, 0x14400, v200
	v_add_u32_e32 v206, 0x14800, v200
	v_add_u32_e32 v210, 0x14c00, v200
	ds_read_b128 v[180:183], v180
	ds_read_b128 v[202:205], v202
	ds_read_b128 v[206:209], v206
	ds_read_b128 v[210:213], v210
	s_waitcnt vmcnt(8)
	s_waitcnt lgkmcnt(0)
	s_barrier
	s_setprio 1
	v_mfma_f32_16x16x32_bf16 v[130:133], v[122:125], v[146:149], v[130:133]
	v_mfma_f32_16x16x32_bf16 v[126:129], v[138:141], v[146:149], v[126:129]
	v_mfma_f32_16x16x32_bf16 v[110:113], v[122:125], v[154:157], v[110:113]
	v_mfma_f32_16x16x32_bf16 v[106:109], v[138:141], v[154:157], v[106:109]
	v_mfma_f32_16x16x32_bf16 v[94:97], v[122:125], v[162:165], v[94:97]
	v_mfma_f32_16x16x32_bf16 v[90:93], v[138:141], v[162:165], v[90:93]
	v_mfma_f32_16x16x32_bf16 v[78:81], v[122:125], v[170:173], v[78:81]
	v_mfma_f32_16x16x32_bf16 v[74:77], v[138:141], v[170:173], v[74:77]
	v_mfma_f32_16x16x32_bf16 v[130:133], v[134:137], v[150:153], v[130:133]
	v_mfma_f32_16x16x32_bf16 v[126:129], v[142:145], v[150:153], v[126:129]
	v_mfma_f32_16x16x32_bf16 v[110:113], v[134:137], v[158:161], v[110:113]
	v_mfma_f32_16x16x32_bf16 v[106:109], v[142:145], v[158:161], v[106:109]
	v_mfma_f32_16x16x32_bf16 v[94:97], v[134:137], v[166:169], v[94:97]
	v_mfma_f32_16x16x32_bf16 v[90:93], v[142:145], v[166:169], v[90:93]
	v_mfma_f32_16x16x32_bf16 v[78:81], v[134:137], v[174:177], v[78:81]
	v_mfma_f32_16x16x32_bf16 v[74:77], v[142:145], v[174:177], v[74:77]
	v_mfma_f32_16x16x32_bf16 v[118:121], v[180:183], v[146:149], v[118:121]
	v_mfma_f32_16x16x32_bf16 v[114:117], v[206:209], v[146:149], v[114:117]
	v_mfma_f32_16x16x32_bf16 v[102:105], v[180:183], v[154:157], v[102:105]
	v_mfma_f32_16x16x32_bf16 v[98:101], v[206:209], v[154:157], v[98:101]
	v_mfma_f32_16x16x32_bf16 v[86:89], v[180:183], v[162:165], v[86:89]
	v_mfma_f32_16x16x32_bf16 v[82:85], v[206:209], v[162:165], v[82:85]
	v_mfma_f32_16x16x32_bf16 v[70:73], v[180:183], v[170:173], v[70:73]
	v_mfma_f32_16x16x32_bf16 v[66:69], v[206:209], v[170:173], v[66:69]
	v_mfma_f32_16x16x32_bf16 v[118:121], v[202:205], v[150:153], v[118:121]
	v_mfma_f32_16x16x32_bf16 v[114:117], v[210:213], v[150:153], v[114:117]
	v_mfma_f32_16x16x32_bf16 v[102:105], v[202:205], v[158:161], v[102:105]
	v_mfma_f32_16x16x32_bf16 v[98:101], v[210:213], v[158:161], v[98:101]
	v_mfma_f32_16x16x32_bf16 v[86:89], v[202:205], v[166:169], v[86:89]
	v_mfma_f32_16x16x32_bf16 v[82:85], v[210:213], v[166:169], v[82:85]
	v_mfma_f32_16x16x32_bf16 v[70:73], v[202:205], v[174:177], v[70:73]
	v_mfma_f32_16x16x32_bf16 v[66:69], v[210:213], v[174:177], v[66:69]
	s_setprio 0
	s_barrier
	s_cselect_b32 s6, s0, 0
	s_lshl_b32 s3, s3, 11
	s_lshl_b32 s7, s6, 6
	s_or_b32 s10, s3, s7
	s_lshl_b32 s10, s10, 1
	v_readfirstlane_b32 s11, v186
	v_add_u32_e32 v214, s10, v184
	s_mov_b32 m0, s11
	global_load_lds_dwordx4 v214, s[74:75]
	v_add_u32_e32 v214, s10, v185
	v_readfirstlane_b32 s10, v187
	s_mov_b32 m0, s10
	s_nop 0
	global_load_lds_dwordx4 v214, s[74:75]
	s_lshl_b32 s10, s5, 11
	s_or_b32 s11, s10, s7
	s_lshl_b32 s11, s11, 1
	v_readfirstlane_b32 s18, v179
	v_add_u32_e32 v214, s11, v184
	s_mov_b32 m0, s18
	ds_read_b128 v[146:149], v199 offset:16384
	ds_read_b128 v[150:153], v199 offset:17408
	ds_read_b128 v[154:157], v199 offset:18432
	ds_read_b128 v[158:161], v199 offset:19456
	ds_read_b128 v[162:165], v199 offset:20480
	ds_read_b128 v[166:169], v199 offset:21504
	ds_read_b128 v[170:173], v199 offset:22528
	ds_read_b128 v[174:177], v199 offset:23552
	global_load_lds_dwordx4 v214, s[80:81]
	v_add_u32_e32 v214, s11, v185
	v_readfirstlane_b32 s11, v188
	s_mov_b32 m0, s11
	s_nop 0
	global_load_lds_dwordx4 v214, s[80:81]
	s_or_b32 s11, s3, 0x40000
	s_or_b32 s18, s11, s7
	s_lshl_b32 s18, s18, 1
	v_readfirstlane_b32 s19, v189
	v_add_u32_e32 v215, s18, v184
	s_mov_b32 m0, s19
	s_nop 0
	global_load_lds_dwordx4 v215, s[74:75]
	v_add_u32_e32 v215, s18, v185
	v_readfirstlane_b32 s18, v190
	s_mov_b32 m0, s18
	s_nop 0
	global_load_lds_dwordx4 v215, s[74:75]
	s_waitcnt vmcnt(8)
	s_waitcnt lgkmcnt(0)
	s_barrier
	s_setprio 1
	v_mfma_f32_16x16x32_bf16 v[62:65], v[122:125], v[146:149], v[62:65]
	v_mfma_f32_16x16x32_bf16 v[58:61], v[138:141], v[146:149], v[58:61]
	v_mfma_f32_16x16x32_bf16 v[46:49], v[122:125], v[154:157], v[46:49]
	v_mfma_f32_16x16x32_bf16 v[42:45], v[138:141], v[154:157], v[42:45]
	v_mfma_f32_16x16x32_bf16 v[30:33], v[122:125], v[162:165], v[30:33]
	v_mfma_f32_16x16x32_bf16 v[26:29], v[138:141], v[162:165], v[26:29]
	v_mfma_f32_16x16x32_bf16 v[14:17], v[122:125], v[170:173], v[14:17]
	v_mfma_f32_16x16x32_bf16 v[10:13], v[138:141], v[170:173], v[10:13]
	v_mfma_f32_16x16x32_bf16 v[62:65], v[134:137], v[150:153], v[62:65]
	v_mfma_f32_16x16x32_bf16 v[58:61], v[142:145], v[150:153], v[58:61]
	v_mfma_f32_16x16x32_bf16 v[46:49], v[134:137], v[158:161], v[46:49]
	v_mfma_f32_16x16x32_bf16 v[42:45], v[142:145], v[158:161], v[42:45]
	v_mfma_f32_16x16x32_bf16 v[30:33], v[134:137], v[166:169], v[30:33]
	v_mfma_f32_16x16x32_bf16 v[26:29], v[142:145], v[166:169], v[26:29]
	v_mfma_f32_16x16x32_bf16 v[14:17], v[134:137], v[174:177], v[14:17]
	v_mfma_f32_16x16x32_bf16 v[10:13], v[142:145], v[174:177], v[10:13]
	v_mfma_f32_16x16x32_bf16 v[54:57], v[180:183], v[146:149], v[54:57]
	v_mfma_f32_16x16x32_bf16 v[50:53], v[206:209], v[146:149], v[50:53]
	v_mfma_f32_16x16x32_bf16 v[38:41], v[180:183], v[154:157], v[38:41]
	v_mfma_f32_16x16x32_bf16 v[34:37], v[206:209], v[154:157], v[34:37]
	v_mfma_f32_16x16x32_bf16 v[22:25], v[180:183], v[162:165], v[22:25]
	v_mfma_f32_16x16x32_bf16 v[18:21], v[206:209], v[162:165], v[18:21]
	v_mfma_f32_16x16x32_bf16 v[6:9], v[180:183], v[170:173], v[6:9]
	v_mfma_f32_16x16x32_bf16 v[2:5], v[206:209], v[170:173], v[2:5]
	v_mfma_f32_16x16x32_bf16 v[54:57], v[202:205], v[150:153], v[54:57]
	v_mfma_f32_16x16x32_bf16 v[50:53], v[210:213], v[150:153], v[50:53]
	v_mfma_f32_16x16x32_bf16 v[38:41], v[202:205], v[158:161], v[38:41]
	v_mfma_f32_16x16x32_bf16 v[34:37], v[210:213], v[158:161], v[34:37]
	v_mfma_f32_16x16x32_bf16 v[22:25], v[202:205], v[166:169], v[22:25]
	v_mfma_f32_16x16x32_bf16 v[18:21], v[210:213], v[166:169], v[18:21]
	v_mfma_f32_16x16x32_bf16 v[6:9], v[202:205], v[174:177], v[6:9]
	v_mfma_f32_16x16x32_bf16 v[2:5], v[210:213], v[174:177], v[2:5]
	s_setprio 0
	s_barrier
	v_or_b32_e32 v122, 0x18000, v200
	v_add_u32_e32 v134, 0x18400, v200
	v_add_u32_e32 v138, 0x18800, v200
	v_add_u32_e32 v142, 0x18c00, v200
	ds_read_b128 v[122:125], v122
	ds_read_b128 v[134:137], v134
	ds_read_b128 v[138:141], v138
	ds_read_b128 v[142:145], v142
	s_lshl_b32 s5, s5, 12
	s_lshl_b32 s6, s6, 7
	s_add_i32 s5, s6, s5
	s_add_i32 s5, s5, 0x80000
	v_readfirstlane_b32 s6, v191
	v_add_u32_e32 v180, s5, v184
	s_mov_b32 m0, s6
	ds_read_b128 v[146:149], v199 offset:32768
	ds_read_b128 v[150:153], v199 offset:33792
	ds_read_b128 v[154:157], v199 offset:34816
	ds_read_b128 v[158:161], v199 offset:35840
	ds_read_b128 v[162:165], v199 offset:36864
	ds_read_b128 v[166:169], v199 offset:37888
	ds_read_b128 v[170:173], v199 offset:38912
	ds_read_b128 v[174:177], v199 offset:39936
	global_load_lds_dwordx4 v180, s[80:81]
	v_add_u32_e32 v180, s5, v185
	v_readfirstlane_b32 s5, v192
	s_mov_b32 m0, s5
	s_nop 0
	global_load_lds_dwordx4 v180, s[80:81]
	s_waitcnt lgkmcnt(8)
	v_or_b32_e32 v180, 0x1c000, v200
	v_add_u32_e32 v202, 0x1c400, v200
	v_add_u32_e32 v206, 0x1c800, v200
	v_add_u32_e32 v210, 0x1cc00, v200
	ds_read_b128 v[180:183], v180
	ds_read_b128 v[202:205], v202
	ds_read_b128 v[206:209], v206
	ds_read_b128 v[210:213], v210
	s_waitcnt vmcnt(8)
	s_waitcnt lgkmcnt(0)
	s_barrier
	s_setprio 1
	v_mfma_f32_16x16x32_bf16 v[130:133], v[122:125], v[146:149], v[130:133]
	v_mfma_f32_16x16x32_bf16 v[126:129], v[138:141], v[146:149], v[126:129]
	v_mfma_f32_16x16x32_bf16 v[110:113], v[122:125], v[154:157], v[110:113]
	v_mfma_f32_16x16x32_bf16 v[106:109], v[138:141], v[154:157], v[106:109]
	v_mfma_f32_16x16x32_bf16 v[94:97], v[122:125], v[162:165], v[94:97]
	v_mfma_f32_16x16x32_bf16 v[90:93], v[138:141], v[162:165], v[90:93]
	v_mfma_f32_16x16x32_bf16 v[78:81], v[122:125], v[170:173], v[78:81]
	v_mfma_f32_16x16x32_bf16 v[74:77], v[138:141], v[170:173], v[74:77]
	v_mfma_f32_16x16x32_bf16 v[130:133], v[134:137], v[150:153], v[130:133]
	v_mfma_f32_16x16x32_bf16 v[126:129], v[142:145], v[150:153], v[126:129]
	v_mfma_f32_16x16x32_bf16 v[110:113], v[134:137], v[158:161], v[110:113]
	v_mfma_f32_16x16x32_bf16 v[106:109], v[142:145], v[158:161], v[106:109]
	v_mfma_f32_16x16x32_bf16 v[94:97], v[134:137], v[166:169], v[94:97]
	v_mfma_f32_16x16x32_bf16 v[90:93], v[142:145], v[166:169], v[90:93]
	v_mfma_f32_16x16x32_bf16 v[78:81], v[134:137], v[174:177], v[78:81]
	v_mfma_f32_16x16x32_bf16 v[74:77], v[142:145], v[174:177], v[74:77]
	v_mfma_f32_16x16x32_bf16 v[118:121], v[180:183], v[146:149], v[118:121]
	v_mfma_f32_16x16x32_bf16 v[114:117], v[206:209], v[146:149], v[114:117]
	v_mfma_f32_16x16x32_bf16 v[102:105], v[180:183], v[154:157], v[102:105]
	v_mfma_f32_16x16x32_bf16 v[98:101], v[206:209], v[154:157], v[98:101]
	v_mfma_f32_16x16x32_bf16 v[86:89], v[180:183], v[162:165], v[86:89]
	v_mfma_f32_16x16x32_bf16 v[82:85], v[206:209], v[162:165], v[82:85]
	v_mfma_f32_16x16x32_bf16 v[70:73], v[180:183], v[170:173], v[70:73]
	v_mfma_f32_16x16x32_bf16 v[66:69], v[206:209], v[170:173], v[66:69]
	v_mfma_f32_16x16x32_bf16 v[118:121], v[202:205], v[150:153], v[118:121]
	v_mfma_f32_16x16x32_bf16 v[114:117], v[210:213], v[150:153], v[114:117]
	v_mfma_f32_16x16x32_bf16 v[102:105], v[202:205], v[158:161], v[102:105]
	v_mfma_f32_16x16x32_bf16 v[98:101], v[210:213], v[158:161], v[98:101]
	v_mfma_f32_16x16x32_bf16 v[86:89], v[202:205], v[166:169], v[86:89]
	v_mfma_f32_16x16x32_bf16 v[82:85], v[210:213], v[166:169], v[82:85]
	v_mfma_f32_16x16x32_bf16 v[70:73], v[202:205], v[174:177], v[70:73]
	v_mfma_f32_16x16x32_bf16 v[66:69], v[210:213], v[174:177], v[66:69]
	s_setprio 0
	s_barrier
	s_or_b32 s5, s7, 64
	s_or_b32 s3, s5, s3
	s_lshl_b32 s3, s3, 1
	v_readfirstlane_b32 s6, v193
	v_add_u32_e32 v214, s3, v184
	s_mov_b32 m0, s6
	global_load_lds_dwordx4 v214, s[74:75]
	v_add_u32_e32 v214, s3, v185
	v_readfirstlane_b32 s3, v194
	s_mov_b32 m0, s3
	s_nop 0
	global_load_lds_dwordx4 v214, s[74:75]
	s_or_b32 s3, s5, s10
	s_lshl_b32 s3, s3, 1
	v_readfirstlane_b32 s6, v195
	v_add_u32_e32 v214, s3, v184
	s_mov_b32 m0, s6
	ds_read_b128 v[146:149], v199 offset:49152
	ds_read_b128 v[150:153], v199 offset:50176
	ds_read_b128 v[154:157], v199 offset:51200
	ds_read_b128 v[158:161], v199 offset:52224
	ds_read_b128 v[162:165], v199 offset:53248
	ds_read_b128 v[166:169], v199 offset:54272
	ds_read_b128 v[170:173], v199 offset:55296
	ds_read_b128 v[174:177], v199 offset:56320
	global_load_lds_dwordx4 v214, s[80:81]
	v_add_u32_e32 v214, s3, v185
	v_readfirstlane_b32 s3, v196
	s_mov_b32 m0, s3
	s_nop 0
	global_load_lds_dwordx4 v214, s[80:81]
	s_or_b32 s3, s11, s5
	s_lshl_b32 s3, s3, 1
	v_readfirstlane_b32 s5, v197
	v_add_u32_e32 v215, s3, v184
	s_mov_b32 m0, s5
	s_nop 0
	global_load_lds_dwordx4 v215, s[74:75]
	v_add_u32_e32 v215, s3, v185
	v_readfirstlane_b32 s3, v198
	s_mov_b32 m0, s3
	s_nop 0
	global_load_lds_dwordx4 v215, s[74:75]
	s_waitcnt vmcnt(8)
	s_waitcnt lgkmcnt(0)
	s_barrier
	s_setprio 1
	v_mfma_f32_16x16x32_bf16 v[62:65], v[122:125], v[146:149], v[62:65]
	v_mfma_f32_16x16x32_bf16 v[58:61], v[138:141], v[146:149], v[58:61]
	v_mfma_f32_16x16x32_bf16 v[46:49], v[122:125], v[154:157], v[46:49]
	v_mfma_f32_16x16x32_bf16 v[42:45], v[138:141], v[154:157], v[42:45]
	v_mfma_f32_16x16x32_bf16 v[30:33], v[122:125], v[162:165], v[30:33]
	v_mfma_f32_16x16x32_bf16 v[26:29], v[138:141], v[162:165], v[26:29]
	v_mfma_f32_16x16x32_bf16 v[14:17], v[122:125], v[170:173], v[14:17]
	v_mfma_f32_16x16x32_bf16 v[10:13], v[138:141], v[170:173], v[10:13]
	v_mfma_f32_16x16x32_bf16 v[62:65], v[134:137], v[150:153], v[62:65]
	v_mfma_f32_16x16x32_bf16 v[58:61], v[142:145], v[150:153], v[58:61]
	v_mfma_f32_16x16x32_bf16 v[46:49], v[134:137], v[158:161], v[46:49]
	v_mfma_f32_16x16x32_bf16 v[42:45], v[142:145], v[158:161], v[42:45]
	v_mfma_f32_16x16x32_bf16 v[30:33], v[134:137], v[166:169], v[30:33]
	v_mfma_f32_16x16x32_bf16 v[26:29], v[142:145], v[166:169], v[26:29]
	v_mfma_f32_16x16x32_bf16 v[14:17], v[134:137], v[174:177], v[14:17]
	v_mfma_f32_16x16x32_bf16 v[10:13], v[142:145], v[174:177], v[10:13]
	v_mfma_f32_16x16x32_bf16 v[54:57], v[180:183], v[146:149], v[54:57]
	v_mfma_f32_16x16x32_bf16 v[50:53], v[206:209], v[146:149], v[50:53]
	v_mfma_f32_16x16x32_bf16 v[38:41], v[180:183], v[154:157], v[38:41]
	v_mfma_f32_16x16x32_bf16 v[34:37], v[206:209], v[154:157], v[34:37]
	v_mfma_f32_16x16x32_bf16 v[22:25], v[180:183], v[162:165], v[22:25]
	v_mfma_f32_16x16x32_bf16 v[18:21], v[206:209], v[162:165], v[18:21]
	v_mfma_f32_16x16x32_bf16 v[6:9], v[180:183], v[170:173], v[6:9]
	v_mfma_f32_16x16x32_bf16 v[2:5], v[206:209], v[170:173], v[2:5]
	v_mfma_f32_16x16x32_bf16 v[54:57], v[202:205], v[150:153], v[54:57]
	v_mfma_f32_16x16x32_bf16 v[50:53], v[210:213], v[150:153], v[50:53]
	v_mfma_f32_16x16x32_bf16 v[38:41], v[202:205], v[158:161], v[38:41]
	v_mfma_f32_16x16x32_bf16 v[34:37], v[210:213], v[158:161], v[34:37]
	v_mfma_f32_16x16x32_bf16 v[22:25], v[202:205], v[166:169], v[22:25]
	v_mfma_f32_16x16x32_bf16 v[18:21], v[210:213], v[166:169], v[18:21]
	v_mfma_f32_16x16x32_bf16 v[6:9], v[202:205], v[174:177], v[6:9]
	v_mfma_f32_16x16x32_bf16 v[2:5], v[210:213], v[174:177], v[2:5]
	s_setprio 0
	s_add_i32 s0, s0, 2
	s_cmp_gt_u32 s1, 29
	v_add_u32_e32 v0, 0x100, v0
	s_barrier
	s_cbranch_scc0 .LBB0_414
